# K-loops: waves 4-7 run their load segments at s_setprio 2 (they lose LDS/VMEM arbitration to the older half otherwise)
# baseline (speedup 1.0000x reference)
; #define PG8_STAGE(bufoff, gbase, voff) do { _Pragma("unroll") for (int _i = 0; _i < 2; ++_i) \
;         __builtin_amdgcn_global_load_lds((const unsigned*)((const char*)(gbase) + (voff)[_i]), (PG8_LAS unsigned*)(lds + (bufoff) + ldsw + _i * 8192), 16, 0, 0); } while (0)
; #define PG8_LDA(dst, b, h) do { _Pragma("unroll") for (int m = 0; m < 4; ++m) _Pragma("unroll") for (int k = 0; k < 2; ++k) dst[m][k] = *(const PG8_LAS bf16x8*)(lds + PG8_SA(b, h) + aoff + m * 2048 + k * 1024); } while (0)
; #define PG8_LDB(dst, b, h) do { _Pragma("unroll") for (int n = 0; n < 2; ++n) _Pragma("unroll") for (int k = 0; k < 2; ++k) dst[n][k] = *(const PG8_LAS bf16x8*)(lds + PG8_SB(b, h) + boff + n * 2048 + k * 1024); } while (0)
; #define PG8_MMA(ai, bj, At, Bt) do { __builtin_amdgcn_s_setprio(1); _Pragma("unroll") for (int m = 0; m < 4; ++m) _Pragma("unroll") for (int n = 0; n < 2; ++n) _Pragma("unroll") for (int k = 0; k < 2; ++k) \
;         acc[ai][bj][m][n] = __builtin_amdgcn_mfma_f32_16x16x32_bf16(Bt[n][k], At[m][k], acc[ai][bj][m][n], 0, 0, 0); __builtin_amdgcn_s_setprio(0); } while (0)
; #define PG8_WAIT_V(n) asm volatile("s_waitcnt vmcnt(" #n ")" ::: "memory")
; #define PG8_WAIT_L(n) asm volatile("s_waitcnt lgkmcnt(" #n ")" ::: "memory")
; #define PG8_BAR __builtin_amdgcn_s_barrier()
; #define PG8_SCHED __builtin_amdgcn_sched_barrier(0)
;     ...
;             const bool last = (t == nt - 2);
;             const char* a1 = cA + (size_t)(t + 1) * kstep;
;             const char* a2 = last ? nA : cA + (size_t)(t + 2) * kstep; const char* b2 = last ? nB : cB + (size_t)(t + 2) * kstep;
;             const char* a3 = a2 + kstep; const char* b3 = b2 + kstep;
;             if (last && has_next) S.a_ready(nxt);
;             if constexpr (SP2) {
;             PG8_LDB(B0, 0, 0); PG8_LDB(B1, 0, 1); PG8_SCHED; PG8_LDA(At, 0, 0); PG8_STAGE(PG8_SA(1, 1), a1 + hstepA, voffA);
;             PG8_WAIT_V(8); PG8_WAIT_L(0); PG8_BAR; PG8_MMA(0, 0, At, B0); PG8_MMA(0, 1, At, B1); PG8_BAR; PG8_SCHED;
;             PG8_LDA(At, 0, 1); PG8_STAGE(PG8_SB(0, 0), b2, voffB); PG8_STAGE(PG8_SB(0, 1), b2 + hstepB, voffB); PG8_STAGE(PG8_SA(0, 0), a2, voffA);
.LBB0_228:
	ds_read_b128 v[128:131], v201
	ds_read_b128 v[132:135], v201 offset:1024
	ds_read_b128 v[136:139], v201 offset:2048
	ds_read_b128 v[140:143], v201 offset:3072
	ds_read_b128 v[144:147], v205
	ds_read_b128 v[148:151], v205 offset:1024
	ds_read_b128 v[152:155], v205 offset:2048
	ds_read_b128 v[156:159], v205 offset:3072
	s_add_u32 s34, s28, 0xfffc0080
	s_addc_u32 s35, s29, -1
	s_cmp_eq_u32 s63, 12
	s_cselect_b32 s41, s42, s35
	s_cselect_b32 s40, s43, s34
	s_cselect_b32 s35, s44, s53
	s_cselect_b32 s34, s45, s51
	v_lshl_add_u64 v[192:193], s[28:29], 0, v[184:185]
	s_add_i32 m0, s61, 0xc000
	ds_read_b128 v[160:163], v207
	ds_read_b128 v[164:167], v207 offset:1024
	ds_read_b128 v[210:213], v207 offset:2048
	ds_read_b128 v[214:217], v207 offset:3072
	ds_read_b128 v[218:221], v207 offset:4096
	ds_read_b128 v[222:225], v207 offset:5120
	ds_read_b128 v[226:229], v207 offset:6144
	ds_read_b128 v[234:237], v207 offset:7168
	global_load_lds_dwordx4 v[192:193], off
	v_lshl_add_u64 v[192:193], s[28:29], 0, v[186:187]
	s_add_i32 m0, s61, 0xe000
	s_nop 0
	global_load_lds_dwordx4 v[192:193], off
	s_waitcnt vmcnt(8)
	s_waitcnt lgkmcnt(0)
	s_barrier
	s_setprio 1
	s_waitcnt lgkmcnt(0)
	v_mfma_f32_16x16x32_bf16 v[124:127], v[128:131], v[160:163], v[124:127]
	v_mfma_f32_16x16x32_bf16 v[120:123], v[136:139], v[160:163], v[120:123]
	v_mfma_f32_16x16x32_bf16 v[108:111], v[128:131], v[210:213], v[108:111]
	v_mfma_f32_16x16x32_bf16 v[104:107], v[136:139], v[210:213], v[104:107]
	v_mfma_f32_16x16x32_bf16 v[92:95], v[128:131], v[218:221], v[92:95]
	v_mfma_f32_16x16x32_bf16 v[88:91], v[136:139], v[218:221], v[88:91]
	v_mfma_f32_16x16x32_bf16 v[76:79], v[128:131], v[226:229], v[76:79]
	v_mfma_f32_16x16x32_bf16 v[72:75], v[136:139], v[226:229], v[72:75]
	v_mfma_f32_16x16x32_bf16 v[124:127], v[132:135], v[164:167], v[124:127]
	v_mfma_f32_16x16x32_bf16 v[120:123], v[140:143], v[164:167], v[120:123]
	v_mfma_f32_16x16x32_bf16 v[108:111], v[132:135], v[214:217], v[108:111]
	v_mfma_f32_16x16x32_bf16 v[104:107], v[140:143], v[214:217], v[104:107]
	v_mfma_f32_16x16x32_bf16 v[92:95], v[132:135], v[222:225], v[92:95]
	v_mfma_f32_16x16x32_bf16 v[88:91], v[140:143], v[222:225], v[88:91]
	v_mfma_f32_16x16x32_bf16 v[76:79], v[132:135], v[234:237], v[76:79]
	v_mfma_f32_16x16x32_bf16 v[72:75], v[140:143], v[234:237], v[72:75]
	s_setprio 0
	s_setprio 1
	v_mfma_f32_16x16x32_bf16 v[116:119], v[144:147], v[160:163], v[116:119]
	v_mfma_f32_16x16x32_bf16 v[112:115], v[152:155], v[160:163], v[112:115]
	v_mfma_f32_16x16x32_bf16 v[100:103], v[144:147], v[210:213], v[100:103]
	v_mfma_f32_16x16x32_bf16 v[96:99], v[152:155], v[210:213], v[96:99]
	v_mfma_f32_16x16x32_bf16 v[84:87], v[144:147], v[218:221], v[84:87]
	v_mfma_f32_16x16x32_bf16 v[80:83], v[152:155], v[218:221], v[80:83]
	v_mfma_f32_16x16x32_bf16 v[68:71], v[144:147], v[226:229], v[68:71]
	v_mfma_f32_16x16x32_bf16 v[64:67], v[152:155], v[226:229], v[64:67]
	v_mfma_f32_16x16x32_bf16 v[116:119], v[148:151], v[164:167], v[116:119]
	v_mfma_f32_16x16x32_bf16 v[112:115], v[156:159], v[164:167], v[112:115]
	v_mfma_f32_16x16x32_bf16 v[100:103], v[148:151], v[214:217], v[100:103]
	v_mfma_f32_16x16x32_bf16 v[96:99], v[156:159], v[214:217], v[96:99]
	v_mfma_f32_16x16x32_bf16 v[84:87], v[148:151], v[222:225], v[84:87]
	v_mfma_f32_16x16x32_bf16 v[80:83], v[156:159], v[222:225], v[80:83]
	v_mfma_f32_16x16x32_bf16 v[68:71], v[148:151], v[234:237], v[68:71]
	v_mfma_f32_16x16x32_bf16 v[64:67], v[156:159], v[234:237], v[64:67]
	s_setprio 0
	s_barrier
	s_cmp_lg_u32 s98, 0
	s_cbranch_scc0 .Llp_1
	s_setprio 2
.Llp_1:
	s_add_i32 s85, s79, s65
	v_lshl_add_u64 v[192:193], s[34:35], 0, v[176:177]
	s_mov_b32 m0, s85
	ds_read_b128 v[160:163], v207 offset:16384
	ds_read_b128 v[164:167], v207 offset:17408
	ds_read_b128 v[210:213], v207 offset:18432
	ds_read_b128 v[214:217], v207 offset:19456
	ds_read_b128 v[218:221], v207 offset:20480
	ds_read_b128 v[222:225], v207 offset:21504
	ds_read_b128 v[226:229], v207 offset:22528
	ds_read_b128 v[234:237], v207 offset:23552
	global_load_lds_dwordx4 v[192:193], off
	s_add_i32 m0, s85, 0x2000
	s_add_u32 s86, s34, 0x40000
	v_lshl_add_u64 v[202:203], s[34:35], 0, v[180:181]
	s_addc_u32 s87, s35, 0
	s_add_i32 s85, s80, s65
	global_load_lds_dwordx4 v[202:203], off
	v_lshl_add_u64 v[230:231], s[86:87], 0, v[176:177]
	s_mov_b32 m0, s85
	v_lshl_add_u64 v[238:239], s[40:41], 0, v[178:179]
	global_load_lds_dwordx4 v[230:231], off
	v_lshl_add_u64 v[230:231], s[86:87], 0, v[180:181]
	s_add_i32 m0, s85, 0x2000
	s_nop 0
	global_load_lds_dwordx4 v[230:231], off
	v_lshl_add_u64 v[230:231], s[40:41], 0, v[174:175]
	s_mov_b32 m0, s61
	s_nop 0
	global_load_lds_dwordx4 v[230:231], off
	s_mov_b32 m0, s66
	s_nop 0
	global_load_lds_dwordx4 v[238:239], off
	s_waitcnt vmcnt(8)
	s_waitcnt lgkmcnt(0)
	s_barrier
; #define PG8_STAGE(bufoff, gbase, voff) do { _Pragma("unroll") for (int _i = 0; _i < 2; ++_i) \
;         __builtin_amdgcn_global_load_lds((const unsigned*)((const char*)(gbase) + (voff)[_i]), (PG8_LAS unsigned*)(lds + (bufoff) + ldsw + _i * 8192), 16, 0, 0); } while (0)
; #define PG8_LDA(dst, b, h) do { _Pragma("unroll") for (int m = 0; m < 4; ++m) _Pragma("unroll") for (int k = 0; k < 2; ++k) dst[m][k] = *(const PG8_LAS bf16x8*)(lds + PG8_SA(b, h) + aoff + m * 2048 + k * 1024); } while (0)
; #define PG8_LDB(dst, b, h) do { _Pragma("unroll") for (int n = 0; n < 2; ++n) _Pragma("unroll") for (int k = 0; k < 2; ++k) dst[n][k] = *(const PG8_LAS bf16x8*)(lds + PG8_SB(b, h) + boff + n * 2048 + k * 1024); } while (0)
; #define PG8_MMA(ai, bj, At, Bt) do { __builtin_amdgcn_s_setprio(1); _Pragma("unroll") for (int m = 0; m < 4; ++m) _Pragma("unroll") for (int n = 0; n < 2; ++n) _Pragma("unroll") for (int k = 0; k < 2; ++k) \
;         acc[ai][bj][m][n] = __builtin_amdgcn_mfma_f32_16x16x32_bf16(Bt[n][k], At[m][k], acc[ai][bj][m][n], 0, 0, 0); __builtin_amdgcn_s_setprio(0); } while (0)
; #define PG8_WAIT_V(n) asm volatile("s_waitcnt vmcnt(" #n ")" ::: "memory")
; #define PG8_WAIT_L(n) asm volatile("s_waitcnt lgkmcnt(" #n ")" ::: "memory")
; #define PG8_BAR __builtin_amdgcn_s_barrier()
; #define PG8_SCHED __builtin_amdgcn_sched_barrier(0)
;     ...
;             PG8_WAIT_V(8); PG8_WAIT_L(0); PG8_BAR; PG8_MMA(1, 0, At, B0); PG8_MMA(1, 1, At, B1); PG8_BAR; PG8_SCHED;
;             PG8_LDB(B0, 1, 0); PG8_LDB(B1, 1, 1); PG8_SCHED; PG8_LDA(At, 1, 0); PG8_STAGE(PG8_SA(0, 1), a2 + hstepA, voffA);
;             PG8_WAIT_V(8); PG8_WAIT_L(0); PG8_BAR; PG8_MMA(0, 0, At, B0); PG8_MMA(0, 1, At, B1); PG8_BAR; PG8_SCHED;
	s_setprio 1
	s_waitcnt lgkmcnt(0)
	v_mfma_f32_16x16x32_bf16 v[60:63], v[128:131], v[160:163], v[60:63]
	v_mfma_f32_16x16x32_bf16 v[56:59], v[136:139], v[160:163], v[56:59]
	v_mfma_f32_16x16x32_bf16 v[44:47], v[128:131], v[210:213], v[44:47]
	v_mfma_f32_16x16x32_bf16 v[40:43], v[136:139], v[210:213], v[40:43]
	v_mfma_f32_16x16x32_bf16 v[28:31], v[128:131], v[218:221], v[28:31]
	v_mfma_f32_16x16x32_bf16 v[24:27], v[136:139], v[218:221], v[24:27]
	v_mfma_f32_16x16x32_bf16 v[12:15], v[128:131], v[226:229], v[12:15]
	v_mfma_f32_16x16x32_bf16 v[8:11], v[136:139], v[226:229], v[8:11]
	v_mfma_f32_16x16x32_bf16 v[60:63], v[132:135], v[164:167], v[60:63]
	v_mfma_f32_16x16x32_bf16 v[56:59], v[140:143], v[164:167], v[56:59]
	v_mfma_f32_16x16x32_bf16 v[44:47], v[132:135], v[214:217], v[44:47]
	v_mfma_f32_16x16x32_bf16 v[40:43], v[140:143], v[214:217], v[40:43]
	v_mfma_f32_16x16x32_bf16 v[28:31], v[132:135], v[222:225], v[28:31]
	v_mfma_f32_16x16x32_bf16 v[24:27], v[140:143], v[222:225], v[24:27]
	v_mfma_f32_16x16x32_bf16 v[12:15], v[132:135], v[234:237], v[12:15]
	v_mfma_f32_16x16x32_bf16 v[8:11], v[140:143], v[234:237], v[8:11]
	s_setprio 0
	s_setprio 1
	v_mfma_f32_16x16x32_bf16 v[52:55], v[144:147], v[160:163], v[52:55]
	v_mfma_f32_16x16x32_bf16 v[48:51], v[152:155], v[160:163], v[48:51]
	v_mfma_f32_16x16x32_bf16 v[36:39], v[144:147], v[210:213], v[36:39]
	v_mfma_f32_16x16x32_bf16 v[32:35], v[152:155], v[210:213], v[32:35]
	v_mfma_f32_16x16x32_bf16 v[20:23], v[144:147], v[218:221], v[20:23]
	v_mfma_f32_16x16x32_bf16 v[16:19], v[152:155], v[218:221], v[16:19]
	v_mfma_f32_16x16x32_bf16 v[4:7], v[144:147], v[226:229], v[4:7]
	v_mfma_f32_16x16x32_bf16 v[0:3], v[152:155], v[226:229], v[0:3]
	v_mfma_f32_16x16x32_bf16 v[52:55], v[148:151], v[164:167], v[52:55]
	v_mfma_f32_16x16x32_bf16 v[48:51], v[156:159], v[164:167], v[48:51]
	v_mfma_f32_16x16x32_bf16 v[36:39], v[148:151], v[214:217], v[36:39]
	v_mfma_f32_16x16x32_bf16 v[32:35], v[156:159], v[214:217], v[32:35]
	v_mfma_f32_16x16x32_bf16 v[20:23], v[148:151], v[222:225], v[20:23]
	v_mfma_f32_16x16x32_bf16 v[16:19], v[156:159], v[222:225], v[16:19]
	v_mfma_f32_16x16x32_bf16 v[4:7], v[148:151], v[234:237], v[4:7]
	v_mfma_f32_16x16x32_bf16 v[0:3], v[156:159], v[234:237], v[0:3]
	s_setprio 0
	s_barrier
	s_cmp_lg_u32 s98, 0
	s_cbranch_scc0 .Llp_2
	s_setprio 2
.Llp_2:
	s_add_i32 s85, 0, 0x18000
	s_add_i32 s86, 0, 0x1c000
	v_add_u32_e32 v140, s85, v199
	v_add_u32_e32 v156, s86, v199
	ds_read_b128 v[128:131], v140
	ds_read_b128 v[132:135], v140 offset:1024
	ds_read_b128 v[136:139], v140 offset:2048
	ds_read_b128 v[140:143], v140 offset:3072
	ds_read_b128 v[144:147], v156
	ds_read_b128 v[148:151], v156 offset:1024
	ds_read_b128 v[152:155], v156 offset:2048
	ds_read_b128 v[156:159], v156 offset:3072
	s_add_u32 s40, s40, 0x40000
	s_addc_u32 s41, s41, 0
	s_mov_b32 m0, s67
	v_lshl_add_u64 v[240:241], s[40:41], 0, v[174:175]
	ds_read_b128 v[160:163], v207 offset:32768
	ds_read_b128 v[164:167], v207 offset:33792
	ds_read_b128 v[210:213], v207 offset:34816
	ds_read_b128 v[214:217], v207 offset:35840
	ds_read_b128 v[218:221], v207 offset:36864
	ds_read_b128 v[222:225], v207 offset:37888
	ds_read_b128 v[226:229], v207 offset:38912
	ds_read_b128 v[234:237], v207 offset:39936
	global_load_lds_dwordx4 v[240:241], off
	v_lshl_add_u64 v[240:241], s[40:41], 0, v[178:179]
	s_mov_b32 m0, s68
	s_nop 0
	global_load_lds_dwordx4 v[240:241], off
	s_waitcnt vmcnt(8)
	s_waitcnt lgkmcnt(0)
	s_barrier
	s_setprio 1
	s_waitcnt lgkmcnt(0)
	v_mfma_f32_16x16x32_bf16 v[124:127], v[128:131], v[160:163], v[124:127]
	v_mfma_f32_16x16x32_bf16 v[120:123], v[136:139], v[160:163], v[120:123]
	v_mfma_f32_16x16x32_bf16 v[108:111], v[128:131], v[210:213], v[108:111]
	v_mfma_f32_16x16x32_bf16 v[104:107], v[136:139], v[210:213], v[104:107]
	v_mfma_f32_16x16x32_bf16 v[92:95], v[128:131], v[218:221], v[92:95]
	v_mfma_f32_16x16x32_bf16 v[88:91], v[136:139], v[218:221], v[88:91]
	v_mfma_f32_16x16x32_bf16 v[76:79], v[128:131], v[226:229], v[76:79]
	v_mfma_f32_16x16x32_bf16 v[72:75], v[136:139], v[226:229], v[72:75]
	v_mfma_f32_16x16x32_bf16 v[124:127], v[132:135], v[164:167], v[124:127]
	v_mfma_f32_16x16x32_bf16 v[120:123], v[140:143], v[164:167], v[120:123]
	v_mfma_f32_16x16x32_bf16 v[108:111], v[132:135], v[214:217], v[108:111]
	v_mfma_f32_16x16x32_bf16 v[104:107], v[140:143], v[214:217], v[104:107]
	v_mfma_f32_16x16x32_bf16 v[92:95], v[132:135], v[222:225], v[92:95]
	v_mfma_f32_16x16x32_bf16 v[88:91], v[140:143], v[222:225], v[88:91]
	v_mfma_f32_16x16x32_bf16 v[76:79], v[132:135], v[234:237], v[76:79]
	v_mfma_f32_16x16x32_bf16 v[72:75], v[140:143], v[234:237], v[72:75]
	s_setprio 0
	s_setprio 1
	v_mfma_f32_16x16x32_bf16 v[116:119], v[144:147], v[160:163], v[116:119]
	v_mfma_f32_16x16x32_bf16 v[112:115], v[152:155], v[160:163], v[112:115]
	v_mfma_f32_16x16x32_bf16 v[100:103], v[144:147], v[210:213], v[100:103]
	v_mfma_f32_16x16x32_bf16 v[96:99], v[152:155], v[210:213], v[96:99]
	v_mfma_f32_16x16x32_bf16 v[84:87], v[144:147], v[218:221], v[84:87]
	v_mfma_f32_16x16x32_bf16 v[80:83], v[152:155], v[218:221], v[80:83]
	v_mfma_f32_16x16x32_bf16 v[68:71], v[144:147], v[226:229], v[68:71]
	v_mfma_f32_16x16x32_bf16 v[64:67], v[152:155], v[226:229], v[64:67]
	v_mfma_f32_16x16x32_bf16 v[116:119], v[148:151], v[164:167], v[116:119]
	v_mfma_f32_16x16x32_bf16 v[112:115], v[156:159], v[164:167], v[112:115]
	v_mfma_f32_16x16x32_bf16 v[100:103], v[148:151], v[214:217], v[100:103]
	v_mfma_f32_16x16x32_bf16 v[96:99], v[156:159], v[214:217], v[96:99]
	v_mfma_f32_16x16x32_bf16 v[84:87], v[148:151], v[222:225], v[84:87]
	v_mfma_f32_16x16x32_bf16 v[80:83], v[156:159], v[222:225], v[80:83]
	v_mfma_f32_16x16x32_bf16 v[68:71], v[148:151], v[234:237], v[68:71]
	v_mfma_f32_16x16x32_bf16 v[64:67], v[156:159], v[234:237], v[64:67]
	s_setprio 0
	s_barrier
	s_cmp_lg_u32 s98, 0
	s_cbranch_scc0 .Llp_3
	s_setprio 2
; #define PG8_STAGE(bufoff, gbase, voff) do { _Pragma("unroll") for (int _i = 0; _i < 2; ++_i) \
;         __builtin_amdgcn_global_load_lds((const unsigned*)((const char*)(gbase) + (voff)[_i]), (PG8_LAS unsigned*)(lds + (bufoff) + ldsw + _i * 8192), 16, 0, 0); } while (0)
; #define PG8_LDA(dst, b, h) do { _Pragma("unroll") for (int m = 0; m < 4; ++m) _Pragma("unroll") for (int k = 0; k < 2; ++k) dst[m][k] = *(const PG8_LAS bf16x8*)(lds + PG8_SA(b, h) + aoff + m * 2048 + k * 1024); } while (0)
; #define PG8_MMA(ai, bj, At, Bt) do { __builtin_amdgcn_s_setprio(1); _Pragma("unroll") for (int m = 0; m < 4; ++m) _Pragma("unroll") for (int n = 0; n < 2; ++n) _Pragma("unroll") for (int k = 0; k < 2; ++k) \
;         acc[ai][bj][m][n] = __builtin_amdgcn_mfma_f32_16x16x32_bf16(Bt[n][k], At[m][k], acc[ai][bj][m][n], 0, 0, 0); __builtin_amdgcn_s_setprio(0); } while (0)
; #define PG8_WAIT_V(n) asm volatile("s_waitcnt vmcnt(" #n ")" ::: "memory")
; #define PG8_WAIT_L(n) asm volatile("s_waitcnt lgkmcnt(" #n ")" ::: "memory")
; #define PG8_BAR __builtin_amdgcn_s_barrier()
; #define PG8_SCHED __builtin_amdgcn_sched_barrier(0)
;     ...
;         for (int t = 0; t < nt; t += 2) {
;     ...
;             PG8_LDA(At, 1, 1); PG8_STAGE(PG8_SB(1, 0), b3, voffB); PG8_STAGE(PG8_SB(1, 1), b3 + hstepB, voffB); PG8_STAGE(PG8_SA(1, 0), a3, voffA);
;             PG8_WAIT_V(8); PG8_WAIT_L(0); PG8_BAR; PG8_MMA(1, 0, At, B0); PG8_MMA(1, 1, At, B1); PG8_BAR; PG8_SCHED;
.Llp_3:
	s_add_i32 s40, s85, s65
	v_lshl_add_u64 v[192:193], v[192:193], 0, s[26:27]
	s_mov_b32 m0, s40
	ds_read_b128 v[160:163], v207 offset:49152
	ds_read_b128 v[164:167], v207 offset:50176
	ds_read_b128 v[210:213], v207 offset:51200
	ds_read_b128 v[214:217], v207 offset:52224
	ds_read_b128 v[218:221], v207 offset:53248
	ds_read_b128 v[222:225], v207 offset:54272
	ds_read_b128 v[226:229], v207 offset:55296
	ds_read_b128 v[234:237], v207 offset:56320
	global_load_lds_dwordx4 v[192:193], off
	s_add_i32 m0, s40, 0x2000
	s_add_u32 s34, s34, 0x40080
	v_lshl_add_u64 v[192:193], v[202:203], 0, s[26:27]
	s_addc_u32 s35, s35, 0
	s_add_i32 s40, s86, s65
	global_load_lds_dwordx4 v[192:193], off
	v_lshl_add_u64 v[192:193], s[34:35], 0, v[176:177]
	s_mov_b32 m0, s40
	s_nop 0
	global_load_lds_dwordx4 v[192:193], off
	v_lshl_add_u64 v[192:193], s[34:35], 0, v[180:181]
	s_add_i32 m0, s40, 0x2000
	s_nop 0
	global_load_lds_dwordx4 v[192:193], off
	v_lshl_add_u64 v[192:193], v[230:231], 0, s[26:27]
	s_mov_b32 m0, s76
	s_nop 0
	global_load_lds_dwordx4 v[192:193], off
	v_lshl_add_u64 v[192:193], v[238:239], 0, s[26:27]
	s_mov_b32 m0, s77
	s_nop 0
	global_load_lds_dwordx4 v[192:193], off
	s_waitcnt vmcnt(8)
	s_waitcnt lgkmcnt(0)
	s_barrier
	s_setprio 1
	s_waitcnt lgkmcnt(0)
	v_mfma_f32_16x16x32_bf16 v[60:63], v[128:131], v[160:163], v[60:63]
	v_mfma_f32_16x16x32_bf16 v[56:59], v[136:139], v[160:163], v[56:59]
	v_mfma_f32_16x16x32_bf16 v[44:47], v[128:131], v[210:213], v[44:47]
	v_mfma_f32_16x16x32_bf16 v[40:43], v[136:139], v[210:213], v[40:43]
	v_mfma_f32_16x16x32_bf16 v[28:31], v[128:131], v[218:221], v[28:31]
	v_mfma_f32_16x16x32_bf16 v[24:27], v[136:139], v[218:221], v[24:27]
	v_mfma_f32_16x16x32_bf16 v[12:15], v[128:131], v[226:229], v[12:15]
	v_mfma_f32_16x16x32_bf16 v[8:11], v[136:139], v[226:229], v[8:11]
	v_mfma_f32_16x16x32_bf16 v[60:63], v[132:135], v[164:167], v[60:63]
	v_mfma_f32_16x16x32_bf16 v[56:59], v[140:143], v[164:167], v[56:59]
	v_mfma_f32_16x16x32_bf16 v[44:47], v[132:135], v[214:217], v[44:47]
	v_mfma_f32_16x16x32_bf16 v[40:43], v[140:143], v[214:217], v[40:43]
	v_mfma_f32_16x16x32_bf16 v[28:31], v[132:135], v[222:225], v[28:31]
	v_mfma_f32_16x16x32_bf16 v[24:27], v[140:143], v[222:225], v[24:27]
	v_mfma_f32_16x16x32_bf16 v[12:15], v[132:135], v[234:237], v[12:15]
	v_mfma_f32_16x16x32_bf16 v[8:11], v[140:143], v[234:237], v[8:11]
	s_setprio 0
	s_setprio 1
	v_mfma_f32_16x16x32_bf16 v[52:55], v[144:147], v[160:163], v[52:55]
	v_mfma_f32_16x16x32_bf16 v[48:51], v[152:155], v[160:163], v[48:51]
	v_mfma_f32_16x16x32_bf16 v[36:39], v[144:147], v[210:213], v[36:39]
	v_mfma_f32_16x16x32_bf16 v[32:35], v[152:155], v[210:213], v[32:35]
	v_mfma_f32_16x16x32_bf16 v[20:23], v[144:147], v[218:221], v[20:23]
	v_mfma_f32_16x16x32_bf16 v[16:19], v[152:155], v[218:221], v[16:19]
	v_mfma_f32_16x16x32_bf16 v[4:7], v[144:147], v[226:229], v[4:7]
	v_mfma_f32_16x16x32_bf16 v[0:3], v[152:155], v[226:229], v[0:3]
	v_mfma_f32_16x16x32_bf16 v[52:55], v[148:151], v[164:167], v[52:55]
	v_mfma_f32_16x16x32_bf16 v[48:51], v[156:159], v[164:167], v[48:51]
	v_mfma_f32_16x16x32_bf16 v[36:39], v[148:151], v[214:217], v[36:39]
	v_mfma_f32_16x16x32_bf16 v[32:35], v[156:159], v[214:217], v[32:35]
	v_mfma_f32_16x16x32_bf16 v[20:23], v[148:151], v[222:225], v[20:23]
	v_mfma_f32_16x16x32_bf16 v[16:19], v[156:159], v[222:225], v[16:19]
	v_mfma_f32_16x16x32_bf16 v[4:7], v[148:151], v[234:237], v[4:7]
	v_mfma_f32_16x16x32_bf16 v[0:3], v[156:159], v[234:237], v[0:3]
	s_setprio 0
	s_barrier
	s_cmp_lg_u32 s98, 0
	s_cbranch_scc0 .Llp_4
	s_setprio 2
.Llp_4:
	s_add_i32 s63, s63, 2
	s_add_u32 s28, s28, 0x100
	s_addc_u32 s29, s29, 0
	s_add_u32 s51, s51, 0x100
	s_addc_u32 s53, s53, 0
	s_cmp_gt_u32 s63, 13
	s_cbranch_scc0 .LBB0_228
	s_and_b64 vcc, exec, s[36:37]
	s_cbranch_vccz .LBB0_231
	s_barrier

; #define PG8_STAGE(bufoff, gbase, voff) do { _Pragma("unroll") for (int _i = 0; _i < 2; ++_i) \
;         __builtin_amdgcn_global_load_lds((const unsigned*)((const char*)(gbase) + (voff)[_i]), (PG8_LAS unsigned*)(lds + (bufoff) + ldsw + _i * 8192), 16, 0, 0); } while (0)
; #define PG8_LDA(dst, b, h) do { _Pragma("unroll") for (int m = 0; m < 4; ++m) _Pragma("unroll") for (int k = 0; k < 2; ++k) dst[m][k] = *(const PG8_LAS bf16x8*)(lds + PG8_SA(b, h) + aoff + m * 2048 + k * 1024); } while (0)
; #define PG8_LDB(dst, b, h) do { _Pragma("unroll") for (int n = 0; n < 2; ++n) _Pragma("unroll") for (int k = 0; k < 2; ++k) dst[n][k] = *(const PG8_LAS bf16x8*)(lds + PG8_SB(b, h) + boff + n * 2048 + k * 1024); } while (0)
; #define PG8_MMA(ai, bj, At, Bt) do { __builtin_amdgcn_s_setprio(1); _Pragma("unroll") for (int m = 0; m < 4; ++m) _Pragma("unroll") for (int n = 0; n < 2; ++n) _Pragma("unroll") for (int k = 0; k < 2; ++k) \
;         acc[ai][bj][m][n] = __builtin_amdgcn_mfma_f32_16x16x32_bf16(Bt[n][k], At[m][k], acc[ai][bj][m][n], 0, 0, 0); __builtin_amdgcn_s_setprio(0); } while (0)
; #define PG8_WAIT_V(n) asm volatile("s_waitcnt vmcnt(" #n ")" ::: "memory")
; #define PG8_WAIT_L(n) asm volatile("s_waitcnt lgkmcnt(" #n ")" ::: "memory")
; #define PG8_BAR __builtin_amdgcn_s_barrier()
; #define PG8_SCHED __builtin_amdgcn_sched_barrier(0)
;     ...
;             const bool last = (t == nt - 2);
;             const char* a1 = cA + (size_t)(t + 1) * kstep;
;             const char* a2 = last ? nA : cA + (size_t)(t + 2) * kstep; const char* b2 = last ? nB : cB + (size_t)(t + 2) * kstep;
;             const char* a3 = a2 + kstep; const char* b3 = b2 + kstep;
;             if (last && has_next) S.a_ready(nxt);
;             if constexpr (SP2) {
;             PG8_LDB(B0, 0, 0); PG8_LDB(B1, 0, 1); PG8_SCHED; PG8_LDA(At, 0, 0); PG8_STAGE(PG8_SA(1, 1), a1 + hstepA, voffA);
;             PG8_WAIT_V(8); PG8_WAIT_L(0); PG8_BAR; PG8_MMA(0, 0, At, B0); PG8_MMA(0, 1, At, B1); PG8_BAR; PG8_SCHED;
;             PG8_LDA(At, 0, 1); PG8_STAGE(PG8_SB(0, 0), b2, voffB); PG8_STAGE(PG8_SB(0, 1), b2 + hstepB, voffB); PG8_STAGE(PG8_SA(0, 0), a2, voffA);
.LBB0_396:
	ds_read_b128 v[128:131], v163
	ds_read_b128 v[132:135], v163 offset:1024
	ds_read_b128 v[152:155], v163 offset:2048
	ds_read_b128 v[156:159], v163 offset:3072
	ds_read_b128 v[168:171], v164
	ds_read_b128 v[172:175], v164 offset:1024
	ds_read_b128 v[176:179], v164 offset:2048
	ds_read_b128 v[180:183], v164 offset:3072
	s_add_u32 s34, s28, 0xfffc0080
	s_addc_u32 s35, s29, -1
	s_cmp_eq_u32 s72, 12
	s_cselect_b32 s41, s37, s35
	s_cselect_b32 s40, s68, s34
	s_cselect_b32 s35, s27, s71
	s_cselect_b32 s34, s69, s70
	v_lshl_add_u64 v[160:161], s[28:29], 0, v[144:145]
	s_add_i32 m0, s49, 0xc000
	ds_read_b128 v[184:187], v165
	ds_read_b128 v[188:191], v165 offset:1024
	ds_read_b128 v[192:195], v165 offset:2048
	ds_read_b128 v[196:199], v165 offset:3072
	ds_read_b128 v[200:203], v165 offset:4096
	ds_read_b128 v[204:207], v165 offset:5120
	ds_read_b128 v[208:211], v165 offset:6144
	ds_read_b128 v[212:215], v165 offset:7168
	global_load_lds_dwordx4 v[160:161], off
	v_lshl_add_u64 v[160:161], s[28:29], 0, v[146:147]
	s_add_i32 m0, s49, 0xe000
	s_nop 0
	global_load_lds_dwordx4 v[160:161], off
	s_waitcnt vmcnt(8)
	s_waitcnt lgkmcnt(0)
	s_barrier
	s_setprio 1
	s_waitcnt lgkmcnt(0)
	v_mfma_f32_16x16x32_bf16 v[124:127], v[128:131], v[184:187], v[124:127]
	v_mfma_f32_16x16x32_bf16 v[120:123], v[152:155], v[184:187], v[120:123]
	v_mfma_f32_16x16x32_bf16 v[108:111], v[128:131], v[192:195], v[108:111]
	v_mfma_f32_16x16x32_bf16 v[104:107], v[152:155], v[192:195], v[104:107]
	v_mfma_f32_16x16x32_bf16 v[92:95], v[128:131], v[200:203], v[92:95]
	v_mfma_f32_16x16x32_bf16 v[88:91], v[152:155], v[200:203], v[88:91]
	v_mfma_f32_16x16x32_bf16 v[76:79], v[128:131], v[208:211], v[76:79]
	v_mfma_f32_16x16x32_bf16 v[72:75], v[152:155], v[208:211], v[72:75]
	v_mfma_f32_16x16x32_bf16 v[124:127], v[132:135], v[188:191], v[124:127]
	v_mfma_f32_16x16x32_bf16 v[120:123], v[156:159], v[188:191], v[120:123]
	v_mfma_f32_16x16x32_bf16 v[108:111], v[132:135], v[196:199], v[108:111]
	v_mfma_f32_16x16x32_bf16 v[104:107], v[156:159], v[196:199], v[104:107]
	v_mfma_f32_16x16x32_bf16 v[92:95], v[132:135], v[204:207], v[92:95]
	v_mfma_f32_16x16x32_bf16 v[88:91], v[156:159], v[204:207], v[88:91]
	v_mfma_f32_16x16x32_bf16 v[76:79], v[132:135], v[212:215], v[76:79]
	v_mfma_f32_16x16x32_bf16 v[72:75], v[156:159], v[212:215], v[72:75]
	s_setprio 0
	s_setprio 1
	v_mfma_f32_16x16x32_bf16 v[116:119], v[168:171], v[184:187], v[116:119]
	v_mfma_f32_16x16x32_bf16 v[112:115], v[176:179], v[184:187], v[112:115]
	v_mfma_f32_16x16x32_bf16 v[100:103], v[168:171], v[192:195], v[100:103]
	v_mfma_f32_16x16x32_bf16 v[96:99], v[176:179], v[192:195], v[96:99]
	v_mfma_f32_16x16x32_bf16 v[84:87], v[168:171], v[200:203], v[84:87]
	v_mfma_f32_16x16x32_bf16 v[80:83], v[176:179], v[200:203], v[80:83]
	v_mfma_f32_16x16x32_bf16 v[68:71], v[168:171], v[208:211], v[68:71]
	v_mfma_f32_16x16x32_bf16 v[64:67], v[176:179], v[208:211], v[64:67]
	v_mfma_f32_16x16x32_bf16 v[116:119], v[172:175], v[188:191], v[116:119]
	v_mfma_f32_16x16x32_bf16 v[112:115], v[180:183], v[188:191], v[112:115]
	v_mfma_f32_16x16x32_bf16 v[100:103], v[172:175], v[196:199], v[100:103]
	v_mfma_f32_16x16x32_bf16 v[96:99], v[180:183], v[196:199], v[96:99]
	v_mfma_f32_16x16x32_bf16 v[84:87], v[172:175], v[204:207], v[84:87]
	v_mfma_f32_16x16x32_bf16 v[80:83], v[180:183], v[204:207], v[80:83]
	v_mfma_f32_16x16x32_bf16 v[68:71], v[172:175], v[212:215], v[68:71]
	v_mfma_f32_16x16x32_bf16 v[64:67], v[180:183], v[212:215], v[64:67]
	s_setprio 0
	s_barrier
	s_cmp_lg_u32 s98, 0
	s_cbranch_scc0 .Llp_5
	s_setprio 2
.Llp_5:
	s_add_i32 s73, s62, s52
	v_lshl_add_u64 v[160:161], s[34:35], 0, v[138:139]
	s_mov_b32 m0, s73
	ds_read_b128 v[184:187], v165 offset:16384
	ds_read_b128 v[188:191], v165 offset:17408
	ds_read_b128 v[192:195], v165 offset:18432
	ds_read_b128 v[196:199], v165 offset:19456
	ds_read_b128 v[200:203], v165 offset:20480
	ds_read_b128 v[204:207], v165 offset:21504
	ds_read_b128 v[208:211], v165 offset:22528
	ds_read_b128 v[212:215], v165 offset:23552
	global_load_lds_dwordx4 v[160:161], off
	s_add_i32 m0, s73, 0x2000
	s_add_u32 s74, s34, 0x40000
	v_lshl_add_u64 v[216:217], s[34:35], 0, v[142:143]
	s_addc_u32 s75, s35, 0
	s_add_i32 s73, s63, s52
	global_load_lds_dwordx4 v[216:217], off
	v_lshl_add_u64 v[218:219], s[74:75], 0, v[138:139]
	s_mov_b32 m0, s73
	v_lshl_add_u64 v[220:221], s[40:41], 0, v[140:141]
	global_load_lds_dwordx4 v[218:219], off
	v_lshl_add_u64 v[218:219], s[74:75], 0, v[142:143]
	s_add_i32 m0, s73, 0x2000
	s_nop 0
	global_load_lds_dwordx4 v[218:219], off
	v_lshl_add_u64 v[218:219], s[40:41], 0, v[136:137]
	s_mov_b32 m0, s49
	s_nop 0
	global_load_lds_dwordx4 v[218:219], off
	s_mov_b32 m0, s51
	s_nop 0
	global_load_lds_dwordx4 v[220:221], off
	s_waitcnt vmcnt(8)
	s_waitcnt lgkmcnt(0)
	s_barrier
; #define PG8_STAGE(bufoff, gbase, voff) do { _Pragma("unroll") for (int _i = 0; _i < 2; ++_i) \
;         __builtin_amdgcn_global_load_lds((const unsigned*)((const char*)(gbase) + (voff)[_i]), (PG8_LAS unsigned*)(lds + (bufoff) + ldsw + _i * 8192), 16, 0, 0); } while (0)
; #define PG8_LDA(dst, b, h) do { _Pragma("unroll") for (int m = 0; m < 4; ++m) _Pragma("unroll") for (int k = 0; k < 2; ++k) dst[m][k] = *(const PG8_LAS bf16x8*)(lds + PG8_SA(b, h) + aoff + m * 2048 + k * 1024); } while (0)
; #define PG8_LDB(dst, b, h) do { _Pragma("unroll") for (int n = 0; n < 2; ++n) _Pragma("unroll") for (int k = 0; k < 2; ++k) dst[n][k] = *(const PG8_LAS bf16x8*)(lds + PG8_SB(b, h) + boff + n * 2048 + k * 1024); } while (0)
; #define PG8_MMA(ai, bj, At, Bt) do { __builtin_amdgcn_s_setprio(1); _Pragma("unroll") for (int m = 0; m < 4; ++m) _Pragma("unroll") for (int n = 0; n < 2; ++n) _Pragma("unroll") for (int k = 0; k < 2; ++k) \
;         acc[ai][bj][m][n] = __builtin_amdgcn_mfma_f32_16x16x32_bf16(Bt[n][k], At[m][k], acc[ai][bj][m][n], 0, 0, 0); __builtin_amdgcn_s_setprio(0); } while (0)
; #define PG8_WAIT_V(n) asm volatile("s_waitcnt vmcnt(" #n ")" ::: "memory")
; #define PG8_WAIT_L(n) asm volatile("s_waitcnt lgkmcnt(" #n ")" ::: "memory")
; #define PG8_BAR __builtin_amdgcn_s_barrier()
; #define PG8_SCHED __builtin_amdgcn_sched_barrier(0)
;     ...
;             PG8_WAIT_V(8); PG8_WAIT_L(0); PG8_BAR; PG8_MMA(1, 0, At, B0); PG8_MMA(1, 1, At, B1); PG8_BAR; PG8_SCHED;
;             PG8_LDB(B0, 1, 0); PG8_LDB(B1, 1, 1); PG8_SCHED; PG8_LDA(At, 1, 0); PG8_STAGE(PG8_SA(0, 1), a2 + hstepA, voffA);
;             PG8_WAIT_V(8); PG8_WAIT_L(0); PG8_BAR; PG8_MMA(0, 0, At, B0); PG8_MMA(0, 1, At, B1); PG8_BAR; PG8_SCHED;
	s_setprio 1
	s_waitcnt lgkmcnt(0)
	v_mfma_f32_16x16x32_bf16 v[60:63], v[128:131], v[184:187], v[60:63]
	v_mfma_f32_16x16x32_bf16 v[56:59], v[152:155], v[184:187], v[56:59]
	v_mfma_f32_16x16x32_bf16 v[44:47], v[128:131], v[192:195], v[44:47]
	v_mfma_f32_16x16x32_bf16 v[40:43], v[152:155], v[192:195], v[40:43]
	v_mfma_f32_16x16x32_bf16 v[28:31], v[128:131], v[200:203], v[28:31]
	v_mfma_f32_16x16x32_bf16 v[24:27], v[152:155], v[200:203], v[24:27]
	v_mfma_f32_16x16x32_bf16 v[12:15], v[128:131], v[208:211], v[12:15]
	v_mfma_f32_16x16x32_bf16 v[8:11], v[152:155], v[208:211], v[8:11]
	v_mfma_f32_16x16x32_bf16 v[60:63], v[132:135], v[188:191], v[60:63]
	v_mfma_f32_16x16x32_bf16 v[56:59], v[156:159], v[188:191], v[56:59]
	v_mfma_f32_16x16x32_bf16 v[44:47], v[132:135], v[196:199], v[44:47]
	v_mfma_f32_16x16x32_bf16 v[40:43], v[156:159], v[196:199], v[40:43]
	v_mfma_f32_16x16x32_bf16 v[28:31], v[132:135], v[204:207], v[28:31]
	v_mfma_f32_16x16x32_bf16 v[24:27], v[156:159], v[204:207], v[24:27]
	v_mfma_f32_16x16x32_bf16 v[12:15], v[132:135], v[212:215], v[12:15]
	v_mfma_f32_16x16x32_bf16 v[8:11], v[156:159], v[212:215], v[8:11]
	s_setprio 0
	s_setprio 1
	v_mfma_f32_16x16x32_bf16 v[52:55], v[168:171], v[184:187], v[52:55]
	v_mfma_f32_16x16x32_bf16 v[48:51], v[176:179], v[184:187], v[48:51]
	v_mfma_f32_16x16x32_bf16 v[36:39], v[168:171], v[192:195], v[36:39]
	v_mfma_f32_16x16x32_bf16 v[32:35], v[176:179], v[192:195], v[32:35]
	v_mfma_f32_16x16x32_bf16 v[20:23], v[168:171], v[200:203], v[20:23]
	v_mfma_f32_16x16x32_bf16 v[16:19], v[176:179], v[200:203], v[16:19]
	v_mfma_f32_16x16x32_bf16 v[4:7], v[168:171], v[208:211], v[4:7]
	v_mfma_f32_16x16x32_bf16 v[0:3], v[176:179], v[208:211], v[0:3]
	v_mfma_f32_16x16x32_bf16 v[52:55], v[172:175], v[188:191], v[52:55]
	v_mfma_f32_16x16x32_bf16 v[48:51], v[180:183], v[188:191], v[48:51]
	v_mfma_f32_16x16x32_bf16 v[36:39], v[172:175], v[196:199], v[36:39]
	v_mfma_f32_16x16x32_bf16 v[32:35], v[180:183], v[196:199], v[32:35]
	v_mfma_f32_16x16x32_bf16 v[20:23], v[172:175], v[204:207], v[20:23]
	v_mfma_f32_16x16x32_bf16 v[16:19], v[180:183], v[204:207], v[16:19]
	v_mfma_f32_16x16x32_bf16 v[4:7], v[172:175], v[212:215], v[4:7]
	v_mfma_f32_16x16x32_bf16 v[0:3], v[180:183], v[212:215], v[0:3]
	s_setprio 0
	s_barrier
	s_cmp_lg_u32 s98, 0
	s_cbranch_scc0 .Llp_6
	s_setprio 2
.Llp_6:
	s_add_i32 s73, 0, 0x18000
	s_add_i32 s74, 0, 0x1c000
	v_add_u32_e32 v156, s73, v162
	v_add_u32_e32 v167, s74, v162
	ds_read_b128 v[128:131], v156
	ds_read_b128 v[132:135], v156 offset:1024
	ds_read_b128 v[152:155], v156 offset:2048
	ds_read_b128 v[156:159], v156 offset:3072
	ds_read_b128 v[168:171], v167
	ds_read_b128 v[172:175], v167 offset:1024
	ds_read_b128 v[176:179], v167 offset:2048
	ds_read_b128 v[180:183], v167 offset:3072
	s_add_u32 s40, s40, 0x40000
	s_addc_u32 s41, s41, 0
	s_mov_b32 m0, s53
	v_lshl_add_u64 v[222:223], s[40:41], 0, v[136:137]
	ds_read_b128 v[184:187], v165 offset:32768
	ds_read_b128 v[188:191], v165 offset:33792
	ds_read_b128 v[192:195], v165 offset:34816
	ds_read_b128 v[196:199], v165 offset:35840
	ds_read_b128 v[200:203], v165 offset:36864
	ds_read_b128 v[204:207], v165 offset:37888
	ds_read_b128 v[208:211], v165 offset:38912
	ds_read_b128 v[212:215], v165 offset:39936
	global_load_lds_dwordx4 v[222:223], off
	v_lshl_add_u64 v[222:223], s[40:41], 0, v[140:141]
	s_mov_b32 m0, s54
	s_nop 0
	global_load_lds_dwordx4 v[222:223], off
	s_waitcnt vmcnt(8)
	s_waitcnt lgkmcnt(0)
	s_barrier
	s_setprio 1
	s_waitcnt lgkmcnt(0)
	v_mfma_f32_16x16x32_bf16 v[124:127], v[128:131], v[184:187], v[124:127]
	v_mfma_f32_16x16x32_bf16 v[120:123], v[152:155], v[184:187], v[120:123]
	v_mfma_f32_16x16x32_bf16 v[108:111], v[128:131], v[192:195], v[108:111]
	v_mfma_f32_16x16x32_bf16 v[104:107], v[152:155], v[192:195], v[104:107]
	v_mfma_f32_16x16x32_bf16 v[92:95], v[128:131], v[200:203], v[92:95]
	v_mfma_f32_16x16x32_bf16 v[88:91], v[152:155], v[200:203], v[88:91]
	v_mfma_f32_16x16x32_bf16 v[76:79], v[128:131], v[208:211], v[76:79]
	v_mfma_f32_16x16x32_bf16 v[72:75], v[152:155], v[208:211], v[72:75]
	v_mfma_f32_16x16x32_bf16 v[124:127], v[132:135], v[188:191], v[124:127]
	v_mfma_f32_16x16x32_bf16 v[120:123], v[156:159], v[188:191], v[120:123]
	v_mfma_f32_16x16x32_bf16 v[108:111], v[132:135], v[196:199], v[108:111]
	v_mfma_f32_16x16x32_bf16 v[104:107], v[156:159], v[196:199], v[104:107]
	v_mfma_f32_16x16x32_bf16 v[92:95], v[132:135], v[204:207], v[92:95]
	v_mfma_f32_16x16x32_bf16 v[88:91], v[156:159], v[204:207], v[88:91]
	v_mfma_f32_16x16x32_bf16 v[76:79], v[132:135], v[212:215], v[76:79]
	v_mfma_f32_16x16x32_bf16 v[72:75], v[156:159], v[212:215], v[72:75]
	s_setprio 0
	s_setprio 1
	v_mfma_f32_16x16x32_bf16 v[116:119], v[168:171], v[184:187], v[116:119]
	v_mfma_f32_16x16x32_bf16 v[112:115], v[176:179], v[184:187], v[112:115]
	v_mfma_f32_16x16x32_bf16 v[100:103], v[168:171], v[192:195], v[100:103]
	v_mfma_f32_16x16x32_bf16 v[96:99], v[176:179], v[192:195], v[96:99]
	v_mfma_f32_16x16x32_bf16 v[84:87], v[168:171], v[200:203], v[84:87]
	v_mfma_f32_16x16x32_bf16 v[80:83], v[176:179], v[200:203], v[80:83]
	v_mfma_f32_16x16x32_bf16 v[68:71], v[168:171], v[208:211], v[68:71]
	v_mfma_f32_16x16x32_bf16 v[64:67], v[176:179], v[208:211], v[64:67]
	v_mfma_f32_16x16x32_bf16 v[116:119], v[172:175], v[188:191], v[116:119]
	v_mfma_f32_16x16x32_bf16 v[112:115], v[180:183], v[188:191], v[112:115]
	v_mfma_f32_16x16x32_bf16 v[100:103], v[172:175], v[196:199], v[100:103]
	v_mfma_f32_16x16x32_bf16 v[96:99], v[180:183], v[196:199], v[96:99]
	v_mfma_f32_16x16x32_bf16 v[84:87], v[172:175], v[204:207], v[84:87]
	v_mfma_f32_16x16x32_bf16 v[80:83], v[180:183], v[204:207], v[80:83]
	v_mfma_f32_16x16x32_bf16 v[68:71], v[172:175], v[212:215], v[68:71]
	v_mfma_f32_16x16x32_bf16 v[64:67], v[180:183], v[212:215], v[64:67]
	s_setprio 0
	s_barrier
	s_cmp_lg_u32 s98, 0
	s_cbranch_scc0 .Llp_7
	s_setprio 2
; #define PG8_STAGE(bufoff, gbase, voff) do { _Pragma("unroll") for (int _i = 0; _i < 2; ++_i) \
;         __builtin_amdgcn_global_load_lds((const unsigned*)((const char*)(gbase) + (voff)[_i]), (PG8_LAS unsigned*)(lds + (bufoff) + ldsw + _i * 8192), 16, 0, 0); } while (0)
; #define PG8_LDA(dst, b, h) do { _Pragma("unroll") for (int m = 0; m < 4; ++m) _Pragma("unroll") for (int k = 0; k < 2; ++k) dst[m][k] = *(const PG8_LAS bf16x8*)(lds + PG8_SA(b, h) + aoff + m * 2048 + k * 1024); } while (0)
; #define PG8_MMA(ai, bj, At, Bt) do { __builtin_amdgcn_s_setprio(1); _Pragma("unroll") for (int m = 0; m < 4; ++m) _Pragma("unroll") for (int n = 0; n < 2; ++n) _Pragma("unroll") for (int k = 0; k < 2; ++k) \
;         acc[ai][bj][m][n] = __builtin_amdgcn_mfma_f32_16x16x32_bf16(Bt[n][k], At[m][k], acc[ai][bj][m][n], 0, 0, 0); __builtin_amdgcn_s_setprio(0); } while (0)
; #define PG8_WAIT_V(n) asm volatile("s_waitcnt vmcnt(" #n ")" ::: "memory")
; #define PG8_WAIT_L(n) asm volatile("s_waitcnt lgkmcnt(" #n ")" ::: "memory")
; #define PG8_BAR __builtin_amdgcn_s_barrier()
; #define PG8_SCHED __builtin_amdgcn_sched_barrier(0)
;     ...
;         for (int t = 0; t < nt; t += 2) {
;     ...
;             PG8_LDA(At, 1, 1); PG8_STAGE(PG8_SB(1, 0), b3, voffB); PG8_STAGE(PG8_SB(1, 1), b3 + hstepB, voffB); PG8_STAGE(PG8_SA(1, 0), a3, voffA);
;             PG8_WAIT_V(8); PG8_WAIT_L(0); PG8_BAR; PG8_MMA(1, 0, At, B0); PG8_MMA(1, 1, At, B1); PG8_BAR; PG8_SCHED;
.Llp_7:
	s_add_i32 s40, s73, s52
	v_lshl_add_u64 v[160:161], v[160:161], 0, s[16:17]
	s_mov_b32 m0, s40
	ds_read_b128 v[184:187], v165 offset:49152
	ds_read_b128 v[188:191], v165 offset:50176
	ds_read_b128 v[192:195], v165 offset:51200
	ds_read_b128 v[196:199], v165 offset:52224
	ds_read_b128 v[200:203], v165 offset:53248
	ds_read_b128 v[204:207], v165 offset:54272
	ds_read_b128 v[208:211], v165 offset:55296
	ds_read_b128 v[212:215], v165 offset:56320
	global_load_lds_dwordx4 v[160:161], off
	s_add_i32 m0, s40, 0x2000
	s_add_u32 s34, s34, 0x40080
	v_lshl_add_u64 v[160:161], v[216:217], 0, s[16:17]
	s_addc_u32 s35, s35, 0
	s_add_i32 s40, s74, s52
	global_load_lds_dwordx4 v[160:161], off
	v_lshl_add_u64 v[160:161], s[34:35], 0, v[138:139]
	s_mov_b32 m0, s40
	s_nop 0
	global_load_lds_dwordx4 v[160:161], off
	v_lshl_add_u64 v[160:161], s[34:35], 0, v[142:143]
	s_add_i32 m0, s40, 0x2000
	s_nop 0
	global_load_lds_dwordx4 v[160:161], off
	v_lshl_add_u64 v[160:161], v[218:219], 0, s[16:17]
	s_mov_b32 m0, s58
	s_nop 0
	global_load_lds_dwordx4 v[160:161], off
	v_lshl_add_u64 v[160:161], v[220:221], 0, s[16:17]
	s_mov_b32 m0, s59
	s_nop 0
	global_load_lds_dwordx4 v[160:161], off
	s_waitcnt vmcnt(8)
	s_waitcnt lgkmcnt(0)
	s_barrier
	s_setprio 1
	s_waitcnt lgkmcnt(0)
	v_mfma_f32_16x16x32_bf16 v[60:63], v[128:131], v[184:187], v[60:63]
	v_mfma_f32_16x16x32_bf16 v[56:59], v[152:155], v[184:187], v[56:59]
	v_mfma_f32_16x16x32_bf16 v[44:47], v[128:131], v[192:195], v[44:47]
	v_mfma_f32_16x16x32_bf16 v[40:43], v[152:155], v[192:195], v[40:43]
	v_mfma_f32_16x16x32_bf16 v[28:31], v[128:131], v[200:203], v[28:31]
	v_mfma_f32_16x16x32_bf16 v[24:27], v[152:155], v[200:203], v[24:27]
	v_mfma_f32_16x16x32_bf16 v[12:15], v[128:131], v[208:211], v[12:15]
	v_mfma_f32_16x16x32_bf16 v[8:11], v[152:155], v[208:211], v[8:11]
	v_mfma_f32_16x16x32_bf16 v[60:63], v[132:135], v[188:191], v[60:63]
	v_mfma_f32_16x16x32_bf16 v[56:59], v[156:159], v[188:191], v[56:59]
	v_mfma_f32_16x16x32_bf16 v[44:47], v[132:135], v[196:199], v[44:47]
	v_mfma_f32_16x16x32_bf16 v[40:43], v[156:159], v[196:199], v[40:43]
	v_mfma_f32_16x16x32_bf16 v[28:31], v[132:135], v[204:207], v[28:31]
	v_mfma_f32_16x16x32_bf16 v[24:27], v[156:159], v[204:207], v[24:27]
	v_mfma_f32_16x16x32_bf16 v[12:15], v[132:135], v[212:215], v[12:15]
	v_mfma_f32_16x16x32_bf16 v[8:11], v[156:159], v[212:215], v[8:11]
	s_setprio 0
	s_setprio 1
	v_mfma_f32_16x16x32_bf16 v[52:55], v[168:171], v[184:187], v[52:55]
	v_mfma_f32_16x16x32_bf16 v[48:51], v[176:179], v[184:187], v[48:51]
	v_mfma_f32_16x16x32_bf16 v[36:39], v[168:171], v[192:195], v[36:39]
	v_mfma_f32_16x16x32_bf16 v[32:35], v[176:179], v[192:195], v[32:35]
	v_mfma_f32_16x16x32_bf16 v[20:23], v[168:171], v[200:203], v[20:23]
	v_mfma_f32_16x16x32_bf16 v[16:19], v[176:179], v[200:203], v[16:19]
	v_mfma_f32_16x16x32_bf16 v[4:7], v[168:171], v[208:211], v[4:7]
	v_mfma_f32_16x16x32_bf16 v[0:3], v[176:179], v[208:211], v[0:3]
	v_mfma_f32_16x16x32_bf16 v[52:55], v[172:175], v[188:191], v[52:55]
	v_mfma_f32_16x16x32_bf16 v[48:51], v[180:183], v[188:191], v[48:51]
	v_mfma_f32_16x16x32_bf16 v[36:39], v[172:175], v[196:199], v[36:39]
	v_mfma_f32_16x16x32_bf16 v[32:35], v[180:183], v[196:199], v[32:35]
	v_mfma_f32_16x16x32_bf16 v[20:23], v[172:175], v[204:207], v[20:23]
	v_mfma_f32_16x16x32_bf16 v[16:19], v[180:183], v[204:207], v[16:19]
	v_mfma_f32_16x16x32_bf16 v[4:7], v[172:175], v[212:215], v[4:7]
	v_mfma_f32_16x16x32_bf16 v[0:3], v[180:183], v[212:215], v[0:3]
	s_setprio 0
	s_barrier
	s_cmp_lg_u32 s98, 0
	s_cbranch_scc0 .Llp_8
	s_setprio 2
.Llp_8:
	s_add_i32 s72, s72, 2
	s_add_u32 s28, s28, 0x100
	s_addc_u32 s29, s29, 0
	s_add_u32 s70, s70, 0x100
	s_addc_u32 s71, s71, 0
	s_cmp_gt_u32 s72, 13
	s_cbranch_scc0 .LBB0_396
	s_and_b64 vcc, exec, s[18:19]
	s_cbranch_vccz .LBB0_399
	s_barrier

; #define PG8_STAGE(bufoff, gbase, voff) do { _Pragma("unroll") for (int _i = 0; _i < 2; ++_i) \
;         __builtin_amdgcn_global_load_lds((const unsigned*)((const char*)(gbase) + (voff)[_i]), (PG8_LAS unsigned*)(lds + (bufoff) + ldsw + _i * 8192), 16, 0, 0); } while (0)
; #define PG8_LDA(dst, b, h) do { _Pragma("unroll") for (int m = 0; m < 4; ++m) _Pragma("unroll") for (int k = 0; k < 2; ++k) dst[m][k] = *(const PG8_LAS bf16x8*)(lds + PG8_SA(b, h) + aoff + m * 2048 + k * 1024); } while (0)
; #define PG8_LDB(dst, b, h) do { _Pragma("unroll") for (int n = 0; n < 2; ++n) _Pragma("unroll") for (int k = 0; k < 2; ++k) dst[n][k] = *(const PG8_LAS bf16x8*)(lds + PG8_SB(b, h) + boff + n * 2048 + k * 1024); } while (0)
; #define PG8_MMA(ai, bj, At, Bt) do { __builtin_amdgcn_s_setprio(1); _Pragma("unroll") for (int m = 0; m < 4; ++m) _Pragma("unroll") for (int n = 0; n < 2; ++n) _Pragma("unroll") for (int k = 0; k < 2; ++k) \
;         acc[ai][bj][m][n] = __builtin_amdgcn_mfma_f32_16x16x32_bf16(Bt[n][k], At[m][k], acc[ai][bj][m][n], 0, 0, 0); __builtin_amdgcn_s_setprio(0); } while (0)
; #define PG8_WAIT_V(n) asm volatile("s_waitcnt vmcnt(" #n ")" ::: "memory")
; #define PG8_WAIT_L(n) asm volatile("s_waitcnt lgkmcnt(" #n ")" ::: "memory")
; #define PG8_BAR __builtin_amdgcn_s_barrier()
; #define PG8_SCHED __builtin_amdgcn_sched_barrier(0)
;     ...
;             const bool last = (t == nt - 2);
;             const char* a1 = cA + (size_t)(t + 1) * kstep;
;             const char* a2 = last ? nA : cA + (size_t)(t + 2) * kstep; const char* b2 = last ? nB : cB + (size_t)(t + 2) * kstep;
;             const char* a3 = a2 + kstep; const char* b3 = b2 + kstep;
;             if (last && has_next) S.a_ready(nxt);
;             if constexpr (SP2) {
;             PG8_LDB(B0, 0, 0); PG8_LDB(B1, 0, 1); PG8_SCHED; PG8_LDA(At, 0, 0); PG8_STAGE(PG8_SA(1, 1), a1 + hstepA, voffA);
;             PG8_WAIT_V(8); PG8_WAIT_L(0); PG8_BAR; PG8_MMA(0, 0, At, B0); PG8_MMA(0, 1, At, B1); PG8_BAR; PG8_SCHED;
;             PG8_LDA(At, 0, 1); PG8_STAGE(PG8_SB(0, 0), b2, voffB); PG8_STAGE(PG8_SB(0, 1), b2 + hstepB, voffB); PG8_STAGE(PG8_SA(0, 0), a2, voffA);
.LBB0_632:
	s_add_u32 s28, s8, 0xfffe0080
	s_addc_u32 s29, s9, -1
	s_add_i32 s48, 0, 0x10000
	s_cmp_eq_u32 s86, 2
	s_cselect_b32 s35, s23, s29
	s_cselect_b32 s34, s37, s28
	s_cselect_b32 s29, s25, s85
	s_cselect_b32 s28, s24, s69
	s_add_i32 s61, 0, 0x14000
	v_add_u32_e32 v142, s48, v1
	v_add_u32_e32 v158, s61, v1
	ds_read_b128 v[130:133], v142
	ds_read_b128 v[134:137], v142 offset:1024
	ds_read_b128 v[138:141], v142 offset:2048
	ds_read_b128 v[142:145], v142 offset:3072
	ds_read_b128 v[146:149], v158
	ds_read_b128 v[150:153], v158 offset:1024
	ds_read_b128 v[154:157], v158 offset:2048
	ds_read_b128 v[158:161], v158 offset:3072
	v_lshl_add_u64 v[188:189], s[8:9], 0, v[170:171]
	s_add_i32 m0, s43, 0xc000
	ds_read_b128 v[174:177], v190
	ds_read_b128 v[180:183], v190 offset:1024
	ds_read_b128 v[184:187], v190 offset:2048
	ds_read_b128 v[192:195], v190 offset:3072
	ds_read_b128 v[196:199], v190 offset:4096
	ds_read_b128 v[200:203], v190 offset:5120
	ds_read_b128 v[204:207], v190 offset:6144
	ds_read_b128 v[210:213], v190 offset:7168
	global_load_lds_dwordx4 v[188:189], off
	v_lshl_add_u64 v[188:189], s[8:9], 0, v[172:173]
	s_add_i32 m0, s43, 0xe000
	s_nop 0
	global_load_lds_dwordx4 v[188:189], off
	s_waitcnt vmcnt(8)
	s_waitcnt lgkmcnt(0)
	s_barrier
	s_setprio 1
	s_waitcnt lgkmcnt(0)
	v_mfma_f32_16x16x32_bf16 v[126:129], v[130:133], v[174:177], v[126:129]
	v_mfma_f32_16x16x32_bf16 v[122:125], v[138:141], v[174:177], v[122:125]
	v_mfma_f32_16x16x32_bf16 v[110:113], v[130:133], v[184:187], v[110:113]
	v_mfma_f32_16x16x32_bf16 v[106:109], v[138:141], v[184:187], v[106:109]
	v_mfma_f32_16x16x32_bf16 v[94:97], v[130:133], v[196:199], v[94:97]
	v_mfma_f32_16x16x32_bf16 v[90:93], v[138:141], v[196:199], v[90:93]
	v_mfma_f32_16x16x32_bf16 v[78:81], v[130:133], v[204:207], v[78:81]
	v_mfma_f32_16x16x32_bf16 v[74:77], v[138:141], v[204:207], v[74:77]
	v_mfma_f32_16x16x32_bf16 v[126:129], v[134:137], v[180:183], v[126:129]
	v_mfma_f32_16x16x32_bf16 v[122:125], v[142:145], v[180:183], v[122:125]
	v_mfma_f32_16x16x32_bf16 v[110:113], v[134:137], v[192:195], v[110:113]
	v_mfma_f32_16x16x32_bf16 v[106:109], v[142:145], v[192:195], v[106:109]
	v_mfma_f32_16x16x32_bf16 v[94:97], v[134:137], v[200:203], v[94:97]
	v_mfma_f32_16x16x32_bf16 v[90:93], v[142:145], v[200:203], v[90:93]
	v_mfma_f32_16x16x32_bf16 v[78:81], v[134:137], v[210:213], v[78:81]
	v_mfma_f32_16x16x32_bf16 v[74:77], v[142:145], v[210:213], v[74:77]
	s_setprio 0
	s_setprio 1
	v_mfma_f32_16x16x32_bf16 v[118:121], v[146:149], v[174:177], v[118:121]
	v_mfma_f32_16x16x32_bf16 v[114:117], v[154:157], v[174:177], v[114:117]
	v_mfma_f32_16x16x32_bf16 v[102:105], v[146:149], v[184:187], v[102:105]
	v_mfma_f32_16x16x32_bf16 v[98:101], v[154:157], v[184:187], v[98:101]
	v_mfma_f32_16x16x32_bf16 v[86:89], v[146:149], v[196:199], v[86:89]
	v_mfma_f32_16x16x32_bf16 v[82:85], v[154:157], v[196:199], v[82:85]
	v_mfma_f32_16x16x32_bf16 v[70:73], v[146:149], v[204:207], v[70:73]
	v_mfma_f32_16x16x32_bf16 v[66:69], v[154:157], v[204:207], v[66:69]
	v_mfma_f32_16x16x32_bf16 v[118:121], v[150:153], v[180:183], v[118:121]
	v_mfma_f32_16x16x32_bf16 v[114:117], v[158:161], v[180:183], v[114:117]
	v_mfma_f32_16x16x32_bf16 v[102:105], v[150:153], v[192:195], v[102:105]
	v_mfma_f32_16x16x32_bf16 v[98:101], v[158:161], v[192:195], v[98:101]
	v_mfma_f32_16x16x32_bf16 v[86:89], v[150:153], v[200:203], v[86:89]
	v_mfma_f32_16x16x32_bf16 v[82:85], v[158:161], v[200:203], v[82:85]
	v_mfma_f32_16x16x32_bf16 v[70:73], v[150:153], v[210:213], v[70:73]
	v_mfma_f32_16x16x32_bf16 v[66:69], v[158:161], v[210:213], v[66:69]
	s_setprio 0
	s_barrier
	s_cmp_lg_u32 s98, 0
	s_cbranch_scc0 .Llp_9
	s_setprio 2
.Llp_9:
	s_add_i32 s48, s48, s42
	v_lshl_add_u64 v[188:189], s[28:29], 0, v[166:167]
	s_mov_b32 m0, s48
	ds_read_b128 v[174:177], v190 offset:16384
	ds_read_b128 v[180:183], v190 offset:17408
	ds_read_b128 v[184:187], v190 offset:18432
	ds_read_b128 v[192:195], v190 offset:19456
	ds_read_b128 v[196:199], v190 offset:20480
	ds_read_b128 v[200:203], v190 offset:21504
	ds_read_b128 v[204:207], v190 offset:22528
	ds_read_b128 v[210:213], v190 offset:23552
	global_load_lds_dwordx4 v[188:189], off
	s_add_i32 m0, s48, 0x2000
	s_add_u32 s48, s28, 0x18000
	v_lshl_add_u64 v[214:215], s[28:29], 0, v[162:163]
	s_addc_u32 s49, s29, 0
	s_add_i32 s61, s61, s42
	global_load_lds_dwordx4 v[214:215], off
	v_lshl_add_u64 v[216:217], s[48:49], 0, v[166:167]
	s_mov_b32 m0, s61
	v_lshl_add_u64 v[218:219], s[34:35], 0, v[164:165]
	global_load_lds_dwordx4 v[216:217], off
	v_lshl_add_u64 v[216:217], s[48:49], 0, v[162:163]
	s_add_i32 m0, s61, 0x2000
	s_nop 0
	global_load_lds_dwordx4 v[216:217], off
	v_lshl_add_u64 v[216:217], s[34:35], 0, v[168:169]
	s_mov_b32 m0, s43
	s_nop 0
	global_load_lds_dwordx4 v[216:217], off
	s_mov_b32 m0, s44
	s_nop 0
	global_load_lds_dwordx4 v[218:219], off
	s_waitcnt vmcnt(8)
	s_waitcnt lgkmcnt(0)
	s_barrier
; #define PG8_STAGE(bufoff, gbase, voff) do { _Pragma("unroll") for (int _i = 0; _i < 2; ++_i) \
;         __builtin_amdgcn_global_load_lds((const unsigned*)((const char*)(gbase) + (voff)[_i]), (PG8_LAS unsigned*)(lds + (bufoff) + ldsw + _i * 8192), 16, 0, 0); } while (0)
; #define PG8_LDA(dst, b, h) do { _Pragma("unroll") for (int m = 0; m < 4; ++m) _Pragma("unroll") for (int k = 0; k < 2; ++k) dst[m][k] = *(const PG8_LAS bf16x8*)(lds + PG8_SA(b, h) + aoff + m * 2048 + k * 1024); } while (0)
; #define PG8_LDB(dst, b, h) do { _Pragma("unroll") for (int n = 0; n < 2; ++n) _Pragma("unroll") for (int k = 0; k < 2; ++k) dst[n][k] = *(const PG8_LAS bf16x8*)(lds + PG8_SB(b, h) + boff + n * 2048 + k * 1024); } while (0)
; #define PG8_MMA(ai, bj, At, Bt) do { __builtin_amdgcn_s_setprio(1); _Pragma("unroll") for (int m = 0; m < 4; ++m) _Pragma("unroll") for (int n = 0; n < 2; ++n) _Pragma("unroll") for (int k = 0; k < 2; ++k) \
;         acc[ai][bj][m][n] = __builtin_amdgcn_mfma_f32_16x16x32_bf16(Bt[n][k], At[m][k], acc[ai][bj][m][n], 0, 0, 0); __builtin_amdgcn_s_setprio(0); } while (0)
; #define PG8_WAIT_V(n) asm volatile("s_waitcnt vmcnt(" #n ")" ::: "memory")
; #define PG8_WAIT_L(n) asm volatile("s_waitcnt lgkmcnt(" #n ")" ::: "memory")
; #define PG8_BAR __builtin_amdgcn_s_barrier()
; #define PG8_SCHED __builtin_amdgcn_sched_barrier(0)
;     ...
;             PG8_WAIT_V(8); PG8_WAIT_L(0); PG8_BAR; PG8_MMA(1, 0, At, B0); PG8_MMA(1, 1, At, B1); PG8_BAR; PG8_SCHED;
;             PG8_LDB(B0, 1, 0); PG8_LDB(B1, 1, 1); PG8_SCHED; PG8_LDA(At, 1, 0); PG8_STAGE(PG8_SA(0, 1), a2 + hstepA, voffA);
;             PG8_WAIT_V(8); PG8_WAIT_L(0); PG8_BAR; PG8_MMA(0, 0, At, B0); PG8_MMA(0, 1, At, B1); PG8_BAR; PG8_SCHED;
	s_setprio 1
	s_waitcnt lgkmcnt(0)
	v_mfma_f32_16x16x32_bf16 v[62:65], v[130:133], v[174:177], v[62:65]
	v_mfma_f32_16x16x32_bf16 v[58:61], v[138:141], v[174:177], v[58:61]
	v_mfma_f32_16x16x32_bf16 v[46:49], v[130:133], v[184:187], v[46:49]
	v_mfma_f32_16x16x32_bf16 v[42:45], v[138:141], v[184:187], v[42:45]
	v_mfma_f32_16x16x32_bf16 v[30:33], v[130:133], v[196:199], v[30:33]
	v_mfma_f32_16x16x32_bf16 v[26:29], v[138:141], v[196:199], v[26:29]
	v_mfma_f32_16x16x32_bf16 v[14:17], v[130:133], v[204:207], v[14:17]
	v_mfma_f32_16x16x32_bf16 v[10:13], v[138:141], v[204:207], v[10:13]
	v_mfma_f32_16x16x32_bf16 v[62:65], v[134:137], v[180:183], v[62:65]
	v_mfma_f32_16x16x32_bf16 v[58:61], v[142:145], v[180:183], v[58:61]
	v_mfma_f32_16x16x32_bf16 v[46:49], v[134:137], v[192:195], v[46:49]
	v_mfma_f32_16x16x32_bf16 v[42:45], v[142:145], v[192:195], v[42:45]
	v_mfma_f32_16x16x32_bf16 v[30:33], v[134:137], v[200:203], v[30:33]
	v_mfma_f32_16x16x32_bf16 v[26:29], v[142:145], v[200:203], v[26:29]
	v_mfma_f32_16x16x32_bf16 v[14:17], v[134:137], v[210:213], v[14:17]
	v_mfma_f32_16x16x32_bf16 v[10:13], v[142:145], v[210:213], v[10:13]
	s_setprio 0
	s_setprio 1
	v_mfma_f32_16x16x32_bf16 v[54:57], v[146:149], v[174:177], v[54:57]
	v_mfma_f32_16x16x32_bf16 v[50:53], v[154:157], v[174:177], v[50:53]
	v_mfma_f32_16x16x32_bf16 v[38:41], v[146:149], v[184:187], v[38:41]
	v_mfma_f32_16x16x32_bf16 v[34:37], v[154:157], v[184:187], v[34:37]
	v_mfma_f32_16x16x32_bf16 v[22:25], v[146:149], v[196:199], v[22:25]
	v_mfma_f32_16x16x32_bf16 v[18:21], v[154:157], v[196:199], v[18:21]
	v_mfma_f32_16x16x32_bf16 v[6:9], v[146:149], v[204:207], v[6:9]
	v_mfma_f32_16x16x32_bf16 v[2:5], v[154:157], v[204:207], v[2:5]
	v_mfma_f32_16x16x32_bf16 v[54:57], v[150:153], v[180:183], v[54:57]
	v_mfma_f32_16x16x32_bf16 v[50:53], v[158:161], v[180:183], v[50:53]
	v_mfma_f32_16x16x32_bf16 v[38:41], v[150:153], v[192:195], v[38:41]
	v_mfma_f32_16x16x32_bf16 v[34:37], v[158:161], v[192:195], v[34:37]
	v_mfma_f32_16x16x32_bf16 v[22:25], v[150:153], v[200:203], v[22:25]
	v_mfma_f32_16x16x32_bf16 v[18:21], v[158:161], v[200:203], v[18:21]
	v_mfma_f32_16x16x32_bf16 v[6:9], v[150:153], v[210:213], v[6:9]
	v_mfma_f32_16x16x32_bf16 v[2:5], v[158:161], v[210:213], v[2:5]
	s_setprio 0
	s_barrier
	s_cmp_lg_u32 s98, 0
	s_cbranch_scc0 .Llp_10
	s_setprio 2
.Llp_10:
	s_add_i32 s48, 0, 0x18000
	s_add_i32 s49, 0, 0x1c000
	v_add_u32_e32 v142, s48, v1
	v_add_u32_e32 v158, s49, v1
	ds_read_b128 v[130:133], v142
	ds_read_b128 v[134:137], v142 offset:1024
	ds_read_b128 v[138:141], v142 offset:2048
	ds_read_b128 v[142:145], v142 offset:3072
	ds_read_b128 v[146:149], v158
	ds_read_b128 v[150:153], v158 offset:1024
	ds_read_b128 v[154:157], v158 offset:2048
	ds_read_b128 v[158:161], v158 offset:3072
	s_add_u32 s34, s34, 0x20000
	s_addc_u32 s35, s35, 0
	s_mov_b32 m0, s45
	v_lshl_add_u64 v[222:223], s[34:35], 0, v[168:169]
	ds_read_b128 v[174:177], v190 offset:32768
	ds_read_b128 v[180:183], v190 offset:33792
	ds_read_b128 v[184:187], v190 offset:34816
	ds_read_b128 v[192:195], v190 offset:35840
	ds_read_b128 v[196:199], v190 offset:36864
	ds_read_b128 v[200:203], v190 offset:37888
	ds_read_b128 v[204:207], v190 offset:38912
	ds_read_b128 v[210:213], v190 offset:39936
	global_load_lds_dwordx4 v[222:223], off
	v_lshl_add_u64 v[222:223], s[34:35], 0, v[164:165]
	s_mov_b32 m0, s46
	s_nop 0
	global_load_lds_dwordx4 v[222:223], off
	s_waitcnt vmcnt(8)
	s_waitcnt lgkmcnt(0)
	s_barrier
	s_setprio 1
	s_waitcnt lgkmcnt(0)
	v_mfma_f32_16x16x32_bf16 v[126:129], v[130:133], v[174:177], v[126:129]
	v_mfma_f32_16x16x32_bf16 v[122:125], v[138:141], v[174:177], v[122:125]
	v_mfma_f32_16x16x32_bf16 v[110:113], v[130:133], v[184:187], v[110:113]
	v_mfma_f32_16x16x32_bf16 v[106:109], v[138:141], v[184:187], v[106:109]
	v_mfma_f32_16x16x32_bf16 v[94:97], v[130:133], v[196:199], v[94:97]
	v_mfma_f32_16x16x32_bf16 v[90:93], v[138:141], v[196:199], v[90:93]
	v_mfma_f32_16x16x32_bf16 v[78:81], v[130:133], v[204:207], v[78:81]
	v_mfma_f32_16x16x32_bf16 v[74:77], v[138:141], v[204:207], v[74:77]
	v_mfma_f32_16x16x32_bf16 v[126:129], v[134:137], v[180:183], v[126:129]
	v_mfma_f32_16x16x32_bf16 v[122:125], v[142:145], v[180:183], v[122:125]
	v_mfma_f32_16x16x32_bf16 v[110:113], v[134:137], v[192:195], v[110:113]
	v_mfma_f32_16x16x32_bf16 v[106:109], v[142:145], v[192:195], v[106:109]
	v_mfma_f32_16x16x32_bf16 v[94:97], v[134:137], v[200:203], v[94:97]
	v_mfma_f32_16x16x32_bf16 v[90:93], v[142:145], v[200:203], v[90:93]
	v_mfma_f32_16x16x32_bf16 v[78:81], v[134:137], v[210:213], v[78:81]
	v_mfma_f32_16x16x32_bf16 v[74:77], v[142:145], v[210:213], v[74:77]
	s_setprio 0
	s_setprio 1
	v_mfma_f32_16x16x32_bf16 v[118:121], v[146:149], v[174:177], v[118:121]
	v_mfma_f32_16x16x32_bf16 v[114:117], v[154:157], v[174:177], v[114:117]
	v_mfma_f32_16x16x32_bf16 v[102:105], v[146:149], v[184:187], v[102:105]
	v_mfma_f32_16x16x32_bf16 v[98:101], v[154:157], v[184:187], v[98:101]
	v_mfma_f32_16x16x32_bf16 v[86:89], v[146:149], v[196:199], v[86:89]
	v_mfma_f32_16x16x32_bf16 v[82:85], v[154:157], v[196:199], v[82:85]
	v_mfma_f32_16x16x32_bf16 v[70:73], v[146:149], v[204:207], v[70:73]
	v_mfma_f32_16x16x32_bf16 v[66:69], v[154:157], v[204:207], v[66:69]
	v_mfma_f32_16x16x32_bf16 v[118:121], v[150:153], v[180:183], v[118:121]
	v_mfma_f32_16x16x32_bf16 v[114:117], v[158:161], v[180:183], v[114:117]
	v_mfma_f32_16x16x32_bf16 v[102:105], v[150:153], v[192:195], v[102:105]
	v_mfma_f32_16x16x32_bf16 v[98:101], v[158:161], v[192:195], v[98:101]
	v_mfma_f32_16x16x32_bf16 v[86:89], v[150:153], v[200:203], v[86:89]
	v_mfma_f32_16x16x32_bf16 v[82:85], v[158:161], v[200:203], v[82:85]
	v_mfma_f32_16x16x32_bf16 v[70:73], v[150:153], v[210:213], v[70:73]
	v_mfma_f32_16x16x32_bf16 v[66:69], v[158:161], v[210:213], v[66:69]
	s_setprio 0
	s_barrier
	s_cmp_lg_u32 s98, 0
	s_cbranch_scc0 .Llp_11
	s_setprio 2
; #define PG8_STAGE(bufoff, gbase, voff) do { _Pragma("unroll") for (int _i = 0; _i < 2; ++_i) \
;         __builtin_amdgcn_global_load_lds((const unsigned*)((const char*)(gbase) + (voff)[_i]), (PG8_LAS unsigned*)(lds + (bufoff) + ldsw + _i * 8192), 16, 0, 0); } while (0)
; #define PG8_LDA(dst, b, h) do { _Pragma("unroll") for (int m = 0; m < 4; ++m) _Pragma("unroll") for (int k = 0; k < 2; ++k) dst[m][k] = *(const PG8_LAS bf16x8*)(lds + PG8_SA(b, h) + aoff + m * 2048 + k * 1024); } while (0)
; #define PG8_MMA(ai, bj, At, Bt) do { __builtin_amdgcn_s_setprio(1); _Pragma("unroll") for (int m = 0; m < 4; ++m) _Pragma("unroll") for (int n = 0; n < 2; ++n) _Pragma("unroll") for (int k = 0; k < 2; ++k) \
;         acc[ai][bj][m][n] = __builtin_amdgcn_mfma_f32_16x16x32_bf16(Bt[n][k], At[m][k], acc[ai][bj][m][n], 0, 0, 0); __builtin_amdgcn_s_setprio(0); } while (0)
; #define PG8_WAIT_V(n) asm volatile("s_waitcnt vmcnt(" #n ")" ::: "memory")
; #define PG8_WAIT_L(n) asm volatile("s_waitcnt lgkmcnt(" #n ")" ::: "memory")
; #define PG8_BAR __builtin_amdgcn_s_barrier()
; #define PG8_SCHED __builtin_amdgcn_sched_barrier(0)
;     ...
;         for (int t = 0; t < nt; t += 2) {
;     ...
;             PG8_LDA(At, 1, 1); PG8_STAGE(PG8_SB(1, 0), b3, voffB); PG8_STAGE(PG8_SB(1, 1), b3 + hstepB, voffB); PG8_STAGE(PG8_SA(1, 0), a3, voffA);
;             PG8_WAIT_V(8); PG8_WAIT_L(0); PG8_BAR; PG8_MMA(1, 0, At, B0); PG8_MMA(1, 1, At, B1); PG8_BAR; PG8_SCHED;
.Llp_11:
	s_add_i32 s34, s48, s42
	v_lshl_add_u64 v[188:189], v[188:189], 0, s[66:67]
	s_mov_b32 m0, s34
	ds_read_b128 v[174:177], v190 offset:49152
	ds_read_b128 v[180:183], v190 offset:50176
	ds_read_b128 v[184:187], v190 offset:51200
	ds_read_b128 v[192:195], v190 offset:52224
	ds_read_b128 v[196:199], v190 offset:53248
	ds_read_b128 v[200:203], v190 offset:54272
	ds_read_b128 v[204:207], v190 offset:55296
	ds_read_b128 v[210:213], v190 offset:56320
	global_load_lds_dwordx4 v[188:189], off
	s_add_i32 m0, s34, 0x2000
	s_add_u32 s28, s28, 0x18080
	v_lshl_add_u64 v[188:189], v[214:215], 0, s[66:67]
	s_addc_u32 s29, s29, 0
	s_add_i32 s34, s49, s42
	global_load_lds_dwordx4 v[188:189], off
	v_lshl_add_u64 v[188:189], s[28:29], 0, v[166:167]
	s_mov_b32 m0, s34
	s_nop 0
	global_load_lds_dwordx4 v[188:189], off
	v_lshl_add_u64 v[188:189], s[28:29], 0, v[162:163]
	s_add_i32 m0, s34, 0x2000
	s_nop 0
	global_load_lds_dwordx4 v[188:189], off
	v_lshl_add_u64 v[188:189], v[216:217], 0, s[66:67]
	s_mov_b32 m0, s55
	s_nop 0
	global_load_lds_dwordx4 v[188:189], off
	v_lshl_add_u64 v[188:189], v[218:219], 0, s[66:67]
	s_mov_b32 m0, s56
	s_nop 0
	global_load_lds_dwordx4 v[188:189], off
	s_waitcnt vmcnt(8)
	s_waitcnt lgkmcnt(0)
	s_barrier
	s_setprio 1
	s_waitcnt lgkmcnt(0)
	v_mfma_f32_16x16x32_bf16 v[62:65], v[130:133], v[174:177], v[62:65]
	v_mfma_f32_16x16x32_bf16 v[58:61], v[138:141], v[174:177], v[58:61]
	v_mfma_f32_16x16x32_bf16 v[46:49], v[130:133], v[184:187], v[46:49]
	v_mfma_f32_16x16x32_bf16 v[42:45], v[138:141], v[184:187], v[42:45]
	v_mfma_f32_16x16x32_bf16 v[30:33], v[130:133], v[196:199], v[30:33]
	v_mfma_f32_16x16x32_bf16 v[26:29], v[138:141], v[196:199], v[26:29]
	v_mfma_f32_16x16x32_bf16 v[14:17], v[130:133], v[204:207], v[14:17]
	v_mfma_f32_16x16x32_bf16 v[10:13], v[138:141], v[204:207], v[10:13]
	v_mfma_f32_16x16x32_bf16 v[62:65], v[134:137], v[180:183], v[62:65]
	v_mfma_f32_16x16x32_bf16 v[58:61], v[142:145], v[180:183], v[58:61]
	v_mfma_f32_16x16x32_bf16 v[46:49], v[134:137], v[192:195], v[46:49]
	v_mfma_f32_16x16x32_bf16 v[42:45], v[142:145], v[192:195], v[42:45]
	v_mfma_f32_16x16x32_bf16 v[30:33], v[134:137], v[200:203], v[30:33]
	v_mfma_f32_16x16x32_bf16 v[26:29], v[142:145], v[200:203], v[26:29]
	v_mfma_f32_16x16x32_bf16 v[14:17], v[134:137], v[210:213], v[14:17]
	v_mfma_f32_16x16x32_bf16 v[10:13], v[142:145], v[210:213], v[10:13]
	s_setprio 0
	s_setprio 1
	v_mfma_f32_16x16x32_bf16 v[54:57], v[146:149], v[174:177], v[54:57]
	v_mfma_f32_16x16x32_bf16 v[50:53], v[154:157], v[174:177], v[50:53]
	v_mfma_f32_16x16x32_bf16 v[38:41], v[146:149], v[184:187], v[38:41]
	v_mfma_f32_16x16x32_bf16 v[34:37], v[154:157], v[184:187], v[34:37]
	v_mfma_f32_16x16x32_bf16 v[22:25], v[146:149], v[196:199], v[22:25]
	v_mfma_f32_16x16x32_bf16 v[18:21], v[154:157], v[196:199], v[18:21]
	v_mfma_f32_16x16x32_bf16 v[6:9], v[146:149], v[204:207], v[6:9]
	v_mfma_f32_16x16x32_bf16 v[2:5], v[154:157], v[204:207], v[2:5]
	v_mfma_f32_16x16x32_bf16 v[54:57], v[150:153], v[180:183], v[54:57]
	v_mfma_f32_16x16x32_bf16 v[50:53], v[158:161], v[180:183], v[50:53]
	v_mfma_f32_16x16x32_bf16 v[38:41], v[150:153], v[192:195], v[38:41]
	v_mfma_f32_16x16x32_bf16 v[34:37], v[158:161], v[192:195], v[34:37]
	v_mfma_f32_16x16x32_bf16 v[22:25], v[150:153], v[200:203], v[22:25]
	v_mfma_f32_16x16x32_bf16 v[18:21], v[158:161], v[200:203], v[18:21]
	v_mfma_f32_16x16x32_bf16 v[6:9], v[150:153], v[210:213], v[6:9]
	v_mfma_f32_16x16x32_bf16 v[2:5], v[158:161], v[210:213], v[2:5]
	s_setprio 0
	s_barrier
	s_cmp_lg_u32 s98, 0
	s_cbranch_scc0 .Llp_12
	s_setprio 2
.Llp_12:
	s_add_i32 s86, s86, 2
	s_add_u32 s8, s8, 0x100
	s_addc_u32 s9, s9, 0
	s_add_u32 s69, s69, 0x100
	s_addc_u32 s85, s85, 0
	s_cmp_gt_u32 s86, 3
	s_cbranch_scc0 .LBB0_632
	s_and_b64 vcc, exec, s[20:21]
	s_cbranch_vccz .LBB0_635
	s_barrier

; #define PG8_STAGE(bufoff, gbase, voff) do { _Pragma("unroll") for (int _i = 0; _i < 2; ++_i) \
;         __builtin_amdgcn_global_load_lds((const unsigned*)((const char*)(gbase) + (voff)[_i]), (PG8_LAS unsigned*)(lds + (bufoff) + ldsw + _i * 8192), 16, 0, 0); } while (0)
; #define PG8_LDA(dst, b, h) do { _Pragma("unroll") for (int m = 0; m < 4; ++m) _Pragma("unroll") for (int k = 0; k < 2; ++k) dst[m][k] = *(const PG8_LAS bf16x8*)(lds + PG8_SA(b, h) + aoff + m * 2048 + k * 1024); } while (0)
; #define PG8_LDB(dst, b, h) do { _Pragma("unroll") for (int n = 0; n < 2; ++n) _Pragma("unroll") for (int k = 0; k < 2; ++k) dst[n][k] = *(const PG8_LAS bf16x8*)(lds + PG8_SB(b, h) + boff + n * 2048 + k * 1024); } while (0)
; #define PG8_MMA(ai, bj, At, Bt) do { __builtin_amdgcn_s_setprio(1); _Pragma("unroll") for (int m = 0; m < 4; ++m) _Pragma("unroll") for (int n = 0; n < 2; ++n) _Pragma("unroll") for (int k = 0; k < 2; ++k) \
;         acc[ai][bj][m][n] = __builtin_amdgcn_mfma_f32_16x16x32_bf16(Bt[n][k], At[m][k], acc[ai][bj][m][n], 0, 0, 0); __builtin_amdgcn_s_setprio(0); } while (0)
; #define PG8_WAIT_V(n) asm volatile("s_waitcnt vmcnt(" #n ")" ::: "memory")
; #define PG8_WAIT_L(n) asm volatile("s_waitcnt lgkmcnt(" #n ")" ::: "memory")
; #define PG8_BAR __builtin_amdgcn_s_barrier()
; #define PG8_SCHED __builtin_amdgcn_sched_barrier(0)
;     ...
;             const bool last = (t == nt - 2);
;             const char* a1 = cA + (size_t)(t + 1) * kstep;
;             const char* a2 = last ? nA : cA + (size_t)(t + 2) * kstep; const char* b2 = last ? nB : cB + (size_t)(t + 2) * kstep;
;             const char* a3 = a2 + kstep; const char* b3 = b2 + kstep;
;             if (last && has_next) S.a_ready(nxt);
;             if constexpr (SP2) {
;             PG8_LDB(B0, 0, 0); PG8_LDB(B1, 0, 1); PG8_SCHED; PG8_LDA(At, 0, 0); PG8_STAGE(PG8_SA(1, 1), a1 + hstepA, voffA);
;             PG8_WAIT_V(8); PG8_WAIT_L(0); PG8_BAR; PG8_MMA(0, 0, At, B0); PG8_MMA(0, 1, At, B1); PG8_BAR; PG8_SCHED;
.LBB0_720:
	s_add_u32 s42, s26, s36
	s_addc_u32 s43, s27, s37
	s_add_u32 s40, s42, 0x100
	s_addc_u32 s41, s43, 0
	s_and_b64 s[38:39], s[34:35], exec
	s_cselect_b32 s39, s19, s41
	s_cselect_b32 s38, s85, s40
	s_add_u32 s36, s24, s36
	s_addc_u32 s37, s25, s37
	s_add_u32 s36, s36, 0x100
	s_addc_u32 s37, s37, 0
	s_add_i32 s48, 0, 0x10000
	s_and_b64 s[34:35], s[34:35], exec
	s_cselect_b32 s41, s17, s37
	s_cselect_b32 s40, s91, s36
	s_add_i32 s35, 0, 0x14000
	s_add_u32 s44, s42, 0x10080
	s_addc_u32 s45, s43, 0
	s_add_i32 vcc_hi, s48, s54
	s_add_i32 m0, s55, 0xc000
	s_add_i32 s49, s55, 0xe000
	s_add_i32 s96, vcc_hi, 0x2000
	s_add_u32 s42, s40, 0x10000
	v_add_u32_e32 v150, s48, v1
	v_add_u32_e32 v158, s35, v1
	s_addc_u32 s43, s41, 0
	s_add_i32 vcc_lo, s35, s54
	ds_read_b128 v[130:133], v150
	ds_read_b128 v[134:137], v150 offset:1024
	ds_read_b128 v[146:149], v150 offset:2048
	ds_read_b128 v[150:153], v150 offset:3072
	ds_read_b128 v[154:157], v158
	ds_read_b128 v[160:163], v158 offset:1024
	ds_read_b128 v[164:167], v158 offset:2048
	ds_read_b128 v[168:171], v158 offset:3072
	s_add_i32 s97, vcc_lo, 0x2000
	s_add_i32 s95, 0, 0x18000
	s_add_i32 s94, 0, 0x1c000
	s_add_u32 s36, s38, 0x10000
	s_addc_u32 s37, s39, 0
	s_add_i32 s93, s95, s54
	s_add_i32 s92, s93, 0x2000
	s_add_u32 s34, s40, 0x10080
	s_addc_u32 s35, s41, 0
	s_add_i32 s61, s94, s54
	s_add_i32 s48, s61, 0x2000
	v_lshl_add_u64 v[176:177], s[44:45], 0, v[144:145]
	ds_read_b128 v[172:175], v159
	ds_read_b128 v[180:183], v159 offset:1024
	ds_read_b128 v[184:187], v159 offset:2048
	ds_read_b128 v[188:191], v159 offset:3072
	ds_read_b128 v[192:195], v159 offset:4096
	ds_read_b128 v[196:199], v159 offset:5120
	ds_read_b128 v[200:203], v159 offset:6144
	ds_read_b128 v[204:207], v159 offset:7168
	global_load_lds_dwordx4 v[176:177], off
	v_lshl_add_u64 v[176:177], s[44:45], 0, v[140:141]
	s_mov_b32 m0, s49
	s_nop 0
	global_load_lds_dwordx4 v[176:177], off
	s_waitcnt vmcnt(8)
	s_waitcnt lgkmcnt(0)
	s_barrier
	s_setprio 1
	s_waitcnt lgkmcnt(0)
	v_mfma_f32_16x16x32_bf16 v[126:129], v[130:133], v[172:175], v[126:129]
	v_mfma_f32_16x16x32_bf16 v[122:125], v[146:149], v[172:175], v[122:125]
	v_mfma_f32_16x16x32_bf16 v[110:113], v[130:133], v[184:187], v[110:113]
	v_mfma_f32_16x16x32_bf16 v[106:109], v[146:149], v[184:187], v[106:109]
	v_mfma_f32_16x16x32_bf16 v[94:97], v[130:133], v[192:195], v[94:97]
	v_mfma_f32_16x16x32_bf16 v[90:93], v[146:149], v[192:195], v[90:93]
	v_mfma_f32_16x16x32_bf16 v[78:81], v[130:133], v[200:203], v[78:81]
	v_mfma_f32_16x16x32_bf16 v[74:77], v[146:149], v[200:203], v[74:77]
	v_mfma_f32_16x16x32_bf16 v[126:129], v[134:137], v[180:183], v[126:129]
	v_mfma_f32_16x16x32_bf16 v[122:125], v[150:153], v[180:183], v[122:125]
	v_mfma_f32_16x16x32_bf16 v[110:113], v[134:137], v[188:191], v[110:113]
	v_mfma_f32_16x16x32_bf16 v[106:109], v[150:153], v[188:191], v[106:109]
	v_mfma_f32_16x16x32_bf16 v[94:97], v[134:137], v[196:199], v[94:97]
	v_mfma_f32_16x16x32_bf16 v[90:93], v[150:153], v[196:199], v[90:93]
	v_mfma_f32_16x16x32_bf16 v[78:81], v[134:137], v[204:207], v[78:81]
	v_mfma_f32_16x16x32_bf16 v[74:77], v[150:153], v[204:207], v[74:77]
	s_setprio 0
	s_setprio 1
	v_mfma_f32_16x16x32_bf16 v[118:121], v[154:157], v[172:175], v[118:121]
	v_mfma_f32_16x16x32_bf16 v[114:117], v[164:167], v[172:175], v[114:117]
	v_mfma_f32_16x16x32_bf16 v[102:105], v[154:157], v[184:187], v[102:105]
	v_mfma_f32_16x16x32_bf16 v[98:101], v[164:167], v[184:187], v[98:101]
	v_mfma_f32_16x16x32_bf16 v[86:89], v[154:157], v[192:195], v[86:89]
	v_mfma_f32_16x16x32_bf16 v[82:85], v[164:167], v[192:195], v[82:85]
	v_mfma_f32_16x16x32_bf16 v[70:73], v[154:157], v[200:203], v[70:73]
	v_mfma_f32_16x16x32_bf16 v[66:69], v[164:167], v[200:203], v[66:69]
	v_mfma_f32_16x16x32_bf16 v[118:121], v[160:163], v[180:183], v[118:121]
	v_mfma_f32_16x16x32_bf16 v[114:117], v[168:171], v[180:183], v[114:117]
	v_mfma_f32_16x16x32_bf16 v[102:105], v[160:163], v[188:191], v[102:105]
	v_mfma_f32_16x16x32_bf16 v[98:101], v[168:171], v[188:191], v[98:101]
	v_mfma_f32_16x16x32_bf16 v[86:89], v[160:163], v[196:199], v[86:89]
	v_mfma_f32_16x16x32_bf16 v[82:85], v[168:171], v[196:199], v[82:85]
	v_mfma_f32_16x16x32_bf16 v[70:73], v[160:163], v[204:207], v[70:73]
	v_mfma_f32_16x16x32_bf16 v[66:69], v[168:171], v[204:207], v[66:69]
	s_setprio 0
	s_barrier
	s_cmp_lg_u32 s98, 0
	s_cbranch_scc0 .Llp_13
	s_setprio 2
; #define PG8_STAGE(bufoff, gbase, voff) do { _Pragma("unroll") for (int _i = 0; _i < 2; ++_i) \
;         __builtin_amdgcn_global_load_lds((const unsigned*)((const char*)(gbase) + (voff)[_i]), (PG8_LAS unsigned*)(lds + (bufoff) + ldsw + _i * 8192), 16, 0, 0); } while (0)
; #define PG8_LDA(dst, b, h) do { _Pragma("unroll") for (int m = 0; m < 4; ++m) _Pragma("unroll") for (int k = 0; k < 2; ++k) dst[m][k] = *(const PG8_LAS bf16x8*)(lds + PG8_SA(b, h) + aoff + m * 2048 + k * 1024); } while (0)
; #define PG8_LDB(dst, b, h) do { _Pragma("unroll") for (int n = 0; n < 2; ++n) _Pragma("unroll") for (int k = 0; k < 2; ++k) dst[n][k] = *(const PG8_LAS bf16x8*)(lds + PG8_SB(b, h) + boff + n * 2048 + k * 1024); } while (0)
; #define PG8_MMA(ai, bj, At, Bt) do { __builtin_amdgcn_s_setprio(1); _Pragma("unroll") for (int m = 0; m < 4; ++m) _Pragma("unroll") for (int n = 0; n < 2; ++n) _Pragma("unroll") for (int k = 0; k < 2; ++k) \
;         acc[ai][bj][m][n] = __builtin_amdgcn_mfma_f32_16x16x32_bf16(Bt[n][k], At[m][k], acc[ai][bj][m][n], 0, 0, 0); __builtin_amdgcn_s_setprio(0); } while (0)
; #define PG8_WAIT_V(n) asm volatile("s_waitcnt vmcnt(" #n ")" ::: "memory")
; #define PG8_WAIT_L(n) asm volatile("s_waitcnt lgkmcnt(" #n ")" ::: "memory")
; #define PG8_BAR __builtin_amdgcn_s_barrier()
; #define PG8_SCHED __builtin_amdgcn_sched_barrier(0)
;     ...
;             PG8_LDA(At, 0, 1); PG8_STAGE(PG8_SB(0, 0), b2, voffB); PG8_STAGE(PG8_SB(0, 1), b2 + hstepB, voffB); PG8_STAGE(PG8_SA(0, 0), a2, voffA);
;             PG8_WAIT_V(8); PG8_WAIT_L(0); PG8_BAR; PG8_MMA(1, 0, At, B0); PG8_MMA(1, 1, At, B1); PG8_BAR; PG8_SCHED;
;             PG8_LDB(B0, 1, 0); PG8_LDB(B1, 1, 1); PG8_SCHED; PG8_LDA(At, 1, 0); PG8_STAGE(PG8_SA(0, 1), a2 + hstepA, voffA);
;             PG8_WAIT_V(8); PG8_WAIT_L(0); PG8_BAR; PG8_MMA(0, 0, At, B0); PG8_MMA(0, 1, At, B1); PG8_BAR; PG8_SCHED;
.Llp_13:
	s_mov_b32 m0, vcc_hi
	v_lshl_add_u64 v[176:177], s[40:41], 0, v[142:143]
	ds_read_b128 v[172:175], v159 offset:16384
	ds_read_b128 v[180:183], v159 offset:17408
	ds_read_b128 v[184:187], v159 offset:18432
	ds_read_b128 v[188:191], v159 offset:19456
	ds_read_b128 v[192:195], v159 offset:20480
	ds_read_b128 v[196:199], v159 offset:21504
	ds_read_b128 v[200:203], v159 offset:22528
	ds_read_b128 v[204:207], v159 offset:23552
	global_load_lds_dwordx4 v[176:177], off
	v_lshl_add_u64 v[210:211], s[40:41], 0, v[138:139]
	s_mov_b32 m0, s96
	v_lshl_add_u64 v[212:213], s[42:43], 0, v[142:143]
	global_load_lds_dwordx4 v[210:211], off
	s_mov_b32 m0, vcc_lo
	v_lshl_add_u64 v[214:215], s[38:39], 0, v[140:141]
	global_load_lds_dwordx4 v[212:213], off
	v_lshl_add_u64 v[212:213], s[42:43], 0, v[138:139]
	s_mov_b32 m0, s97
	s_nop 0
	global_load_lds_dwordx4 v[212:213], off
	v_lshl_add_u64 v[212:213], s[38:39], 0, v[144:145]
	s_mov_b32 m0, s55
	s_nop 0
	global_load_lds_dwordx4 v[212:213], off
	s_mov_b32 m0, s56
	s_nop 0
	global_load_lds_dwordx4 v[214:215], off
	s_waitcnt vmcnt(8)
	s_waitcnt lgkmcnt(0)
	s_barrier
	s_setprio 1
	s_waitcnt lgkmcnt(0)
	v_mfma_f32_16x16x32_bf16 v[62:65], v[130:133], v[172:175], v[62:65]
	v_mfma_f32_16x16x32_bf16 v[58:61], v[146:149], v[172:175], v[58:61]
	v_mfma_f32_16x16x32_bf16 v[46:49], v[130:133], v[184:187], v[46:49]
	v_mfma_f32_16x16x32_bf16 v[42:45], v[146:149], v[184:187], v[42:45]
	v_mfma_f32_16x16x32_bf16 v[30:33], v[130:133], v[192:195], v[30:33]
	v_mfma_f32_16x16x32_bf16 v[26:29], v[146:149], v[192:195], v[26:29]
	v_mfma_f32_16x16x32_bf16 v[14:17], v[130:133], v[200:203], v[14:17]
	v_mfma_f32_16x16x32_bf16 v[10:13], v[146:149], v[200:203], v[10:13]
	v_mfma_f32_16x16x32_bf16 v[62:65], v[134:137], v[180:183], v[62:65]
	v_mfma_f32_16x16x32_bf16 v[58:61], v[150:153], v[180:183], v[58:61]
	v_mfma_f32_16x16x32_bf16 v[46:49], v[134:137], v[188:191], v[46:49]
	v_mfma_f32_16x16x32_bf16 v[42:45], v[150:153], v[188:191], v[42:45]
	v_mfma_f32_16x16x32_bf16 v[30:33], v[134:137], v[196:199], v[30:33]
	v_mfma_f32_16x16x32_bf16 v[26:29], v[150:153], v[196:199], v[26:29]
	v_mfma_f32_16x16x32_bf16 v[14:17], v[134:137], v[204:207], v[14:17]
	v_mfma_f32_16x16x32_bf16 v[10:13], v[150:153], v[204:207], v[10:13]
	s_setprio 0
	s_setprio 1
	v_mfma_f32_16x16x32_bf16 v[54:57], v[154:157], v[172:175], v[54:57]
	v_mfma_f32_16x16x32_bf16 v[50:53], v[164:167], v[172:175], v[50:53]
	v_mfma_f32_16x16x32_bf16 v[38:41], v[154:157], v[184:187], v[38:41]
	v_mfma_f32_16x16x32_bf16 v[34:37], v[164:167], v[184:187], v[34:37]
	v_mfma_f32_16x16x32_bf16 v[22:25], v[154:157], v[192:195], v[22:25]
	v_mfma_f32_16x16x32_bf16 v[18:21], v[164:167], v[192:195], v[18:21]
	v_mfma_f32_16x16x32_bf16 v[6:9], v[154:157], v[200:203], v[6:9]
	v_mfma_f32_16x16x32_bf16 v[2:5], v[164:167], v[200:203], v[2:5]
	v_mfma_f32_16x16x32_bf16 v[54:57], v[160:163], v[180:183], v[54:57]
	v_mfma_f32_16x16x32_bf16 v[50:53], v[168:171], v[180:183], v[50:53]
	v_mfma_f32_16x16x32_bf16 v[38:41], v[160:163], v[188:191], v[38:41]
	v_mfma_f32_16x16x32_bf16 v[34:37], v[168:171], v[188:191], v[34:37]
	v_mfma_f32_16x16x32_bf16 v[22:25], v[160:163], v[196:199], v[22:25]
	v_mfma_f32_16x16x32_bf16 v[18:21], v[168:171], v[196:199], v[18:21]
	v_mfma_f32_16x16x32_bf16 v[6:9], v[160:163], v[204:207], v[6:9]
	v_mfma_f32_16x16x32_bf16 v[2:5], v[168:171], v[204:207], v[2:5]
	s_setprio 0
	s_barrier
	s_cmp_lg_u32 s98, 0
	s_cbranch_scc0 .Llp_14
	s_setprio 2
.Llp_14:
	v_add_u32_e32 v150, s95, v1
	v_add_u32_e32 v158, s94, v1
	ds_read_b128 v[130:133], v150
	ds_read_b128 v[134:137], v150 offset:1024
	ds_read_b128 v[146:149], v150 offset:2048
	ds_read_b128 v[150:153], v150 offset:3072
	ds_read_b128 v[154:157], v158
	ds_read_b128 v[160:163], v158 offset:1024
	ds_read_b128 v[164:167], v158 offset:2048
	ds_read_b128 v[168:171], v158 offset:3072
	s_mov_b32 m0, s57
	v_lshl_add_u64 v[216:217], s[36:37], 0, v[144:145]
	ds_read_b128 v[172:175], v159 offset:32768
	ds_read_b128 v[180:183], v159 offset:33792
	ds_read_b128 v[184:187], v159 offset:34816
	ds_read_b128 v[188:191], v159 offset:35840
	ds_read_b128 v[192:195], v159 offset:36864
	ds_read_b128 v[196:199], v159 offset:37888
	ds_read_b128 v[200:203], v159 offset:38912
	ds_read_b128 v[204:207], v159 offset:39936
	global_load_lds_dwordx4 v[216:217], off
	v_lshl_add_u64 v[216:217], s[36:37], 0, v[140:141]
	s_mov_b32 m0, s58
	s_nop 0
	global_load_lds_dwordx4 v[216:217], off
	s_waitcnt vmcnt(8)
	s_waitcnt lgkmcnt(0)
	s_barrier
	s_setprio 1
	s_waitcnt lgkmcnt(0)
	v_mfma_f32_16x16x32_bf16 v[126:129], v[130:133], v[172:175], v[126:129]
	v_mfma_f32_16x16x32_bf16 v[122:125], v[146:149], v[172:175], v[122:125]
	v_mfma_f32_16x16x32_bf16 v[110:113], v[130:133], v[184:187], v[110:113]
	v_mfma_f32_16x16x32_bf16 v[106:109], v[146:149], v[184:187], v[106:109]
	v_mfma_f32_16x16x32_bf16 v[94:97], v[130:133], v[192:195], v[94:97]
	v_mfma_f32_16x16x32_bf16 v[90:93], v[146:149], v[192:195], v[90:93]
	v_mfma_f32_16x16x32_bf16 v[78:81], v[130:133], v[200:203], v[78:81]
	v_mfma_f32_16x16x32_bf16 v[74:77], v[146:149], v[200:203], v[74:77]
	v_mfma_f32_16x16x32_bf16 v[126:129], v[134:137], v[180:183], v[126:129]
	v_mfma_f32_16x16x32_bf16 v[122:125], v[150:153], v[180:183], v[122:125]
	v_mfma_f32_16x16x32_bf16 v[110:113], v[134:137], v[188:191], v[110:113]
	v_mfma_f32_16x16x32_bf16 v[106:109], v[150:153], v[188:191], v[106:109]
	v_mfma_f32_16x16x32_bf16 v[94:97], v[134:137], v[196:199], v[94:97]
	v_mfma_f32_16x16x32_bf16 v[90:93], v[150:153], v[196:199], v[90:93]
	v_mfma_f32_16x16x32_bf16 v[78:81], v[134:137], v[204:207], v[78:81]
	v_mfma_f32_16x16x32_bf16 v[74:77], v[150:153], v[204:207], v[74:77]
	s_setprio 0
	s_setprio 1
	v_mfma_f32_16x16x32_bf16 v[118:121], v[154:157], v[172:175], v[118:121]
	v_mfma_f32_16x16x32_bf16 v[114:117], v[164:167], v[172:175], v[114:117]
	v_mfma_f32_16x16x32_bf16 v[102:105], v[154:157], v[184:187], v[102:105]
	v_mfma_f32_16x16x32_bf16 v[98:101], v[164:167], v[184:187], v[98:101]
	v_mfma_f32_16x16x32_bf16 v[86:89], v[154:157], v[192:195], v[86:89]
	v_mfma_f32_16x16x32_bf16 v[82:85], v[164:167], v[192:195], v[82:85]
	v_mfma_f32_16x16x32_bf16 v[70:73], v[154:157], v[200:203], v[70:73]
	v_mfma_f32_16x16x32_bf16 v[66:69], v[164:167], v[200:203], v[66:69]
	v_mfma_f32_16x16x32_bf16 v[118:121], v[160:163], v[180:183], v[118:121]
	v_mfma_f32_16x16x32_bf16 v[114:117], v[168:171], v[180:183], v[114:117]
	v_mfma_f32_16x16x32_bf16 v[102:105], v[160:163], v[188:191], v[102:105]
	v_mfma_f32_16x16x32_bf16 v[98:101], v[168:171], v[188:191], v[98:101]
	v_mfma_f32_16x16x32_bf16 v[86:89], v[160:163], v[196:199], v[86:89]
	v_mfma_f32_16x16x32_bf16 v[82:85], v[168:171], v[196:199], v[82:85]
	v_mfma_f32_16x16x32_bf16 v[70:73], v[160:163], v[204:207], v[70:73]
	v_mfma_f32_16x16x32_bf16 v[66:69], v[168:171], v[204:207], v[66:69]
	s_setprio 0
	s_barrier
	s_cmp_lg_u32 s98, 0
	s_cbranch_scc0 .Llp_15
	s_setprio 2
; #define PG8_STAGE(bufoff, gbase, voff) do { _Pragma("unroll") for (int _i = 0; _i < 2; ++_i) \
;         __builtin_amdgcn_global_load_lds((const unsigned*)((const char*)(gbase) + (voff)[_i]), (PG8_LAS unsigned*)(lds + (bufoff) + ldsw + _i * 8192), 16, 0, 0); } while (0)
; #define PG8_LDA(dst, b, h) do { _Pragma("unroll") for (int m = 0; m < 4; ++m) _Pragma("unroll") for (int k = 0; k < 2; ++k) dst[m][k] = *(const PG8_LAS bf16x8*)(lds + PG8_SA(b, h) + aoff + m * 2048 + k * 1024); } while (0)
; #define PG8_MMA(ai, bj, At, Bt) do { __builtin_amdgcn_s_setprio(1); _Pragma("unroll") for (int m = 0; m < 4; ++m) _Pragma("unroll") for (int n = 0; n < 2; ++n) _Pragma("unroll") for (int k = 0; k < 2; ++k) \
;         acc[ai][bj][m][n] = __builtin_amdgcn_mfma_f32_16x16x32_bf16(Bt[n][k], At[m][k], acc[ai][bj][m][n], 0, 0, 0); __builtin_amdgcn_s_setprio(0); } while (0)
; #define PG8_WAIT_V(n) asm volatile("s_waitcnt vmcnt(" #n ")" ::: "memory")
; #define PG8_WAIT_L(n) asm volatile("s_waitcnt lgkmcnt(" #n ")" ::: "memory")
; #define PG8_BAR __builtin_amdgcn_s_barrier()
; #define PG8_SCHED __builtin_amdgcn_sched_barrier(0)
;     ...
;         for (int t = 0; t < nt; t += 2) {
;     ...
;             PG8_LDA(At, 1, 1); PG8_STAGE(PG8_SB(1, 0), b3, voffB); PG8_STAGE(PG8_SB(1, 1), b3 + hstepB, voffB); PG8_STAGE(PG8_SA(1, 0), a3, voffA);
;             PG8_WAIT_V(8); PG8_WAIT_L(0); PG8_BAR; PG8_MMA(1, 0, At, B0); PG8_MMA(1, 1, At, B1); PG8_BAR; PG8_SCHED;
.Llp_15:
	s_mov_b32 m0, s93
	v_lshl_add_u64 v[176:177], v[176:177], 0, s[66:67]
	ds_read_b128 v[172:175], v159 offset:49152
	ds_read_b128 v[180:183], v159 offset:50176
	ds_read_b128 v[184:187], v159 offset:51200
	ds_read_b128 v[188:191], v159 offset:52224
	ds_read_b128 v[192:195], v159 offset:53248
	ds_read_b128 v[196:199], v159 offset:54272
	ds_read_b128 v[200:203], v159 offset:55296
	ds_read_b128 v[204:207], v159 offset:56320
	global_load_lds_dwordx4 v[176:177], off
	v_lshl_add_u64 v[176:177], v[210:211], 0, s[66:67]
	s_mov_b32 m0, s92
	s_nop 0
	global_load_lds_dwordx4 v[176:177], off
	v_lshl_add_u64 v[176:177], s[34:35], 0, v[142:143]
	s_mov_b32 m0, s61
	s_nop 0
	global_load_lds_dwordx4 v[176:177], off
	v_lshl_add_u64 v[176:177], s[34:35], 0, v[138:139]
	s_mov_b32 m0, s48
	s_nop 0
	global_load_lds_dwordx4 v[176:177], off
	v_lshl_add_u64 v[176:177], v[212:213], 0, s[66:67]
	s_mov_b32 m0, s87
	s_nop 0
	global_load_lds_dwordx4 v[176:177], off
	v_lshl_add_u64 v[176:177], v[214:215], 0, s[66:67]
	s_mov_b32 m0, s88
	s_nop 0
	global_load_lds_dwordx4 v[176:177], off
	s_waitcnt vmcnt(8)
	s_waitcnt lgkmcnt(0)
	s_barrier
	s_setprio 1
	s_waitcnt lgkmcnt(0)
	v_mfma_f32_16x16x32_bf16 v[62:65], v[130:133], v[172:175], v[62:65]
	v_mfma_f32_16x16x32_bf16 v[58:61], v[146:149], v[172:175], v[58:61]
	v_mfma_f32_16x16x32_bf16 v[46:49], v[130:133], v[184:187], v[46:49]
	v_mfma_f32_16x16x32_bf16 v[42:45], v[146:149], v[184:187], v[42:45]
	v_mfma_f32_16x16x32_bf16 v[30:33], v[130:133], v[192:195], v[30:33]
	v_mfma_f32_16x16x32_bf16 v[26:29], v[146:149], v[192:195], v[26:29]
	v_mfma_f32_16x16x32_bf16 v[14:17], v[130:133], v[200:203], v[14:17]
	v_mfma_f32_16x16x32_bf16 v[10:13], v[146:149], v[200:203], v[10:13]
	v_mfma_f32_16x16x32_bf16 v[62:65], v[134:137], v[180:183], v[62:65]
	v_mfma_f32_16x16x32_bf16 v[58:61], v[150:153], v[180:183], v[58:61]
	v_mfma_f32_16x16x32_bf16 v[46:49], v[134:137], v[188:191], v[46:49]
	v_mfma_f32_16x16x32_bf16 v[42:45], v[150:153], v[188:191], v[42:45]
	v_mfma_f32_16x16x32_bf16 v[30:33], v[134:137], v[196:199], v[30:33]
	v_mfma_f32_16x16x32_bf16 v[26:29], v[150:153], v[196:199], v[26:29]
	v_mfma_f32_16x16x32_bf16 v[14:17], v[134:137], v[204:207], v[14:17]
	v_mfma_f32_16x16x32_bf16 v[10:13], v[150:153], v[204:207], v[10:13]
	s_setprio 0
	s_setprio 1
	v_mfma_f32_16x16x32_bf16 v[54:57], v[154:157], v[172:175], v[54:57]
	v_mfma_f32_16x16x32_bf16 v[50:53], v[164:167], v[172:175], v[50:53]
	v_mfma_f32_16x16x32_bf16 v[38:41], v[154:157], v[184:187], v[38:41]
	v_mfma_f32_16x16x32_bf16 v[34:37], v[164:167], v[184:187], v[34:37]
	v_mfma_f32_16x16x32_bf16 v[22:25], v[154:157], v[192:195], v[22:25]
	v_mfma_f32_16x16x32_bf16 v[18:21], v[164:167], v[192:195], v[18:21]
	v_mfma_f32_16x16x32_bf16 v[6:9], v[154:157], v[200:203], v[6:9]
	v_mfma_f32_16x16x32_bf16 v[2:5], v[164:167], v[200:203], v[2:5]
	v_mfma_f32_16x16x32_bf16 v[54:57], v[160:163], v[180:183], v[54:57]
	v_mfma_f32_16x16x32_bf16 v[50:53], v[168:171], v[180:183], v[50:53]
	v_mfma_f32_16x16x32_bf16 v[38:41], v[160:163], v[188:191], v[38:41]
	v_mfma_f32_16x16x32_bf16 v[34:37], v[168:171], v[188:191], v[34:37]
	v_mfma_f32_16x16x32_bf16 v[22:25], v[160:163], v[196:199], v[22:25]
	v_mfma_f32_16x16x32_bf16 v[18:21], v[168:171], v[196:199], v[18:21]
	v_mfma_f32_16x16x32_bf16 v[6:9], v[160:163], v[204:207], v[6:9]
	v_mfma_f32_16x16x32_bf16 v[2:5], v[168:171], v[204:207], v[2:5]
	s_setprio 0
	s_barrier
	s_cmp_lg_u32 s98, 0
	s_cbranch_scc0 .Llp_16
	s_setprio 2
.Llp_16:
	s_andn2_b64 vcc, exec, s[28:29]
	s_mov_b64 s[34:35], -1
	s_mov_b64 s[28:29], 0
	s_mov_b64 s[36:37], 0x100
	s_cbranch_vccz .LBB0_720
	s_and_b64 vcc, exec, s[14:15]
	s_cbranch_vccz .LBB0_723
	s_barrier

; #define PG8_STAGE(bufoff, gbase, voff) do { _Pragma("unroll") for (int _i = 0; _i < 2; ++_i) \
;         __builtin_amdgcn_global_load_lds((const unsigned*)((const char*)(gbase) + (voff)[_i]), (PG8_LAS unsigned*)(lds + (bufoff) + ldsw + _i * 8192), 16, 0, 0); } while (0)
; #define PG8_LDA(dst, b, h) do { _Pragma("unroll") for (int m = 0; m < 4; ++m) _Pragma("unroll") for (int k = 0; k < 2; ++k) dst[m][k] = *(const PG8_LAS bf16x8*)(lds + PG8_SA(b, h) + aoff + m * 2048 + k * 1024); } while (0)
; #define PG8_LDB(dst, b, h) do { _Pragma("unroll") for (int n = 0; n < 2; ++n) _Pragma("unroll") for (int k = 0; k < 2; ++k) dst[n][k] = *(const PG8_LAS bf16x8*)(lds + PG8_SB(b, h) + boff + n * 2048 + k * 1024); } while (0)
; #define PG8_MMA(ai, bj, At, Bt) do { __builtin_amdgcn_s_setprio(1); _Pragma("unroll") for (int m = 0; m < 4; ++m) _Pragma("unroll") for (int n = 0; n < 2; ++n) _Pragma("unroll") for (int k = 0; k < 2; ++k) \
;         acc[ai][bj][m][n] = __builtin_amdgcn_mfma_f32_16x16x32_bf16(Bt[n][k], At[m][k], acc[ai][bj][m][n], 0, 0, 0); __builtin_amdgcn_s_setprio(0); } while (0)
; #define PG8_WAIT_V(n) asm volatile("s_waitcnt vmcnt(" #n ")" ::: "memory")
; #define PG8_WAIT_L(n) asm volatile("s_waitcnt lgkmcnt(" #n ")" ::: "memory")
; #define PG8_BAR __builtin_amdgcn_s_barrier()
; #define PG8_SCHED __builtin_amdgcn_sched_barrier(0)
;     ...
;             const bool last = (t == nt - 2);
;             const char* a1 = cA + (size_t)(t + 1) * kstep;
;             const char* a2 = last ? nA : cA + (size_t)(t + 2) * kstep; const char* b2 = last ? nB : cB + (size_t)(t + 2) * kstep;
;             const char* a3 = a2 + kstep; const char* b3 = b2 + kstep;
;             if (last && has_next) S.a_ready(nxt);
;             if constexpr (SP2) {
;             PG8_LDB(B0, 0, 0); PG8_LDB(B1, 0, 1); PG8_SCHED; PG8_LDA(At, 0, 0); PG8_STAGE(PG8_SA(1, 1), a1 + hstepA, voffA);
;             PG8_WAIT_V(8); PG8_WAIT_L(0); PG8_BAR; PG8_MMA(0, 0, At, B0); PG8_MMA(0, 1, At, B1); PG8_BAR; PG8_SCHED;
;             PG8_LDA(At, 0, 1); PG8_STAGE(PG8_SB(0, 0), b2, voffB); PG8_STAGE(PG8_SB(0, 1), b2 + hstepB, voffB); PG8_STAGE(PG8_SA(0, 0), a2, voffA);
.LBB0_963:
	s_add_u32 s28, s6, 0xfffe0080
	s_addc_u32 s29, s7, -1
	s_add_i32 s48, 0, 0x10000
	s_cmp_eq_u32 s81, 4
	s_cselect_b32 s35, s57, s29
	s_cselect_b32 s34, s77, s28
	s_cselect_b32 s29, s55, s80
	s_cselect_b32 s28, s78, s79
	s_add_i32 s82, 0, 0x14000
	v_add_u32_e32 v92, s48, v234
	v_add_u32_e32 v132, s82, v234
	ds_read_b128 v[64:67], v92
	ds_read_b128 v[68:71], v92 offset:1024
	ds_read_b128 v[80:83], v92 offset:2048
	ds_read_b128 v[92:95], v92 offset:3072
	ds_read_b128 v[104:107], v132
	ds_read_b128 v[108:111], v132 offset:1024
	ds_read_b128 v[120:123], v132 offset:2048
	ds_read_b128 v[132:135], v132 offset:3072
	v_lshl_add_u64 v[208:209], s[6:7], 0, v[204:205]
	s_add_i32 m0, s66, 0xc000
	ds_read_b128 v[152:155], v235
	ds_read_b128 v[164:167], v235 offset:1024
	ds_read_b128 v[168:171], v235 offset:2048
	ds_read_b128 v[172:175], v235 offset:3072
	ds_read_b128 v[176:179], v235 offset:4096
	ds_read_b128 v[180:183], v235 offset:5120
	ds_read_b128 v[184:187], v235 offset:6144
	ds_read_b128 v[188:191], v235 offset:7168
	global_load_lds_dwordx4 v[208:209], off
	v_lshl_add_u64 v[208:209], s[6:7], 0, v[206:207]
	s_add_i32 m0, s66, 0xe000
	s_nop 0
	global_load_lds_dwordx4 v[208:209], off
	s_waitcnt vmcnt(8)
	s_waitcnt lgkmcnt(0)
	s_barrier
	s_setprio 1
	s_waitcnt lgkmcnt(0)
	v_mfma_f32_16x16x32_bf16 v[160:163], v[64:67], v[152:155], v[160:163]
	v_mfma_f32_16x16x32_bf16 v[156:159], v[80:83], v[152:155], v[156:159]
	v_mfma_f32_16x16x32_bf16 v[140:143], v[64:67], v[168:171], v[140:143]
	v_mfma_f32_16x16x32_bf16 v[136:139], v[80:83], v[168:171], v[136:139]
	v_mfma_f32_16x16x32_bf16 v[116:119], v[64:67], v[176:179], v[116:119]
	v_mfma_f32_16x16x32_bf16 v[112:115], v[80:83], v[176:179], v[112:115]
	v_mfma_f32_16x16x32_bf16 v[88:91], v[64:67], v[184:187], v[88:91]
	v_mfma_f32_16x16x32_bf16 v[84:87], v[80:83], v[184:187], v[84:87]
	v_mfma_f32_16x16x32_bf16 v[160:163], v[68:71], v[164:167], v[160:163]
	v_mfma_f32_16x16x32_bf16 v[156:159], v[92:95], v[164:167], v[156:159]
	v_mfma_f32_16x16x32_bf16 v[140:143], v[68:71], v[172:175], v[140:143]
	v_mfma_f32_16x16x32_bf16 v[136:139], v[92:95], v[172:175], v[136:139]
	v_mfma_f32_16x16x32_bf16 v[116:119], v[68:71], v[180:183], v[116:119]
	v_mfma_f32_16x16x32_bf16 v[112:115], v[92:95], v[180:183], v[112:115]
	v_mfma_f32_16x16x32_bf16 v[88:91], v[68:71], v[188:191], v[88:91]
	v_mfma_f32_16x16x32_bf16 v[84:87], v[92:95], v[188:191], v[84:87]
	s_setprio 0
	s_setprio 1
	v_mfma_f32_16x16x32_bf16 v[148:151], v[104:107], v[152:155], v[148:151]
	v_mfma_f32_16x16x32_bf16 v[144:147], v[120:123], v[152:155], v[144:147]
	v_mfma_f32_16x16x32_bf16 v[128:131], v[104:107], v[168:171], v[128:131]
	v_mfma_f32_16x16x32_bf16 v[124:127], v[120:123], v[168:171], v[124:127]
	v_mfma_f32_16x16x32_bf16 v[100:103], v[104:107], v[176:179], v[100:103]
	v_mfma_f32_16x16x32_bf16 v[96:99], v[120:123], v[176:179], v[96:99]
	v_mfma_f32_16x16x32_bf16 v[76:79], v[104:107], v[184:187], v[76:79]
	v_mfma_f32_16x16x32_bf16 v[72:75], v[120:123], v[184:187], v[72:75]
	v_mfma_f32_16x16x32_bf16 v[148:151], v[108:111], v[164:167], v[148:151]
	v_mfma_f32_16x16x32_bf16 v[144:147], v[132:135], v[164:167], v[144:147]
	v_mfma_f32_16x16x32_bf16 v[128:131], v[108:111], v[172:175], v[128:131]
	v_mfma_f32_16x16x32_bf16 v[124:127], v[132:135], v[172:175], v[124:127]
	v_mfma_f32_16x16x32_bf16 v[100:103], v[108:111], v[180:183], v[100:103]
	v_mfma_f32_16x16x32_bf16 v[96:99], v[132:135], v[180:183], v[96:99]
	v_mfma_f32_16x16x32_bf16 v[76:79], v[108:111], v[188:191], v[76:79]
	v_mfma_f32_16x16x32_bf16 v[72:75], v[132:135], v[188:191], v[72:75]
	s_setprio 0
	s_barrier
	s_cmp_lg_u32 s98, 0
	s_cbranch_scc0 .Llp_17
	s_setprio 2
.Llp_17:
	s_add_i32 s48, s48, s65
	v_lshl_add_u64 v[208:209], s[28:29], 0, v[192:193]
	s_mov_b32 m0, s48
	ds_read_b128 v[152:155], v235 offset:16384
	ds_read_b128 v[164:167], v235 offset:17408
	ds_read_b128 v[168:171], v235 offset:18432
	ds_read_b128 v[172:175], v235 offset:19456
	ds_read_b128 v[176:179], v235 offset:20480
	ds_read_b128 v[180:183], v235 offset:21504
	ds_read_b128 v[184:187], v235 offset:22528
	ds_read_b128 v[188:191], v235 offset:23552
	global_load_lds_dwordx4 v[208:209], off
	s_add_i32 m0, s48, 0x2000
	s_add_u32 s48, s28, 0x20000
	v_lshl_add_u64 v[210:211], s[28:29], 0, v[198:199]
	s_addc_u32 s49, s29, 0
	s_add_i32 s82, s82, s65
	global_load_lds_dwordx4 v[210:211], off
	v_lshl_add_u64 v[212:213], s[48:49], 0, v[192:193]
	s_mov_b32 m0, s82
	v_lshl_add_u64 v[214:215], s[34:35], 0, v[200:201]
	global_load_lds_dwordx4 v[212:213], off
	v_lshl_add_u64 v[212:213], s[48:49], 0, v[198:199]
	s_add_i32 m0, s82, 0x2000
	s_nop 0
	global_load_lds_dwordx4 v[212:213], off
	v_lshl_add_u64 v[212:213], s[34:35], 0, v[202:203]
	s_mov_b32 m0, s66
	s_nop 0
	global_load_lds_dwordx4 v[212:213], off
	s_mov_b32 m0, s67
	s_nop 0
	global_load_lds_dwordx4 v[214:215], off
	s_waitcnt vmcnt(8)
	s_waitcnt lgkmcnt(0)
	s_barrier
; #define PG8_STAGE(bufoff, gbase, voff) do { _Pragma("unroll") for (int _i = 0; _i < 2; ++_i) \
;         __builtin_amdgcn_global_load_lds((const unsigned*)((const char*)(gbase) + (voff)[_i]), (PG8_LAS unsigned*)(lds + (bufoff) + ldsw + _i * 8192), 16, 0, 0); } while (0)
; #define PG8_LDA(dst, b, h) do { _Pragma("unroll") for (int m = 0; m < 4; ++m) _Pragma("unroll") for (int k = 0; k < 2; ++k) dst[m][k] = *(const PG8_LAS bf16x8*)(lds + PG8_SA(b, h) + aoff + m * 2048 + k * 1024); } while (0)
; #define PG8_LDB(dst, b, h) do { _Pragma("unroll") for (int n = 0; n < 2; ++n) _Pragma("unroll") for (int k = 0; k < 2; ++k) dst[n][k] = *(const PG8_LAS bf16x8*)(lds + PG8_SB(b, h) + boff + n * 2048 + k * 1024); } while (0)
; #define PG8_MMA(ai, bj, At, Bt) do { __builtin_amdgcn_s_setprio(1); _Pragma("unroll") for (int m = 0; m < 4; ++m) _Pragma("unroll") for (int n = 0; n < 2; ++n) _Pragma("unroll") for (int k = 0; k < 2; ++k) \
;         acc[ai][bj][m][n] = __builtin_amdgcn_mfma_f32_16x16x32_bf16(Bt[n][k], At[m][k], acc[ai][bj][m][n], 0, 0, 0); __builtin_amdgcn_s_setprio(0); } while (0)
; #define PG8_WAIT_V(n) asm volatile("s_waitcnt vmcnt(" #n ")" ::: "memory")
; #define PG8_WAIT_L(n) asm volatile("s_waitcnt lgkmcnt(" #n ")" ::: "memory")
; #define PG8_BAR __builtin_amdgcn_s_barrier()
; #define PG8_SCHED __builtin_amdgcn_sched_barrier(0)
;     ...
;             PG8_WAIT_V(8); PG8_WAIT_L(0); PG8_BAR; PG8_MMA(1, 0, At, B0); PG8_MMA(1, 1, At, B1); PG8_BAR; PG8_SCHED;
;             PG8_LDB(B0, 1, 0); PG8_LDB(B1, 1, 1); PG8_SCHED; PG8_LDA(At, 1, 0); PG8_STAGE(PG8_SA(0, 1), a2 + hstepA, voffA);
;             PG8_WAIT_V(8); PG8_WAIT_L(0); PG8_BAR; PG8_MMA(0, 0, At, B0); PG8_MMA(0, 1, At, B1); PG8_BAR; PG8_SCHED;
	s_setprio 1
	s_waitcnt lgkmcnt(0)
	v_mfma_f32_16x16x32_bf16 v[60:63], v[64:67], v[152:155], v[60:63]
	v_mfma_f32_16x16x32_bf16 v[56:59], v[80:83], v[152:155], v[56:59]
	v_mfma_f32_16x16x32_bf16 v[44:47], v[64:67], v[168:171], v[44:47]
	v_mfma_f32_16x16x32_bf16 v[40:43], v[80:83], v[168:171], v[40:43]
	v_mfma_f32_16x16x32_bf16 v[28:31], v[64:67], v[176:179], v[28:31]
	v_mfma_f32_16x16x32_bf16 v[24:27], v[80:83], v[176:179], v[24:27]
	v_mfma_f32_16x16x32_bf16 v[12:15], v[64:67], v[184:187], v[12:15]
	v_mfma_f32_16x16x32_bf16 v[8:11], v[80:83], v[184:187], v[8:11]
	v_mfma_f32_16x16x32_bf16 v[60:63], v[68:71], v[164:167], v[60:63]
	v_mfma_f32_16x16x32_bf16 v[56:59], v[92:95], v[164:167], v[56:59]
	v_mfma_f32_16x16x32_bf16 v[44:47], v[68:71], v[172:175], v[44:47]
	v_mfma_f32_16x16x32_bf16 v[40:43], v[92:95], v[172:175], v[40:43]
	v_mfma_f32_16x16x32_bf16 v[28:31], v[68:71], v[180:183], v[28:31]
	v_mfma_f32_16x16x32_bf16 v[24:27], v[92:95], v[180:183], v[24:27]
	v_mfma_f32_16x16x32_bf16 v[12:15], v[68:71], v[188:191], v[12:15]
	v_mfma_f32_16x16x32_bf16 v[8:11], v[92:95], v[188:191], v[8:11]
	s_setprio 0
	s_setprio 1
	v_mfma_f32_16x16x32_bf16 v[52:55], v[104:107], v[152:155], v[52:55]
	v_mfma_f32_16x16x32_bf16 v[48:51], v[120:123], v[152:155], v[48:51]
	v_mfma_f32_16x16x32_bf16 v[36:39], v[104:107], v[168:171], v[36:39]
	v_mfma_f32_16x16x32_bf16 v[32:35], v[120:123], v[168:171], v[32:35]
	v_mfma_f32_16x16x32_bf16 v[20:23], v[104:107], v[176:179], v[20:23]
	v_mfma_f32_16x16x32_bf16 v[16:19], v[120:123], v[176:179], v[16:19]
	v_mfma_f32_16x16x32_bf16 v[4:7], v[104:107], v[184:187], v[4:7]
	v_mfma_f32_16x16x32_bf16 v[0:3], v[120:123], v[184:187], v[0:3]
	v_mfma_f32_16x16x32_bf16 v[52:55], v[108:111], v[164:167], v[52:55]
	v_mfma_f32_16x16x32_bf16 v[48:51], v[132:135], v[164:167], v[48:51]
	v_mfma_f32_16x16x32_bf16 v[36:39], v[108:111], v[172:175], v[36:39]
	v_mfma_f32_16x16x32_bf16 v[32:35], v[132:135], v[172:175], v[32:35]
	v_mfma_f32_16x16x32_bf16 v[20:23], v[108:111], v[180:183], v[20:23]
	v_mfma_f32_16x16x32_bf16 v[16:19], v[132:135], v[180:183], v[16:19]
	v_mfma_f32_16x16x32_bf16 v[4:7], v[108:111], v[188:191], v[4:7]
	v_mfma_f32_16x16x32_bf16 v[0:3], v[132:135], v[188:191], v[0:3]
	s_setprio 0
	s_barrier
	s_cmp_lg_u32 s98, 0
	s_cbranch_scc0 .Llp_18
	s_setprio 2
.Llp_18:
	s_add_i32 s48, 0, 0x18000
	s_add_i32 s49, 0, 0x1c000
	v_add_u32_e32 v92, s48, v234
	v_add_u32_e32 v132, s49, v234
	ds_read_b128 v[64:67], v92
	ds_read_b128 v[68:71], v92 offset:1024
	ds_read_b128 v[80:83], v92 offset:2048
	ds_read_b128 v[92:95], v92 offset:3072
	ds_read_b128 v[104:107], v132
	ds_read_b128 v[108:111], v132 offset:1024
	ds_read_b128 v[120:123], v132 offset:2048
	ds_read_b128 v[132:135], v132 offset:3072
	s_add_u32 s34, s34, 0x20000
	s_addc_u32 s35, s35, 0
	s_mov_b32 m0, s68
	v_lshl_add_u64 v[216:217], s[34:35], 0, v[202:203]
	ds_read_b128 v[152:155], v235 offset:32768
	ds_read_b128 v[164:167], v235 offset:33792
	ds_read_b128 v[168:171], v235 offset:34816
	ds_read_b128 v[172:175], v235 offset:35840
	ds_read_b128 v[176:179], v235 offset:36864
	ds_read_b128 v[180:183], v235 offset:37888
	ds_read_b128 v[184:187], v235 offset:38912
	ds_read_b128 v[188:191], v235 offset:39936
	global_load_lds_dwordx4 v[216:217], off
	v_lshl_add_u64 v[216:217], s[34:35], 0, v[200:201]
	s_mov_b32 m0, s69
	s_nop 0
	global_load_lds_dwordx4 v[216:217], off
	s_waitcnt vmcnt(8)
	s_waitcnt lgkmcnt(0)
	s_barrier
	s_setprio 1
	s_waitcnt lgkmcnt(0)
	v_mfma_f32_16x16x32_bf16 v[160:163], v[64:67], v[152:155], v[160:163]
	v_mfma_f32_16x16x32_bf16 v[156:159], v[80:83], v[152:155], v[156:159]
	v_mfma_f32_16x16x32_bf16 v[140:143], v[64:67], v[168:171], v[140:143]
	v_mfma_f32_16x16x32_bf16 v[136:139], v[80:83], v[168:171], v[136:139]
	v_mfma_f32_16x16x32_bf16 v[116:119], v[64:67], v[176:179], v[116:119]
	v_mfma_f32_16x16x32_bf16 v[112:115], v[80:83], v[176:179], v[112:115]
	v_mfma_f32_16x16x32_bf16 v[88:91], v[64:67], v[184:187], v[88:91]
	v_mfma_f32_16x16x32_bf16 v[84:87], v[80:83], v[184:187], v[84:87]
	v_mfma_f32_16x16x32_bf16 v[160:163], v[68:71], v[164:167], v[160:163]
	v_mfma_f32_16x16x32_bf16 v[156:159], v[92:95], v[164:167], v[156:159]
	v_mfma_f32_16x16x32_bf16 v[140:143], v[68:71], v[172:175], v[140:143]
	v_mfma_f32_16x16x32_bf16 v[136:139], v[92:95], v[172:175], v[136:139]
	v_mfma_f32_16x16x32_bf16 v[116:119], v[68:71], v[180:183], v[116:119]
	v_mfma_f32_16x16x32_bf16 v[112:115], v[92:95], v[180:183], v[112:115]
	v_mfma_f32_16x16x32_bf16 v[88:91], v[68:71], v[188:191], v[88:91]
	v_mfma_f32_16x16x32_bf16 v[84:87], v[92:95], v[188:191], v[84:87]
	s_setprio 0
	s_setprio 1
	v_mfma_f32_16x16x32_bf16 v[148:151], v[104:107], v[152:155], v[148:151]
	v_mfma_f32_16x16x32_bf16 v[144:147], v[120:123], v[152:155], v[144:147]
	v_mfma_f32_16x16x32_bf16 v[128:131], v[104:107], v[168:171], v[128:131]
	v_mfma_f32_16x16x32_bf16 v[124:127], v[120:123], v[168:171], v[124:127]
	v_mfma_f32_16x16x32_bf16 v[100:103], v[104:107], v[176:179], v[100:103]
	v_mfma_f32_16x16x32_bf16 v[96:99], v[120:123], v[176:179], v[96:99]
	v_mfma_f32_16x16x32_bf16 v[76:79], v[104:107], v[184:187], v[76:79]
	v_mfma_f32_16x16x32_bf16 v[72:75], v[120:123], v[184:187], v[72:75]
	v_mfma_f32_16x16x32_bf16 v[148:151], v[108:111], v[164:167], v[148:151]
	v_mfma_f32_16x16x32_bf16 v[144:147], v[132:135], v[164:167], v[144:147]
	v_mfma_f32_16x16x32_bf16 v[128:131], v[108:111], v[172:175], v[128:131]
	v_mfma_f32_16x16x32_bf16 v[124:127], v[132:135], v[172:175], v[124:127]
	v_mfma_f32_16x16x32_bf16 v[100:103], v[108:111], v[180:183], v[100:103]
	v_mfma_f32_16x16x32_bf16 v[96:99], v[132:135], v[180:183], v[96:99]
	v_mfma_f32_16x16x32_bf16 v[76:79], v[108:111], v[188:191], v[76:79]
	v_mfma_f32_16x16x32_bf16 v[72:75], v[132:135], v[188:191], v[72:75]
	s_setprio 0
	s_barrier
	s_cmp_lg_u32 s98, 0
	s_cbranch_scc0 .Llp_19
	s_setprio 2
; #define PG8_STAGE(bufoff, gbase, voff) do { _Pragma("unroll") for (int _i = 0; _i < 2; ++_i) \
;         __builtin_amdgcn_global_load_lds((const unsigned*)((const char*)(gbase) + (voff)[_i]), (PG8_LAS unsigned*)(lds + (bufoff) + ldsw + _i * 8192), 16, 0, 0); } while (0)
; #define PG8_LDA(dst, b, h) do { _Pragma("unroll") for (int m = 0; m < 4; ++m) _Pragma("unroll") for (int k = 0; k < 2; ++k) dst[m][k] = *(const PG8_LAS bf16x8*)(lds + PG8_SA(b, h) + aoff + m * 2048 + k * 1024); } while (0)
; #define PG8_MMA(ai, bj, At, Bt) do { __builtin_amdgcn_s_setprio(1); _Pragma("unroll") for (int m = 0; m < 4; ++m) _Pragma("unroll") for (int n = 0; n < 2; ++n) _Pragma("unroll") for (int k = 0; k < 2; ++k) \
;         acc[ai][bj][m][n] = __builtin_amdgcn_mfma_f32_16x16x32_bf16(Bt[n][k], At[m][k], acc[ai][bj][m][n], 0, 0, 0); __builtin_amdgcn_s_setprio(0); } while (0)
; #define PG8_WAIT_V(n) asm volatile("s_waitcnt vmcnt(" #n ")" ::: "memory")
; #define PG8_WAIT_L(n) asm volatile("s_waitcnt lgkmcnt(" #n ")" ::: "memory")
; #define PG8_BAR __builtin_amdgcn_s_barrier()
; #define PG8_SCHED __builtin_amdgcn_sched_barrier(0)
;     ...
;         for (int t = 0; t < nt; t += 2) {
;     ...
;             PG8_LDA(At, 1, 1); PG8_STAGE(PG8_SB(1, 0), b3, voffB); PG8_STAGE(PG8_SB(1, 1), b3 + hstepB, voffB); PG8_STAGE(PG8_SA(1, 0), a3, voffA);
;             PG8_WAIT_V(8); PG8_WAIT_L(0); PG8_BAR; PG8_MMA(1, 0, At, B0); PG8_MMA(1, 1, At, B1); PG8_BAR; PG8_SCHED;
.Llp_19:
	s_add_i32 s34, s48, s65
	v_lshl_add_u64 v[208:209], v[208:209], 0, s[22:23]
	s_mov_b32 m0, s34
	ds_read_b128 v[152:155], v235 offset:49152
	ds_read_b128 v[164:167], v235 offset:50176
	ds_read_b128 v[168:171], v235 offset:51200
	ds_read_b128 v[172:175], v235 offset:52224
	ds_read_b128 v[176:179], v235 offset:53248
	ds_read_b128 v[180:183], v235 offset:54272
	ds_read_b128 v[184:187], v235 offset:55296
	ds_read_b128 v[188:191], v235 offset:56320
	global_load_lds_dwordx4 v[208:209], off
	s_add_i32 m0, s34, 0x2000
	s_add_u32 s28, s28, 0x20080
	v_lshl_add_u64 v[208:209], v[210:211], 0, s[22:23]
	s_addc_u32 s29, s29, 0
	s_add_i32 s34, s49, s65
	global_load_lds_dwordx4 v[208:209], off
	v_lshl_add_u64 v[208:209], s[28:29], 0, v[192:193]
	s_mov_b32 m0, s34
	s_nop 0
	global_load_lds_dwordx4 v[208:209], off
	v_lshl_add_u64 v[208:209], s[28:29], 0, v[198:199]
	s_add_i32 m0, s34, 0x2000
	s_nop 0
	global_load_lds_dwordx4 v[208:209], off
	v_lshl_add_u64 v[208:209], v[212:213], 0, s[22:23]
	s_mov_b32 m0, s72
	s_nop 0
	global_load_lds_dwordx4 v[208:209], off
	v_lshl_add_u64 v[208:209], v[214:215], 0, s[22:23]
	s_mov_b32 m0, s73
	s_nop 0
	global_load_lds_dwordx4 v[208:209], off
	s_waitcnt vmcnt(8)
	s_waitcnt lgkmcnt(0)
	s_barrier
	s_setprio 1
	s_waitcnt lgkmcnt(0)
	v_mfma_f32_16x16x32_bf16 v[60:63], v[64:67], v[152:155], v[60:63]
	v_mfma_f32_16x16x32_bf16 v[56:59], v[80:83], v[152:155], v[56:59]
	v_mfma_f32_16x16x32_bf16 v[44:47], v[64:67], v[168:171], v[44:47]
	v_mfma_f32_16x16x32_bf16 v[40:43], v[80:83], v[168:171], v[40:43]
	v_mfma_f32_16x16x32_bf16 v[28:31], v[64:67], v[176:179], v[28:31]
	v_mfma_f32_16x16x32_bf16 v[24:27], v[80:83], v[176:179], v[24:27]
	v_mfma_f32_16x16x32_bf16 v[12:15], v[64:67], v[184:187], v[12:15]
	v_mfma_f32_16x16x32_bf16 v[8:11], v[80:83], v[184:187], v[8:11]
	v_mfma_f32_16x16x32_bf16 v[60:63], v[68:71], v[164:167], v[60:63]
	v_mfma_f32_16x16x32_bf16 v[56:59], v[92:95], v[164:167], v[56:59]
	v_mfma_f32_16x16x32_bf16 v[44:47], v[68:71], v[172:175], v[44:47]
	v_mfma_f32_16x16x32_bf16 v[40:43], v[92:95], v[172:175], v[40:43]
	v_mfma_f32_16x16x32_bf16 v[28:31], v[68:71], v[180:183], v[28:31]
	v_mfma_f32_16x16x32_bf16 v[24:27], v[92:95], v[180:183], v[24:27]
	v_mfma_f32_16x16x32_bf16 v[12:15], v[68:71], v[188:191], v[12:15]
	v_mfma_f32_16x16x32_bf16 v[8:11], v[92:95], v[188:191], v[8:11]
	s_setprio 0
	s_setprio 1
	v_mfma_f32_16x16x32_bf16 v[52:55], v[104:107], v[152:155], v[52:55]
	v_mfma_f32_16x16x32_bf16 v[48:51], v[120:123], v[152:155], v[48:51]
	v_mfma_f32_16x16x32_bf16 v[36:39], v[104:107], v[168:171], v[36:39]
	v_mfma_f32_16x16x32_bf16 v[32:35], v[120:123], v[168:171], v[32:35]
	v_mfma_f32_16x16x32_bf16 v[20:23], v[104:107], v[176:179], v[20:23]
	v_mfma_f32_16x16x32_bf16 v[16:19], v[120:123], v[176:179], v[16:19]
	v_mfma_f32_16x16x32_bf16 v[4:7], v[104:107], v[184:187], v[4:7]
	v_mfma_f32_16x16x32_bf16 v[0:3], v[120:123], v[184:187], v[0:3]
	v_mfma_f32_16x16x32_bf16 v[52:55], v[108:111], v[164:167], v[52:55]
	v_mfma_f32_16x16x32_bf16 v[48:51], v[132:135], v[164:167], v[48:51]
	v_mfma_f32_16x16x32_bf16 v[36:39], v[108:111], v[172:175], v[36:39]
	v_mfma_f32_16x16x32_bf16 v[32:35], v[132:135], v[172:175], v[32:35]
	v_mfma_f32_16x16x32_bf16 v[20:23], v[108:111], v[180:183], v[20:23]
	v_mfma_f32_16x16x32_bf16 v[16:19], v[132:135], v[180:183], v[16:19]
	v_mfma_f32_16x16x32_bf16 v[4:7], v[108:111], v[188:191], v[4:7]
	v_mfma_f32_16x16x32_bf16 v[0:3], v[132:135], v[188:191], v[0:3]
	s_setprio 0
	s_barrier
	s_cmp_lg_u32 s98, 0
	s_cbranch_scc0 .Llp_20
	s_setprio 2
.Llp_20:
	s_add_i32 s81, s81, 2
	s_add_u32 s6, s6, 0x100
	s_addc_u32 s7, s7, 0
	s_add_u32 s79, s79, 0x100
	s_addc_u32 s80, s80, 0
	s_cmp_gt_u32 s81, 5
	s_cbranch_scc0 .LBB0_963
	s_and_b64 vcc, exec, s[38:39]
	s_cbranch_vccz .LBB0_966
	s_barrier

; #define PG8_STAGE(bufoff, gbase, voff) do { _Pragma("unroll") for (int _i = 0; _i < 2; ++_i) \
;         __builtin_amdgcn_global_load_lds((const unsigned*)((const char*)(gbase) + (voff)[_i]), (PG8_LAS unsigned*)(lds + (bufoff) + ldsw + _i * 8192), 16, 0, 0); } while (0)
; #define PG8_LDA(dst, b, h) do { _Pragma("unroll") for (int m = 0; m < 4; ++m) _Pragma("unroll") for (int k = 0; k < 2; ++k) dst[m][k] = *(const PG8_LAS bf16x8*)(lds + PG8_SA(b, h) + aoff + m * 2048 + k * 1024); } while (0)
; #define PG8_LDB(dst, b, h) do { _Pragma("unroll") for (int n = 0; n < 2; ++n) _Pragma("unroll") for (int k = 0; k < 2; ++k) dst[n][k] = *(const PG8_LAS bf16x8*)(lds + PG8_SB(b, h) + boff + n * 2048 + k * 1024); } while (0)
; #define PG8_MMA(ai, bj, At, Bt) do { __builtin_amdgcn_s_setprio(1); _Pragma("unroll") for (int m = 0; m < 4; ++m) _Pragma("unroll") for (int n = 0; n < 2; ++n) _Pragma("unroll") for (int k = 0; k < 2; ++k) \
;         acc[ai][bj][m][n] = __builtin_amdgcn_mfma_f32_16x16x32_bf16(Bt[n][k], At[m][k], acc[ai][bj][m][n], 0, 0, 0); __builtin_amdgcn_s_setprio(0); } while (0)
; #define PG8_WAIT_V(n) asm volatile("s_waitcnt vmcnt(" #n ")" ::: "memory")
; #define PG8_WAIT_L(n) asm volatile("s_waitcnt lgkmcnt(" #n ")" ::: "memory")
; #define PG8_BAR __builtin_amdgcn_s_barrier()
; #define PG8_SCHED __builtin_amdgcn_sched_barrier(0)
;     ...
;             const bool last = (t == nt - 2);
;             const char* a1 = cA + (size_t)(t + 1) * kstep;
;             const char* a2 = last ? nA : cA + (size_t)(t + 2) * kstep; const char* b2 = last ? nB : cB + (size_t)(t + 2) * kstep;
;             const char* a3 = a2 + kstep; const char* b3 = b2 + kstep;
;             if (last && has_next) S.a_ready(nxt);
;             if constexpr (SP2) {
;             PG8_LDB(B0, 0, 0); PG8_LDB(B1, 0, 1); PG8_SCHED; PG8_LDA(At, 0, 0); PG8_STAGE(PG8_SA(1, 1), a1 + hstepA, voffA);
;             PG8_WAIT_V(8); PG8_WAIT_L(0); PG8_BAR; PG8_MMA(0, 0, At, B0); PG8_MMA(0, 1, At, B1); PG8_BAR; PG8_SCHED;
;             PG8_LDA(At, 0, 1); PG8_STAGE(PG8_SB(0, 0), b2, voffB); PG8_STAGE(PG8_SB(0, 1), b2 + hstepB, voffB); PG8_STAGE(PG8_SA(0, 0), a2, voffA);
.LBB0_1083:
	s_add_u32 s6, s28, 0x100
	s_addc_u32 s7, s29, 0
	s_add_i32 s48, 0, 0x10000
	s_cmp_eq_u32 s76, 12
	s_cselect_b32 s41, s53, s7
	s_cselect_b32 s40, s52, s6
	s_cselect_b32 s35, s51, s75
	s_cselect_b32 s34, s73, s74
	s_add_i32 s49, 0, 0x14000
	v_add_u32_e32 v92, s48, v234
	v_add_u32_e32 v132, s49, v234
	ds_read_b128 v[64:67], v92
	ds_read_b128 v[68:71], v92 offset:1024
	ds_read_b128 v[80:83], v92 offset:2048
	ds_read_b128 v[92:95], v92 offset:3072
	ds_read_b128 v[104:107], v132
	ds_read_b128 v[108:111], v132 offset:1024
	ds_read_b128 v[120:123], v132 offset:2048
	ds_read_b128 v[132:135], v132 offset:3072
	v_lshl_add_u64 v[208:209], s[28:29], 0, v[204:205]
	s_add_i32 m0, s61, 0xc000
	ds_read_b128 v[152:155], v235
	ds_read_b128 v[164:167], v235 offset:1024
	ds_read_b128 v[168:171], v235 offset:2048
	ds_read_b128 v[172:175], v235 offset:3072
	ds_read_b128 v[176:179], v235 offset:4096
	ds_read_b128 v[180:183], v235 offset:5120
	ds_read_b128 v[184:187], v235 offset:6144
	ds_read_b128 v[188:191], v235 offset:7168
	global_load_lds_dwordx4 v[208:209], off
	v_lshl_add_u64 v[208:209], s[28:29], 0, v[206:207]
	s_add_i32 m0, s61, 0xe000
	s_nop 0
	global_load_lds_dwordx4 v[208:209], off
	s_waitcnt vmcnt(8)
	s_waitcnt lgkmcnt(0)
	s_barrier
	s_setprio 1
	s_waitcnt lgkmcnt(0)
	v_mfma_f32_16x16x32_bf16 v[160:163], v[64:67], v[152:155], v[160:163]
	v_mfma_f32_16x16x32_bf16 v[156:159], v[80:83], v[152:155], v[156:159]
	v_mfma_f32_16x16x32_bf16 v[140:143], v[64:67], v[168:171], v[140:143]
	v_mfma_f32_16x16x32_bf16 v[136:139], v[80:83], v[168:171], v[136:139]
	v_mfma_f32_16x16x32_bf16 v[116:119], v[64:67], v[176:179], v[116:119]
	v_mfma_f32_16x16x32_bf16 v[112:115], v[80:83], v[176:179], v[112:115]
	v_mfma_f32_16x16x32_bf16 v[88:91], v[64:67], v[184:187], v[88:91]
	v_mfma_f32_16x16x32_bf16 v[84:87], v[80:83], v[184:187], v[84:87]
	v_mfma_f32_16x16x32_bf16 v[160:163], v[68:71], v[164:167], v[160:163]
	v_mfma_f32_16x16x32_bf16 v[156:159], v[92:95], v[164:167], v[156:159]
	v_mfma_f32_16x16x32_bf16 v[140:143], v[68:71], v[172:175], v[140:143]
	v_mfma_f32_16x16x32_bf16 v[136:139], v[92:95], v[172:175], v[136:139]
	v_mfma_f32_16x16x32_bf16 v[116:119], v[68:71], v[180:183], v[116:119]
	v_mfma_f32_16x16x32_bf16 v[112:115], v[92:95], v[180:183], v[112:115]
	v_mfma_f32_16x16x32_bf16 v[88:91], v[68:71], v[188:191], v[88:91]
	v_mfma_f32_16x16x32_bf16 v[84:87], v[92:95], v[188:191], v[84:87]
	s_setprio 0
	s_setprio 1
	v_mfma_f32_16x16x32_bf16 v[148:151], v[104:107], v[152:155], v[148:151]
	v_mfma_f32_16x16x32_bf16 v[144:147], v[120:123], v[152:155], v[144:147]
	v_mfma_f32_16x16x32_bf16 v[128:131], v[104:107], v[168:171], v[128:131]
	v_mfma_f32_16x16x32_bf16 v[124:127], v[120:123], v[168:171], v[124:127]
	v_mfma_f32_16x16x32_bf16 v[100:103], v[104:107], v[176:179], v[100:103]
	v_mfma_f32_16x16x32_bf16 v[96:99], v[120:123], v[176:179], v[96:99]
	v_mfma_f32_16x16x32_bf16 v[76:79], v[104:107], v[184:187], v[76:79]
	v_mfma_f32_16x16x32_bf16 v[72:75], v[120:123], v[184:187], v[72:75]
	v_mfma_f32_16x16x32_bf16 v[148:151], v[108:111], v[164:167], v[148:151]
	v_mfma_f32_16x16x32_bf16 v[144:147], v[132:135], v[164:167], v[144:147]
	v_mfma_f32_16x16x32_bf16 v[128:131], v[108:111], v[172:175], v[128:131]
	v_mfma_f32_16x16x32_bf16 v[124:127], v[132:135], v[172:175], v[124:127]
	v_mfma_f32_16x16x32_bf16 v[100:103], v[108:111], v[180:183], v[100:103]
	v_mfma_f32_16x16x32_bf16 v[96:99], v[132:135], v[180:183], v[96:99]
	v_mfma_f32_16x16x32_bf16 v[76:79], v[108:111], v[188:191], v[76:79]
	v_mfma_f32_16x16x32_bf16 v[72:75], v[132:135], v[188:191], v[72:75]
	s_setprio 0
	s_barrier
	s_cmp_lg_u32 s98, 0
	s_cbranch_scc0 .Llp_21
	s_setprio 2
.Llp_21:
	s_add_i32 s28, s48, s58
	v_lshl_add_u64 v[208:209], s[34:35], 0, v[192:193]
	s_mov_b32 m0, s28
	ds_read_b128 v[152:155], v235 offset:16384
	ds_read_b128 v[164:167], v235 offset:17408
	ds_read_b128 v[168:171], v235 offset:18432
	ds_read_b128 v[172:175], v235 offset:19456
	ds_read_b128 v[176:179], v235 offset:20480
	ds_read_b128 v[180:183], v235 offset:21504
	ds_read_b128 v[184:187], v235 offset:22528
	ds_read_b128 v[188:191], v235 offset:23552
	global_load_lds_dwordx4 v[208:209], off
	s_add_i32 m0, s28, 0x2000
	s_add_u32 s28, s34, 0x40000
	v_lshl_add_u64 v[210:211], s[34:35], 0, v[198:199]
	s_addc_u32 s29, s35, 0
	s_add_i32 s48, s49, s58
	global_load_lds_dwordx4 v[210:211], off
	v_lshl_add_u64 v[212:213], s[28:29], 0, v[192:193]
	s_mov_b32 m0, s48
	v_lshl_add_u64 v[214:215], s[40:41], 0, v[200:201]
	global_load_lds_dwordx4 v[212:213], off
	v_lshl_add_u64 v[212:213], s[28:29], 0, v[198:199]
	s_add_i32 m0, s48, 0x2000
	s_nop 0
	global_load_lds_dwordx4 v[212:213], off
	v_lshl_add_u64 v[212:213], s[40:41], 0, v[202:203]
	s_mov_b32 m0, s61
	s_nop 0
	global_load_lds_dwordx4 v[212:213], off
	s_mov_b32 m0, s62
	s_nop 0
	global_load_lds_dwordx4 v[214:215], off
	s_waitcnt vmcnt(8)
	s_waitcnt lgkmcnt(0)
	s_barrier
; #define PG8_STAGE(bufoff, gbase, voff) do { _Pragma("unroll") for (int _i = 0; _i < 2; ++_i) \
;         __builtin_amdgcn_global_load_lds((const unsigned*)((const char*)(gbase) + (voff)[_i]), (PG8_LAS unsigned*)(lds + (bufoff) + ldsw + _i * 8192), 16, 0, 0); } while (0)
; #define PG8_LDA(dst, b, h) do { _Pragma("unroll") for (int m = 0; m < 4; ++m) _Pragma("unroll") for (int k = 0; k < 2; ++k) dst[m][k] = *(const PG8_LAS bf16x8*)(lds + PG8_SA(b, h) + aoff + m * 2048 + k * 1024); } while (0)
; #define PG8_LDB(dst, b, h) do { _Pragma("unroll") for (int n = 0; n < 2; ++n) _Pragma("unroll") for (int k = 0; k < 2; ++k) dst[n][k] = *(const PG8_LAS bf16x8*)(lds + PG8_SB(b, h) + boff + n * 2048 + k * 1024); } while (0)
; #define PG8_MMA(ai, bj, At, Bt) do { __builtin_amdgcn_s_setprio(1); _Pragma("unroll") for (int m = 0; m < 4; ++m) _Pragma("unroll") for (int n = 0; n < 2; ++n) _Pragma("unroll") for (int k = 0; k < 2; ++k) \
;         acc[ai][bj][m][n] = __builtin_amdgcn_mfma_f32_16x16x32_bf16(Bt[n][k], At[m][k], acc[ai][bj][m][n], 0, 0, 0); __builtin_amdgcn_s_setprio(0); } while (0)
; #define PG8_WAIT_V(n) asm volatile("s_waitcnt vmcnt(" #n ")" ::: "memory")
; #define PG8_WAIT_L(n) asm volatile("s_waitcnt lgkmcnt(" #n ")" ::: "memory")
; #define PG8_BAR __builtin_amdgcn_s_barrier()
; #define PG8_SCHED __builtin_amdgcn_sched_barrier(0)
;     ...
;             PG8_WAIT_V(8); PG8_WAIT_L(0); PG8_BAR; PG8_MMA(1, 0, At, B0); PG8_MMA(1, 1, At, B1); PG8_BAR; PG8_SCHED;
;             PG8_LDB(B0, 1, 0); PG8_LDB(B1, 1, 1); PG8_SCHED; PG8_LDA(At, 1, 0); PG8_STAGE(PG8_SA(0, 1), a2 + hstepA, voffA);
;             PG8_WAIT_V(8); PG8_WAIT_L(0); PG8_BAR; PG8_MMA(0, 0, At, B0); PG8_MMA(0, 1, At, B1); PG8_BAR; PG8_SCHED;
	s_setprio 1
	s_waitcnt lgkmcnt(0)
	v_mfma_f32_16x16x32_bf16 v[60:63], v[64:67], v[152:155], v[60:63]
	v_mfma_f32_16x16x32_bf16 v[56:59], v[80:83], v[152:155], v[56:59]
	v_mfma_f32_16x16x32_bf16 v[44:47], v[64:67], v[168:171], v[44:47]
	v_mfma_f32_16x16x32_bf16 v[40:43], v[80:83], v[168:171], v[40:43]
	v_mfma_f32_16x16x32_bf16 v[28:31], v[64:67], v[176:179], v[28:31]
	v_mfma_f32_16x16x32_bf16 v[24:27], v[80:83], v[176:179], v[24:27]
	v_mfma_f32_16x16x32_bf16 v[12:15], v[64:67], v[184:187], v[12:15]
	v_mfma_f32_16x16x32_bf16 v[8:11], v[80:83], v[184:187], v[8:11]
	v_mfma_f32_16x16x32_bf16 v[60:63], v[68:71], v[164:167], v[60:63]
	v_mfma_f32_16x16x32_bf16 v[56:59], v[92:95], v[164:167], v[56:59]
	v_mfma_f32_16x16x32_bf16 v[44:47], v[68:71], v[172:175], v[44:47]
	v_mfma_f32_16x16x32_bf16 v[40:43], v[92:95], v[172:175], v[40:43]
	v_mfma_f32_16x16x32_bf16 v[28:31], v[68:71], v[180:183], v[28:31]
	v_mfma_f32_16x16x32_bf16 v[24:27], v[92:95], v[180:183], v[24:27]
	v_mfma_f32_16x16x32_bf16 v[12:15], v[68:71], v[188:191], v[12:15]
	v_mfma_f32_16x16x32_bf16 v[8:11], v[92:95], v[188:191], v[8:11]
	s_setprio 0
	s_setprio 1
	v_mfma_f32_16x16x32_bf16 v[52:55], v[104:107], v[152:155], v[52:55]
	v_mfma_f32_16x16x32_bf16 v[48:51], v[120:123], v[152:155], v[48:51]
	v_mfma_f32_16x16x32_bf16 v[36:39], v[104:107], v[168:171], v[36:39]
	v_mfma_f32_16x16x32_bf16 v[32:35], v[120:123], v[168:171], v[32:35]
	v_mfma_f32_16x16x32_bf16 v[20:23], v[104:107], v[176:179], v[20:23]
	v_mfma_f32_16x16x32_bf16 v[16:19], v[120:123], v[176:179], v[16:19]
	v_mfma_f32_16x16x32_bf16 v[4:7], v[104:107], v[184:187], v[4:7]
	v_mfma_f32_16x16x32_bf16 v[0:3], v[120:123], v[184:187], v[0:3]
	v_mfma_f32_16x16x32_bf16 v[52:55], v[108:111], v[164:167], v[52:55]
	v_mfma_f32_16x16x32_bf16 v[48:51], v[132:135], v[164:167], v[48:51]
	v_mfma_f32_16x16x32_bf16 v[36:39], v[108:111], v[172:175], v[36:39]
	v_mfma_f32_16x16x32_bf16 v[32:35], v[132:135], v[172:175], v[32:35]
	v_mfma_f32_16x16x32_bf16 v[20:23], v[108:111], v[180:183], v[20:23]
	v_mfma_f32_16x16x32_bf16 v[16:19], v[132:135], v[180:183], v[16:19]
	v_mfma_f32_16x16x32_bf16 v[4:7], v[108:111], v[188:191], v[4:7]
	v_mfma_f32_16x16x32_bf16 v[0:3], v[132:135], v[188:191], v[0:3]
	s_setprio 0
	s_barrier
	s_cmp_lg_u32 s98, 0
	s_cbranch_scc0 .Llp_22
	s_setprio 2
.Llp_22:
	s_add_i32 s48, 0, 0x18000
	s_add_i32 s49, 0, 0x1c000
	v_add_u32_e32 v92, s48, v234
	v_add_u32_e32 v132, s49, v234
	ds_read_b128 v[64:67], v92
	ds_read_b128 v[68:71], v92 offset:1024
	ds_read_b128 v[80:83], v92 offset:2048
	ds_read_b128 v[92:95], v92 offset:3072
	ds_read_b128 v[104:107], v132
	ds_read_b128 v[108:111], v132 offset:1024
	ds_read_b128 v[120:123], v132 offset:2048
	ds_read_b128 v[132:135], v132 offset:3072
	s_add_u32 s28, s40, 0x60000
	s_addc_u32 s29, s41, 0
	s_mov_b32 m0, s63
	v_lshl_add_u64 v[216:217], s[28:29], 0, v[202:203]
	ds_read_b128 v[152:155], v235 offset:32768
	ds_read_b128 v[164:167], v235 offset:33792
	ds_read_b128 v[168:171], v235 offset:34816
	ds_read_b128 v[172:175], v235 offset:35840
	ds_read_b128 v[176:179], v235 offset:36864
	ds_read_b128 v[180:183], v235 offset:37888
	ds_read_b128 v[184:187], v235 offset:38912
	ds_read_b128 v[188:191], v235 offset:39936
	global_load_lds_dwordx4 v[216:217], off
	v_lshl_add_u64 v[216:217], s[28:29], 0, v[200:201]
	s_mov_b32 m0, s64
	s_nop 0
	global_load_lds_dwordx4 v[216:217], off
	s_waitcnt vmcnt(8)
	s_waitcnt lgkmcnt(0)
	s_barrier
	s_setprio 1
	s_waitcnt lgkmcnt(0)
	v_mfma_f32_16x16x32_bf16 v[160:163], v[64:67], v[152:155], v[160:163]
	v_mfma_f32_16x16x32_bf16 v[156:159], v[80:83], v[152:155], v[156:159]
	v_mfma_f32_16x16x32_bf16 v[140:143], v[64:67], v[168:171], v[140:143]
	v_mfma_f32_16x16x32_bf16 v[136:139], v[80:83], v[168:171], v[136:139]
	v_mfma_f32_16x16x32_bf16 v[116:119], v[64:67], v[176:179], v[116:119]
	v_mfma_f32_16x16x32_bf16 v[112:115], v[80:83], v[176:179], v[112:115]
	v_mfma_f32_16x16x32_bf16 v[88:91], v[64:67], v[184:187], v[88:91]
	v_mfma_f32_16x16x32_bf16 v[84:87], v[80:83], v[184:187], v[84:87]
	v_mfma_f32_16x16x32_bf16 v[160:163], v[68:71], v[164:167], v[160:163]
	v_mfma_f32_16x16x32_bf16 v[156:159], v[92:95], v[164:167], v[156:159]
	v_mfma_f32_16x16x32_bf16 v[140:143], v[68:71], v[172:175], v[140:143]
	v_mfma_f32_16x16x32_bf16 v[136:139], v[92:95], v[172:175], v[136:139]
	v_mfma_f32_16x16x32_bf16 v[116:119], v[68:71], v[180:183], v[116:119]
	v_mfma_f32_16x16x32_bf16 v[112:115], v[92:95], v[180:183], v[112:115]
	v_mfma_f32_16x16x32_bf16 v[88:91], v[68:71], v[188:191], v[88:91]
	v_mfma_f32_16x16x32_bf16 v[84:87], v[92:95], v[188:191], v[84:87]
	s_setprio 0
	s_setprio 1
	v_mfma_f32_16x16x32_bf16 v[148:151], v[104:107], v[152:155], v[148:151]
	v_mfma_f32_16x16x32_bf16 v[144:147], v[120:123], v[152:155], v[144:147]
	v_mfma_f32_16x16x32_bf16 v[128:131], v[104:107], v[168:171], v[128:131]
	v_mfma_f32_16x16x32_bf16 v[124:127], v[120:123], v[168:171], v[124:127]
	v_mfma_f32_16x16x32_bf16 v[100:103], v[104:107], v[176:179], v[100:103]
	v_mfma_f32_16x16x32_bf16 v[96:99], v[120:123], v[176:179], v[96:99]
	v_mfma_f32_16x16x32_bf16 v[76:79], v[104:107], v[184:187], v[76:79]
	v_mfma_f32_16x16x32_bf16 v[72:75], v[120:123], v[184:187], v[72:75]
	v_mfma_f32_16x16x32_bf16 v[148:151], v[108:111], v[164:167], v[148:151]
	v_mfma_f32_16x16x32_bf16 v[144:147], v[132:135], v[164:167], v[144:147]
	v_mfma_f32_16x16x32_bf16 v[128:131], v[108:111], v[172:175], v[128:131]
	v_mfma_f32_16x16x32_bf16 v[124:127], v[132:135], v[172:175], v[124:127]
	v_mfma_f32_16x16x32_bf16 v[100:103], v[108:111], v[180:183], v[100:103]
	v_mfma_f32_16x16x32_bf16 v[96:99], v[132:135], v[180:183], v[96:99]
	v_mfma_f32_16x16x32_bf16 v[76:79], v[108:111], v[188:191], v[76:79]
	v_mfma_f32_16x16x32_bf16 v[72:75], v[132:135], v[188:191], v[72:75]
	s_setprio 0
	s_barrier
	s_cmp_lg_u32 s98, 0
	s_cbranch_scc0 .Llp_23
	s_setprio 2
; #define PG8_STAGE(bufoff, gbase, voff) do { _Pragma("unroll") for (int _i = 0; _i < 2; ++_i) \
;         __builtin_amdgcn_global_load_lds((const unsigned*)((const char*)(gbase) + (voff)[_i]), (PG8_LAS unsigned*)(lds + (bufoff) + ldsw + _i * 8192), 16, 0, 0); } while (0)
; #define PG8_LDA(dst, b, h) do { _Pragma("unroll") for (int m = 0; m < 4; ++m) _Pragma("unroll") for (int k = 0; k < 2; ++k) dst[m][k] = *(const PG8_LAS bf16x8*)(lds + PG8_SA(b, h) + aoff + m * 2048 + k * 1024); } while (0)
; #define PG8_MMA(ai, bj, At, Bt) do { __builtin_amdgcn_s_setprio(1); _Pragma("unroll") for (int m = 0; m < 4; ++m) _Pragma("unroll") for (int n = 0; n < 2; ++n) _Pragma("unroll") for (int k = 0; k < 2; ++k) \
;         acc[ai][bj][m][n] = __builtin_amdgcn_mfma_f32_16x16x32_bf16(Bt[n][k], At[m][k], acc[ai][bj][m][n], 0, 0, 0); __builtin_amdgcn_s_setprio(0); } while (0)
; #define PG8_WAIT_V(n) asm volatile("s_waitcnt vmcnt(" #n ")" ::: "memory")
; #define PG8_WAIT_L(n) asm volatile("s_waitcnt lgkmcnt(" #n ")" ::: "memory")
; #define PG8_BAR __builtin_amdgcn_s_barrier()
; #define PG8_SCHED __builtin_amdgcn_sched_barrier(0)
;     ...
;             PG8_LDA(At, 1, 1); PG8_STAGE(PG8_SB(1, 0), b3, voffB); PG8_STAGE(PG8_SB(1, 1), b3 + hstepB, voffB); PG8_STAGE(PG8_SA(1, 0), a3, voffA);
;             PG8_WAIT_V(8); PG8_WAIT_L(0); PG8_BAR; PG8_MMA(1, 0, At, B0); PG8_MMA(1, 1, At, B1); PG8_BAR; PG8_SCHED;
.Llp_23:
	s_add_i32 s28, s48, s58
	v_lshl_add_u64 v[208:209], v[208:209], 0, s[22:23]
	s_mov_b32 m0, s28
	ds_read_b128 v[152:155], v235 offset:49152
	ds_read_b128 v[164:167], v235 offset:50176
	ds_read_b128 v[168:171], v235 offset:51200
	ds_read_b128 v[172:175], v235 offset:52224
	ds_read_b128 v[176:179], v235 offset:53248
	ds_read_b128 v[180:183], v235 offset:54272
	ds_read_b128 v[184:187], v235 offset:55296
	ds_read_b128 v[188:191], v235 offset:56320
	global_load_lds_dwordx4 v[208:209], off
	s_add_i32 m0, s28, 0x2000
	s_add_u32 s28, s34, 0x40080
	v_lshl_add_u64 v[208:209], v[210:211], 0, s[22:23]
	s_addc_u32 s29, s35, 0
	s_add_i32 s34, s49, s58
	global_load_lds_dwordx4 v[208:209], off
	v_lshl_add_u64 v[208:209], s[28:29], 0, v[192:193]
	s_mov_b32 m0, s34
	s_nop 0
	global_load_lds_dwordx4 v[208:209], off
	v_lshl_add_u64 v[208:209], s[28:29], 0, v[198:199]
	s_add_i32 m0, s34, 0x2000
	s_nop 0
	global_load_lds_dwordx4 v[208:209], off
	v_lshl_add_u64 v[208:209], v[212:213], 0, s[22:23]
	s_mov_b32 m0, s67
	s_nop 0
	global_load_lds_dwordx4 v[208:209], off
	v_lshl_add_u64 v[208:209], v[214:215], 0, s[22:23]
	s_mov_b32 m0, s68
	s_nop 0
	global_load_lds_dwordx4 v[208:209], off
	s_waitcnt vmcnt(8)
	s_waitcnt lgkmcnt(0)
	s_barrier
	s_setprio 1
	s_waitcnt lgkmcnt(0)
	v_mfma_f32_16x16x32_bf16 v[60:63], v[64:67], v[152:155], v[60:63]
	v_mfma_f32_16x16x32_bf16 v[56:59], v[80:83], v[152:155], v[56:59]
	v_mfma_f32_16x16x32_bf16 v[44:47], v[64:67], v[168:171], v[44:47]
	v_mfma_f32_16x16x32_bf16 v[40:43], v[80:83], v[168:171], v[40:43]
	v_mfma_f32_16x16x32_bf16 v[28:31], v[64:67], v[176:179], v[28:31]
	v_mfma_f32_16x16x32_bf16 v[24:27], v[80:83], v[176:179], v[24:27]
	v_mfma_f32_16x16x32_bf16 v[12:15], v[64:67], v[184:187], v[12:15]
	v_mfma_f32_16x16x32_bf16 v[8:11], v[80:83], v[184:187], v[8:11]
	v_mfma_f32_16x16x32_bf16 v[60:63], v[68:71], v[164:167], v[60:63]
	v_mfma_f32_16x16x32_bf16 v[56:59], v[92:95], v[164:167], v[56:59]
	v_mfma_f32_16x16x32_bf16 v[44:47], v[68:71], v[172:175], v[44:47]
	v_mfma_f32_16x16x32_bf16 v[40:43], v[92:95], v[172:175], v[40:43]
	v_mfma_f32_16x16x32_bf16 v[28:31], v[68:71], v[180:183], v[28:31]
	v_mfma_f32_16x16x32_bf16 v[24:27], v[92:95], v[180:183], v[24:27]
	v_mfma_f32_16x16x32_bf16 v[12:15], v[68:71], v[188:191], v[12:15]
	v_mfma_f32_16x16x32_bf16 v[8:11], v[92:95], v[188:191], v[8:11]
	s_setprio 0
	s_setprio 1
	v_mfma_f32_16x16x32_bf16 v[52:55], v[104:107], v[152:155], v[52:55]
	v_mfma_f32_16x16x32_bf16 v[48:51], v[120:123], v[152:155], v[48:51]
	v_mfma_f32_16x16x32_bf16 v[36:39], v[104:107], v[168:171], v[36:39]
	v_mfma_f32_16x16x32_bf16 v[32:35], v[120:123], v[168:171], v[32:35]
	v_mfma_f32_16x16x32_bf16 v[20:23], v[104:107], v[176:179], v[20:23]
	v_mfma_f32_16x16x32_bf16 v[16:19], v[120:123], v[176:179], v[16:19]
	v_mfma_f32_16x16x32_bf16 v[4:7], v[104:107], v[184:187], v[4:7]
	v_mfma_f32_16x16x32_bf16 v[0:3], v[120:123], v[184:187], v[0:3]
	v_mfma_f32_16x16x32_bf16 v[52:55], v[108:111], v[164:167], v[52:55]
	v_mfma_f32_16x16x32_bf16 v[48:51], v[132:135], v[164:167], v[48:51]
	v_mfma_f32_16x16x32_bf16 v[36:39], v[108:111], v[172:175], v[36:39]
	v_mfma_f32_16x16x32_bf16 v[32:35], v[132:135], v[172:175], v[32:35]
	v_mfma_f32_16x16x32_bf16 v[20:23], v[108:111], v[180:183], v[20:23]
	v_mfma_f32_16x16x32_bf16 v[16:19], v[132:135], v[180:183], v[16:19]
	v_mfma_f32_16x16x32_bf16 v[4:7], v[108:111], v[188:191], v[4:7]
	v_mfma_f32_16x16x32_bf16 v[0:3], v[132:135], v[188:191], v[0:3]
	s_setprio 0
	s_barrier
	s_cmp_lg_u32 s98, 0
	s_cbranch_scc0 .Llp_24
	s_setprio 2
.Llp_24:
	s_add_i32 s76, s76, 2
	s_add_u32 s74, s74, 0x100
	s_addc_u32 s75, s75, 0
	s_cmp_gt_u32 s76, 13
	s_mov_b64 s[28:29], s[6:7]
	s_cbranch_scc0 .LBB0_1083
	s_and_b64 vcc, exec, s[36:37]
	s_cbranch_vccz .LBB0_1086
	s_barrier

; #define PG8_STAGE(bufoff, gbase, voff) do { _Pragma("unroll") for (int _i = 0; _i < 2; ++_i) \
;         __builtin_amdgcn_global_load_lds((const unsigned*)((const char*)(gbase) + (voff)[_i]), (PG8_LAS unsigned*)(lds + (bufoff) + ldsw + _i * 8192), 16, 0, 0); } while (0)
; #define PG8_LDA(dst, b, h) do { _Pragma("unroll") for (int m = 0; m < 4; ++m) _Pragma("unroll") for (int k = 0; k < 2; ++k) dst[m][k] = *(const PG8_LAS bf16x8*)(lds + PG8_SA(b, h) + aoff + m * 2048 + k * 1024); } while (0)
; #define PG8_LDB(dst, b, h) do { _Pragma("unroll") for (int n = 0; n < 2; ++n) _Pragma("unroll") for (int k = 0; k < 2; ++k) dst[n][k] = *(const PG8_LAS bf16x8*)(lds + PG8_SB(b, h) + boff + n * 2048 + k * 1024); } while (0)
; #define PG8_MMA(ai, bj, At, Bt) do { __builtin_amdgcn_s_setprio(1); _Pragma("unroll") for (int m = 0; m < 4; ++m) _Pragma("unroll") for (int n = 0; n < 2; ++n) _Pragma("unroll") for (int k = 0; k < 2; ++k) \
;         acc[ai][bj][m][n] = __builtin_amdgcn_mfma_f32_16x16x32_bf16(Bt[n][k], At[m][k], acc[ai][bj][m][n], 0, 0, 0); __builtin_amdgcn_s_setprio(0); } while (0)
; #define PG8_WAIT_V(n) asm volatile("s_waitcnt vmcnt(" #n ")" ::: "memory")
; #define PG8_WAIT_L(n) asm volatile("s_waitcnt lgkmcnt(" #n ")" ::: "memory")
; #define PG8_BAR __builtin_amdgcn_s_barrier()
; #define PG8_SCHED __builtin_amdgcn_sched_barrier(0)
;     ...
;             const bool last = (t == nt - 2);
;             const char* a1 = cA + (size_t)(t + 1) * kstep;
;             const char* a2 = last ? nA : cA + (size_t)(t + 2) * kstep; const char* b2 = last ? nB : cB + (size_t)(t + 2) * kstep;
;             const char* a3 = a2 + kstep; const char* b3 = b2 + kstep;
;             if (last && has_next) S.a_ready(nxt);
;             if constexpr (SP2) {
;             PG8_LDB(B0, 0, 0); PG8_LDB(B1, 0, 1); PG8_SCHED; PG8_LDA(At, 0, 0); PG8_STAGE(PG8_SA(1, 1), a1 + hstepA, voffA);
;             PG8_WAIT_V(8); PG8_WAIT_L(0); PG8_BAR; PG8_MMA(0, 0, At, B0); PG8_MMA(0, 1, At, B1); PG8_BAR; PG8_SCHED;
;             PG8_LDA(At, 0, 1); PG8_STAGE(PG8_SB(0, 0), b2, voffB); PG8_STAGE(PG8_SB(0, 1), b2 + hstepB, voffB); PG8_STAGE(PG8_SA(0, 0), a2, voffA);
;             PG8_WAIT_V(8); PG8_WAIT_L(0); PG8_BAR; PG8_MMA(1, 0, At, B0); PG8_MMA(1, 1, At, B1); PG8_BAR; PG8_SCHED;
.LBB0_1252:
	ds_read_b128 v[128:131], v203
	ds_read_b128 v[132:135], v203 offset:1024
	ds_read_b128 v[136:139], v203 offset:2048
	ds_read_b128 v[140:143], v203 offset:3072
	ds_read_b128 v[144:147], v204
	ds_read_b128 v[148:151], v204 offset:1024
	ds_read_b128 v[152:155], v204 offset:2048
	ds_read_b128 v[156:159], v204 offset:3072
	s_add_u32 s34, s28, 0xfffc0080
	s_addc_u32 s35, s29, -1
	s_cmp_eq_u32 s61, 12
	s_cselect_b32 s41, s25, s35
	s_cselect_b32 s40, s57, s34
	s_cselect_b32 s35, s23, s60
	s_cselect_b32 s34, s58, s59
	v_lshl_add_u64 v[200:201], s[28:29], 0, v[184:185]
	s_add_i32 m0, s39, 0xc000
	ds_read_b128 v[160:163], v205
	ds_read_b128 v[164:167], v205 offset:1024
	ds_read_b128 v[168:171], v205 offset:2048
	ds_read_b128 v[172:175], v205 offset:3072
	ds_read_b128 v[192:195], v205 offset:4096
	ds_read_b128 v[196:199], v205 offset:5120
	ds_read_b128 v[206:209], v205 offset:6144
	ds_read_b128 v[210:213], v205 offset:7168
	global_load_lds_dwordx4 v[200:201], off
	v_lshl_add_u64 v[200:201], s[28:29], 0, v[186:187]
	s_add_i32 m0, s39, 0xe000
	s_nop 0
	global_load_lds_dwordx4 v[200:201], off
	s_waitcnt vmcnt(8)
	s_waitcnt lgkmcnt(0)
	s_barrier
	s_setprio 1
	s_waitcnt lgkmcnt(0)
	v_mfma_f32_16x16x32_bf16 v[124:127], v[128:131], v[160:163], v[124:127]
	v_mfma_f32_16x16x32_bf16 v[120:123], v[136:139], v[160:163], v[120:123]
	v_mfma_f32_16x16x32_bf16 v[108:111], v[128:131], v[168:171], v[108:111]
	v_mfma_f32_16x16x32_bf16 v[104:107], v[136:139], v[168:171], v[104:107]
	v_mfma_f32_16x16x32_bf16 v[92:95], v[128:131], v[192:195], v[92:95]
	v_mfma_f32_16x16x32_bf16 v[88:91], v[136:139], v[192:195], v[88:91]
	v_mfma_f32_16x16x32_bf16 v[76:79], v[128:131], v[206:209], v[76:79]
	v_mfma_f32_16x16x32_bf16 v[72:75], v[136:139], v[206:209], v[72:75]
	v_mfma_f32_16x16x32_bf16 v[124:127], v[132:135], v[164:167], v[124:127]
	v_mfma_f32_16x16x32_bf16 v[120:123], v[140:143], v[164:167], v[120:123]
	v_mfma_f32_16x16x32_bf16 v[108:111], v[132:135], v[172:175], v[108:111]
	v_mfma_f32_16x16x32_bf16 v[104:107], v[140:143], v[172:175], v[104:107]
	v_mfma_f32_16x16x32_bf16 v[92:95], v[132:135], v[196:199], v[92:95]
	v_mfma_f32_16x16x32_bf16 v[88:91], v[140:143], v[196:199], v[88:91]
	v_mfma_f32_16x16x32_bf16 v[76:79], v[132:135], v[210:213], v[76:79]
	v_mfma_f32_16x16x32_bf16 v[72:75], v[140:143], v[210:213], v[72:75]
	s_setprio 0
	s_setprio 1
	v_mfma_f32_16x16x32_bf16 v[116:119], v[144:147], v[160:163], v[116:119]
	v_mfma_f32_16x16x32_bf16 v[112:115], v[152:155], v[160:163], v[112:115]
	v_mfma_f32_16x16x32_bf16 v[100:103], v[144:147], v[168:171], v[100:103]
	v_mfma_f32_16x16x32_bf16 v[96:99], v[152:155], v[168:171], v[96:99]
	v_mfma_f32_16x16x32_bf16 v[84:87], v[144:147], v[192:195], v[84:87]
	v_mfma_f32_16x16x32_bf16 v[80:83], v[152:155], v[192:195], v[80:83]
	v_mfma_f32_16x16x32_bf16 v[68:71], v[144:147], v[206:209], v[68:71]
	v_mfma_f32_16x16x32_bf16 v[64:67], v[152:155], v[206:209], v[64:67]
	v_mfma_f32_16x16x32_bf16 v[116:119], v[148:151], v[164:167], v[116:119]
	v_mfma_f32_16x16x32_bf16 v[112:115], v[156:159], v[164:167], v[112:115]
	v_mfma_f32_16x16x32_bf16 v[100:103], v[148:151], v[172:175], v[100:103]
	v_mfma_f32_16x16x32_bf16 v[96:99], v[156:159], v[172:175], v[96:99]
	v_mfma_f32_16x16x32_bf16 v[84:87], v[148:151], v[196:199], v[84:87]
	v_mfma_f32_16x16x32_bf16 v[80:83], v[156:159], v[196:199], v[80:83]
	v_mfma_f32_16x16x32_bf16 v[68:71], v[148:151], v[210:213], v[68:71]
	v_mfma_f32_16x16x32_bf16 v[64:67], v[156:159], v[210:213], v[64:67]
	s_setprio 0
	s_barrier
	s_cmp_lg_u32 s98, 0
	s_cbranch_scc0 .Llp_25
	s_setprio 2
.Llp_25:
	s_add_i32 s48, s55, s43
	v_lshl_add_u64 v[200:201], s[34:35], 0, v[178:179]
	s_mov_b32 m0, s48
	ds_read_b128 v[160:163], v205 offset:16384
	ds_read_b128 v[164:167], v205 offset:17408
	ds_read_b128 v[168:171], v205 offset:18432
	ds_read_b128 v[172:175], v205 offset:19456
	ds_read_b128 v[192:195], v205 offset:20480
	ds_read_b128 v[196:199], v205 offset:21504
	ds_read_b128 v[206:209], v205 offset:22528
	ds_read_b128 v[210:213], v205 offset:23552
	global_load_lds_dwordx4 v[200:201], off
	s_add_i32 m0, s48, 0x2000
	s_add_u32 s48, s34, 0x40000
	v_lshl_add_u64 v[214:215], s[34:35], 0, v[182:183]
	s_addc_u32 s49, s35, 0
	s_add_i32 s62, s56, s43
	global_load_lds_dwordx4 v[214:215], off
	v_lshl_add_u64 v[216:217], s[48:49], 0, v[178:179]
	s_mov_b32 m0, s62
	v_lshl_add_u64 v[218:219], s[40:41], 0, v[180:181]
	global_load_lds_dwordx4 v[216:217], off
	v_lshl_add_u64 v[216:217], s[48:49], 0, v[182:183]
	s_add_i32 m0, s62, 0x2000
	s_nop 0
	global_load_lds_dwordx4 v[216:217], off
	v_lshl_add_u64 v[216:217], s[40:41], 0, v[176:177]
	s_mov_b32 m0, s39
	s_nop 0
	global_load_lds_dwordx4 v[216:217], off
	s_mov_b32 m0, s45
	s_nop 0
	global_load_lds_dwordx4 v[218:219], off
	s_waitcnt vmcnt(8)
	s_waitcnt lgkmcnt(0)
	s_barrier
; #define PG8_STAGE(bufoff, gbase, voff) do { _Pragma("unroll") for (int _i = 0; _i < 2; ++_i) \
;         __builtin_amdgcn_global_load_lds((const unsigned*)((const char*)(gbase) + (voff)[_i]), (PG8_LAS unsigned*)(lds + (bufoff) + ldsw + _i * 8192), 16, 0, 0); } while (0)
; #define PG8_LDA(dst, b, h) do { _Pragma("unroll") for (int m = 0; m < 4; ++m) _Pragma("unroll") for (int k = 0; k < 2; ++k) dst[m][k] = *(const PG8_LAS bf16x8*)(lds + PG8_SA(b, h) + aoff + m * 2048 + k * 1024); } while (0)
; #define PG8_LDB(dst, b, h) do { _Pragma("unroll") for (int n = 0; n < 2; ++n) _Pragma("unroll") for (int k = 0; k < 2; ++k) dst[n][k] = *(const PG8_LAS bf16x8*)(lds + PG8_SB(b, h) + boff + n * 2048 + k * 1024); } while (0)
; #define PG8_MMA(ai, bj, At, Bt) do { __builtin_amdgcn_s_setprio(1); _Pragma("unroll") for (int m = 0; m < 4; ++m) _Pragma("unroll") for (int n = 0; n < 2; ++n) _Pragma("unroll") for (int k = 0; k < 2; ++k) \
;         acc[ai][bj][m][n] = __builtin_amdgcn_mfma_f32_16x16x32_bf16(Bt[n][k], At[m][k], acc[ai][bj][m][n], 0, 0, 0); __builtin_amdgcn_s_setprio(0); } while (0)
; #define PG8_WAIT_V(n) asm volatile("s_waitcnt vmcnt(" #n ")" ::: "memory")
; #define PG8_WAIT_L(n) asm volatile("s_waitcnt lgkmcnt(" #n ")" ::: "memory")
; #define PG8_BAR __builtin_amdgcn_s_barrier()
; #define PG8_SCHED __builtin_amdgcn_sched_barrier(0)
;     ...
;             PG8_WAIT_V(8); PG8_WAIT_L(0); PG8_BAR; PG8_MMA(1, 0, At, B0); PG8_MMA(1, 1, At, B1); PG8_BAR; PG8_SCHED;
;             PG8_LDB(B0, 1, 0); PG8_LDB(B1, 1, 1); PG8_SCHED; PG8_LDA(At, 1, 0); PG8_STAGE(PG8_SA(0, 1), a2 + hstepA, voffA);
;             PG8_WAIT_V(8); PG8_WAIT_L(0); PG8_BAR; PG8_MMA(0, 0, At, B0); PG8_MMA(0, 1, At, B1); PG8_BAR; PG8_SCHED;
	s_setprio 1
	s_waitcnt lgkmcnt(0)
	v_mfma_f32_16x16x32_bf16 v[60:63], v[128:131], v[160:163], v[60:63]
	v_mfma_f32_16x16x32_bf16 v[56:59], v[136:139], v[160:163], v[56:59]
	v_mfma_f32_16x16x32_bf16 v[44:47], v[128:131], v[168:171], v[44:47]
	v_mfma_f32_16x16x32_bf16 v[40:43], v[136:139], v[168:171], v[40:43]
	v_mfma_f32_16x16x32_bf16 v[28:31], v[128:131], v[192:195], v[28:31]
	v_mfma_f32_16x16x32_bf16 v[24:27], v[136:139], v[192:195], v[24:27]
	v_mfma_f32_16x16x32_bf16 v[12:15], v[128:131], v[206:209], v[12:15]
	v_mfma_f32_16x16x32_bf16 v[8:11], v[136:139], v[206:209], v[8:11]
	v_mfma_f32_16x16x32_bf16 v[60:63], v[132:135], v[164:167], v[60:63]
	v_mfma_f32_16x16x32_bf16 v[56:59], v[140:143], v[164:167], v[56:59]
	v_mfma_f32_16x16x32_bf16 v[44:47], v[132:135], v[172:175], v[44:47]
	v_mfma_f32_16x16x32_bf16 v[40:43], v[140:143], v[172:175], v[40:43]
	v_mfma_f32_16x16x32_bf16 v[28:31], v[132:135], v[196:199], v[28:31]
	v_mfma_f32_16x16x32_bf16 v[24:27], v[140:143], v[196:199], v[24:27]
	v_mfma_f32_16x16x32_bf16 v[12:15], v[132:135], v[210:213], v[12:15]
	v_mfma_f32_16x16x32_bf16 v[8:11], v[140:143], v[210:213], v[8:11]
	s_setprio 0
	s_setprio 1
	v_mfma_f32_16x16x32_bf16 v[52:55], v[144:147], v[160:163], v[52:55]
	v_mfma_f32_16x16x32_bf16 v[48:51], v[152:155], v[160:163], v[48:51]
	v_mfma_f32_16x16x32_bf16 v[36:39], v[144:147], v[168:171], v[36:39]
	v_mfma_f32_16x16x32_bf16 v[32:35], v[152:155], v[168:171], v[32:35]
	v_mfma_f32_16x16x32_bf16 v[20:23], v[144:147], v[192:195], v[20:23]
	v_mfma_f32_16x16x32_bf16 v[16:19], v[152:155], v[192:195], v[16:19]
	v_mfma_f32_16x16x32_bf16 v[4:7], v[144:147], v[206:209], v[4:7]
	v_mfma_f32_16x16x32_bf16 v[0:3], v[152:155], v[206:209], v[0:3]
	v_mfma_f32_16x16x32_bf16 v[52:55], v[148:151], v[164:167], v[52:55]
	v_mfma_f32_16x16x32_bf16 v[48:51], v[156:159], v[164:167], v[48:51]
	v_mfma_f32_16x16x32_bf16 v[36:39], v[148:151], v[172:175], v[36:39]
	v_mfma_f32_16x16x32_bf16 v[32:35], v[156:159], v[172:175], v[32:35]
	v_mfma_f32_16x16x32_bf16 v[20:23], v[148:151], v[196:199], v[20:23]
	v_mfma_f32_16x16x32_bf16 v[16:19], v[156:159], v[196:199], v[16:19]
	v_mfma_f32_16x16x32_bf16 v[4:7], v[148:151], v[210:213], v[4:7]
	v_mfma_f32_16x16x32_bf16 v[0:3], v[156:159], v[210:213], v[0:3]
	s_setprio 0
	s_barrier
	s_cmp_lg_u32 s98, 0
	s_cbranch_scc0 .Llp_26
	s_setprio 2
.Llp_26:
	s_add_i32 s48, 0, 0x18000
	s_add_i32 s49, 0, 0x1c000
	v_add_u32_e32 v140, s48, v202
	v_add_u32_e32 v156, s49, v202
	ds_read_b128 v[128:131], v140
	ds_read_b128 v[132:135], v140 offset:1024
	ds_read_b128 v[136:139], v140 offset:2048
	ds_read_b128 v[140:143], v140 offset:3072
	ds_read_b128 v[144:147], v156
	ds_read_b128 v[148:151], v156 offset:1024
	ds_read_b128 v[152:155], v156 offset:2048
	ds_read_b128 v[156:159], v156 offset:3072
	s_add_u32 s40, s40, 0x40000
	s_addc_u32 s41, s41, 0
	s_mov_b32 m0, s46
	v_lshl_add_u64 v[220:221], s[40:41], 0, v[176:177]
	ds_read_b128 v[160:163], v205 offset:32768
	ds_read_b128 v[164:167], v205 offset:33792
	ds_read_b128 v[168:171], v205 offset:34816
	ds_read_b128 v[172:175], v205 offset:35840
	ds_read_b128 v[192:195], v205 offset:36864
	ds_read_b128 v[196:199], v205 offset:37888
	ds_read_b128 v[206:209], v205 offset:38912
	ds_read_b128 v[210:213], v205 offset:39936
	global_load_lds_dwordx4 v[220:221], off
	v_lshl_add_u64 v[220:221], s[40:41], 0, v[180:181]
	s_mov_b32 m0, s47
	s_nop 0
	global_load_lds_dwordx4 v[220:221], off
	s_waitcnt vmcnt(8)
	s_waitcnt lgkmcnt(0)
	s_barrier
	s_setprio 1
	s_waitcnt lgkmcnt(0)
	v_mfma_f32_16x16x32_bf16 v[124:127], v[128:131], v[160:163], v[124:127]
	v_mfma_f32_16x16x32_bf16 v[120:123], v[136:139], v[160:163], v[120:123]
	v_mfma_f32_16x16x32_bf16 v[108:111], v[128:131], v[168:171], v[108:111]
	v_mfma_f32_16x16x32_bf16 v[104:107], v[136:139], v[168:171], v[104:107]
	v_mfma_f32_16x16x32_bf16 v[92:95], v[128:131], v[192:195], v[92:95]
	v_mfma_f32_16x16x32_bf16 v[88:91], v[136:139], v[192:195], v[88:91]
	v_mfma_f32_16x16x32_bf16 v[76:79], v[128:131], v[206:209], v[76:79]
	v_mfma_f32_16x16x32_bf16 v[72:75], v[136:139], v[206:209], v[72:75]
	v_mfma_f32_16x16x32_bf16 v[124:127], v[132:135], v[164:167], v[124:127]
	v_mfma_f32_16x16x32_bf16 v[120:123], v[140:143], v[164:167], v[120:123]
	v_mfma_f32_16x16x32_bf16 v[108:111], v[132:135], v[172:175], v[108:111]
	v_mfma_f32_16x16x32_bf16 v[104:107], v[140:143], v[172:175], v[104:107]
	v_mfma_f32_16x16x32_bf16 v[92:95], v[132:135], v[196:199], v[92:95]
	v_mfma_f32_16x16x32_bf16 v[88:91], v[140:143], v[196:199], v[88:91]
	v_mfma_f32_16x16x32_bf16 v[76:79], v[132:135], v[210:213], v[76:79]
	v_mfma_f32_16x16x32_bf16 v[72:75], v[140:143], v[210:213], v[72:75]
	s_setprio 0
	s_setprio 1
	v_mfma_f32_16x16x32_bf16 v[116:119], v[144:147], v[160:163], v[116:119]
	v_mfma_f32_16x16x32_bf16 v[112:115], v[152:155], v[160:163], v[112:115]
	v_mfma_f32_16x16x32_bf16 v[100:103], v[144:147], v[168:171], v[100:103]
	v_mfma_f32_16x16x32_bf16 v[96:99], v[152:155], v[168:171], v[96:99]
	v_mfma_f32_16x16x32_bf16 v[84:87], v[144:147], v[192:195], v[84:87]
	v_mfma_f32_16x16x32_bf16 v[80:83], v[152:155], v[192:195], v[80:83]
	v_mfma_f32_16x16x32_bf16 v[68:71], v[144:147], v[206:209], v[68:71]
	v_mfma_f32_16x16x32_bf16 v[64:67], v[152:155], v[206:209], v[64:67]
	v_mfma_f32_16x16x32_bf16 v[116:119], v[148:151], v[164:167], v[116:119]
	v_mfma_f32_16x16x32_bf16 v[112:115], v[156:159], v[164:167], v[112:115]
	v_mfma_f32_16x16x32_bf16 v[100:103], v[148:151], v[172:175], v[100:103]
	v_mfma_f32_16x16x32_bf16 v[96:99], v[156:159], v[172:175], v[96:99]
	v_mfma_f32_16x16x32_bf16 v[84:87], v[148:151], v[196:199], v[84:87]
	v_mfma_f32_16x16x32_bf16 v[80:83], v[156:159], v[196:199], v[80:83]
	v_mfma_f32_16x16x32_bf16 v[68:71], v[148:151], v[210:213], v[68:71]
	v_mfma_f32_16x16x32_bf16 v[64:67], v[156:159], v[210:213], v[64:67]
	s_setprio 0
	s_barrier
	s_cmp_lg_u32 s98, 0
	s_cbranch_scc0 .Llp_27
	s_setprio 2
; #define PG8_STAGE(bufoff, gbase, voff) do { _Pragma("unroll") for (int _i = 0; _i < 2; ++_i) \
;         __builtin_amdgcn_global_load_lds((const unsigned*)((const char*)(gbase) + (voff)[_i]), (PG8_LAS unsigned*)(lds + (bufoff) + ldsw + _i * 8192), 16, 0, 0); } while (0)
; #define PG8_LDA(dst, b, h) do { _Pragma("unroll") for (int m = 0; m < 4; ++m) _Pragma("unroll") for (int k = 0; k < 2; ++k) dst[m][k] = *(const PG8_LAS bf16x8*)(lds + PG8_SA(b, h) + aoff + m * 2048 + k * 1024); } while (0)
; #define PG8_MMA(ai, bj, At, Bt) do { __builtin_amdgcn_s_setprio(1); _Pragma("unroll") for (int m = 0; m < 4; ++m) _Pragma("unroll") for (int n = 0; n < 2; ++n) _Pragma("unroll") for (int k = 0; k < 2; ++k) \
;         acc[ai][bj][m][n] = __builtin_amdgcn_mfma_f32_16x16x32_bf16(Bt[n][k], At[m][k], acc[ai][bj][m][n], 0, 0, 0); __builtin_amdgcn_s_setprio(0); } while (0)
; #define PG8_WAIT_V(n) asm volatile("s_waitcnt vmcnt(" #n ")" ::: "memory")
; #define PG8_WAIT_L(n) asm volatile("s_waitcnt lgkmcnt(" #n ")" ::: "memory")
; #define PG8_BAR __builtin_amdgcn_s_barrier()
; #define PG8_SCHED __builtin_amdgcn_sched_barrier(0)
;     ...
;             PG8_LDA(At, 1, 1); PG8_STAGE(PG8_SB(1, 0), b3, voffB); PG8_STAGE(PG8_SB(1, 1), b3 + hstepB, voffB); PG8_STAGE(PG8_SA(1, 0), a3, voffA);
;             PG8_WAIT_V(8); PG8_WAIT_L(0); PG8_BAR; PG8_MMA(1, 0, At, B0); PG8_MMA(1, 1, At, B1); PG8_BAR; PG8_SCHED;
.Llp_27:
	s_add_i32 s40, s48, s43
	v_lshl_add_u64 v[200:201], v[200:201], 0, s[18:19]
	s_mov_b32 m0, s40
	ds_read_b128 v[160:163], v205 offset:49152
	ds_read_b128 v[164:167], v205 offset:50176
	ds_read_b128 v[168:171], v205 offset:51200
	ds_read_b128 v[172:175], v205 offset:52224
	ds_read_b128 v[192:195], v205 offset:53248
	ds_read_b128 v[196:199], v205 offset:54272
	ds_read_b128 v[206:209], v205 offset:55296
	ds_read_b128 v[210:213], v205 offset:56320
	global_load_lds_dwordx4 v[200:201], off
	s_add_i32 m0, s40, 0x2000
	s_add_u32 s34, s34, 0x40080
	v_lshl_add_u64 v[200:201], v[214:215], 0, s[18:19]
	s_addc_u32 s35, s35, 0
	s_add_i32 s40, s49, s43
	global_load_lds_dwordx4 v[200:201], off
	v_lshl_add_u64 v[200:201], s[34:35], 0, v[178:179]
	s_mov_b32 m0, s40
	s_nop 0
	global_load_lds_dwordx4 v[200:201], off
	v_lshl_add_u64 v[200:201], s[34:35], 0, v[182:183]
	s_add_i32 m0, s40, 0x2000
	s_nop 0
	global_load_lds_dwordx4 v[200:201], off
	v_lshl_add_u64 v[200:201], v[216:217], 0, s[18:19]
	s_mov_b32 m0, s53
	s_nop 0
	global_load_lds_dwordx4 v[200:201], off
	v_lshl_add_u64 v[200:201], v[218:219], 0, s[18:19]
	s_mov_b32 m0, s54
	s_nop 0
	global_load_lds_dwordx4 v[200:201], off
	s_waitcnt vmcnt(8)
	s_waitcnt lgkmcnt(0)
	s_barrier
	s_setprio 1
	s_waitcnt lgkmcnt(0)
	v_mfma_f32_16x16x32_bf16 v[60:63], v[128:131], v[160:163], v[60:63]
	v_mfma_f32_16x16x32_bf16 v[56:59], v[136:139], v[160:163], v[56:59]
	v_mfma_f32_16x16x32_bf16 v[44:47], v[128:131], v[168:171], v[44:47]
	v_mfma_f32_16x16x32_bf16 v[40:43], v[136:139], v[168:171], v[40:43]
	v_mfma_f32_16x16x32_bf16 v[28:31], v[128:131], v[192:195], v[28:31]
	v_mfma_f32_16x16x32_bf16 v[24:27], v[136:139], v[192:195], v[24:27]
	v_mfma_f32_16x16x32_bf16 v[12:15], v[128:131], v[206:209], v[12:15]
	v_mfma_f32_16x16x32_bf16 v[8:11], v[136:139], v[206:209], v[8:11]
	v_mfma_f32_16x16x32_bf16 v[60:63], v[132:135], v[164:167], v[60:63]
	v_mfma_f32_16x16x32_bf16 v[56:59], v[140:143], v[164:167], v[56:59]
	v_mfma_f32_16x16x32_bf16 v[44:47], v[132:135], v[172:175], v[44:47]
	v_mfma_f32_16x16x32_bf16 v[40:43], v[140:143], v[172:175], v[40:43]
	v_mfma_f32_16x16x32_bf16 v[28:31], v[132:135], v[196:199], v[28:31]
	v_mfma_f32_16x16x32_bf16 v[24:27], v[140:143], v[196:199], v[24:27]
	v_mfma_f32_16x16x32_bf16 v[12:15], v[132:135], v[210:213], v[12:15]
	v_mfma_f32_16x16x32_bf16 v[8:11], v[140:143], v[210:213], v[8:11]
	s_setprio 0
	s_setprio 1
	v_mfma_f32_16x16x32_bf16 v[52:55], v[144:147], v[160:163], v[52:55]
	v_mfma_f32_16x16x32_bf16 v[48:51], v[152:155], v[160:163], v[48:51]
	v_mfma_f32_16x16x32_bf16 v[36:39], v[144:147], v[168:171], v[36:39]
	v_mfma_f32_16x16x32_bf16 v[32:35], v[152:155], v[168:171], v[32:35]
	v_mfma_f32_16x16x32_bf16 v[20:23], v[144:147], v[192:195], v[20:23]
	v_mfma_f32_16x16x32_bf16 v[16:19], v[152:155], v[192:195], v[16:19]
	v_mfma_f32_16x16x32_bf16 v[4:7], v[144:147], v[206:209], v[4:7]
	v_mfma_f32_16x16x32_bf16 v[0:3], v[152:155], v[206:209], v[0:3]
	v_mfma_f32_16x16x32_bf16 v[52:55], v[148:151], v[164:167], v[52:55]
	v_mfma_f32_16x16x32_bf16 v[48:51], v[156:159], v[164:167], v[48:51]
	v_mfma_f32_16x16x32_bf16 v[36:39], v[148:151], v[172:175], v[36:39]
	v_mfma_f32_16x16x32_bf16 v[32:35], v[156:159], v[172:175], v[32:35]
	v_mfma_f32_16x16x32_bf16 v[20:23], v[148:151], v[196:199], v[20:23]
	v_mfma_f32_16x16x32_bf16 v[16:19], v[156:159], v[196:199], v[16:19]
	v_mfma_f32_16x16x32_bf16 v[4:7], v[148:151], v[210:213], v[4:7]
	v_mfma_f32_16x16x32_bf16 v[0:3], v[156:159], v[210:213], v[0:3]
	s_setprio 0
	s_barrier
	s_cmp_lg_u32 s98, 0
	s_cbranch_scc0 .Llp_28
	s_setprio 2
.Llp_28:
	s_add_i32 s61, s61, 2
	s_add_u32 s28, s28, 0x100
	s_addc_u32 s29, s29, 0
	s_add_u32 s59, s59, 0x100
	s_addc_u32 s60, s60, 0
	s_cmp_gt_u32 s61, 13
	s_cbranch_scc0 .LBB0_1252
	s_and_b64 vcc, exec, s[20:21]
	s_cbranch_vccz .LBB0_1255
	s_barrier

; #define PG8_STAGE(bufoff, gbase, voff) do { _Pragma("unroll") for (int _i = 0; _i < 2; ++_i) \
;         __builtin_amdgcn_global_load_lds((const unsigned*)((const char*)(gbase) + (voff)[_i]), (PG8_LAS unsigned*)(lds + (bufoff) + ldsw + _i * 8192), 16, 0, 0); } while (0)
; #define PG8_LDA(dst, b, h) do { _Pragma("unroll") for (int m = 0; m < 4; ++m) _Pragma("unroll") for (int k = 0; k < 2; ++k) dst[m][k] = *(const PG8_LAS bf16x8*)(lds + PG8_SA(b, h) + aoff + m * 2048 + k * 1024); } while (0)
; #define PG8_LDB(dst, b, h) do { _Pragma("unroll") for (int n = 0; n < 2; ++n) _Pragma("unroll") for (int k = 0; k < 2; ++k) dst[n][k] = *(const PG8_LAS bf16x8*)(lds + PG8_SB(b, h) + boff + n * 2048 + k * 1024); } while (0)
; #define PG8_MMA(ai, bj, At, Bt) do { __builtin_amdgcn_s_setprio(1); _Pragma("unroll") for (int m = 0; m < 4; ++m) _Pragma("unroll") for (int n = 0; n < 2; ++n) _Pragma("unroll") for (int k = 0; k < 2; ++k) \
;         acc[ai][bj][m][n] = __builtin_amdgcn_mfma_f32_16x16x32_bf16(Bt[n][k], At[m][k], acc[ai][bj][m][n], 0, 0, 0); __builtin_amdgcn_s_setprio(0); } while (0)
; #define PG8_WAIT_V(n) asm volatile("s_waitcnt vmcnt(" #n ")" ::: "memory")
; #define PG8_WAIT_L(n) asm volatile("s_waitcnt lgkmcnt(" #n ")" ::: "memory")
; #define PG8_BAR __builtin_amdgcn_s_barrier()
; #define PG8_SCHED __builtin_amdgcn_sched_barrier(0)
;     ...
;             const bool last = (t == nt - 2);
;             const char* a1 = cA + (size_t)(t + 1) * kstep;
;             const char* a2 = last ? nA : cA + (size_t)(t + 2) * kstep; const char* b2 = last ? nB : cB + (size_t)(t + 2) * kstep;
;             const char* a3 = a2 + kstep; const char* b3 = b2 + kstep;
;             if (last && has_next) S.a_ready(nxt);
;             if constexpr (SP2) {
;             PG8_LDB(B0, 0, 0); PG8_LDB(B1, 0, 1); PG8_SCHED; PG8_LDA(At, 0, 0); PG8_STAGE(PG8_SA(1, 1), a1 + hstepA, voffA);
;             PG8_WAIT_V(8); PG8_WAIT_L(0); PG8_BAR; PG8_MMA(0, 0, At, B0); PG8_MMA(0, 1, At, B1); PG8_BAR; PG8_SCHED;
;             PG8_LDA(At, 0, 1); PG8_STAGE(PG8_SB(0, 0), b2, voffB); PG8_STAGE(PG8_SB(0, 1), b2 + hstepB, voffB); PG8_STAGE(PG8_SA(0, 0), a2, voffA);
;             PG8_WAIT_V(8); PG8_WAIT_L(0); PG8_BAR; PG8_MMA(1, 0, At, B0); PG8_MMA(1, 1, At, B1); PG8_BAR; PG8_SCHED;
.LBB0_1341:
	ds_read_b128 v[144:147], v151
	ds_read_b128 v[160:163], v151 offset:1024
	ds_read_b128 v[164:167], v151 offset:2048
	ds_read_b128 v[168:171], v151 offset:3072
	ds_read_b128 v[172:175], v153
	ds_read_b128 v[176:179], v153 offset:1024
	ds_read_b128 v[180:183], v153 offset:2048
	ds_read_b128 v[184:187], v153 offset:3072
	s_add_u32 s36, s34, 0xfffc0080
	s_addc_u32 s37, s35, -1
	s_cmp_eq_u32 s62, 12
	s_cselect_b32 s39, s23, s37
	s_cselect_b32 s38, s58, s36
	s_cselect_b32 s37, s21, s61
	s_cselect_b32 s36, s59, s60
	v_lshl_add_u64 v[154:155], s[34:35], 0, v[136:137]
	s_add_i32 m0, s29, 0xc000
	ds_read_b128 v[188:191], v157
	ds_read_b128 v[192:195], v157 offset:1024
	ds_read_b128 v[196:199], v157 offset:2048
	ds_read_b128 v[200:203], v157 offset:3072
	ds_read_b128 v[204:207], v157 offset:4096
	ds_read_b128 v[208:211], v157 offset:5120
	ds_read_b128 v[212:215], v157 offset:6144
	ds_read_b128 v[216:219], v157 offset:7168
	global_load_lds_dwordx4 v[154:155], off
	v_lshl_add_u64 v[154:155], s[34:35], 0, v[138:139]
	s_add_i32 m0, s29, 0xe000
	s_nop 0
	global_load_lds_dwordx4 v[154:155], off
	s_waitcnt vmcnt(8)
	s_waitcnt lgkmcnt(0)
	s_barrier
	s_setprio 1
	s_waitcnt lgkmcnt(0)
	v_mfma_f32_16x16x32_bf16 v[124:127], v[144:147], v[188:191], v[124:127]
	v_mfma_f32_16x16x32_bf16 v[120:123], v[164:167], v[188:191], v[120:123]
	v_mfma_f32_16x16x32_bf16 v[108:111], v[144:147], v[196:199], v[108:111]
	v_mfma_f32_16x16x32_bf16 v[104:107], v[164:167], v[196:199], v[104:107]
	v_mfma_f32_16x16x32_bf16 v[92:95], v[144:147], v[204:207], v[92:95]
	v_mfma_f32_16x16x32_bf16 v[88:91], v[164:167], v[204:207], v[88:91]
	v_mfma_f32_16x16x32_bf16 v[76:79], v[144:147], v[212:215], v[76:79]
	v_mfma_f32_16x16x32_bf16 v[72:75], v[164:167], v[212:215], v[72:75]
	v_mfma_f32_16x16x32_bf16 v[124:127], v[160:163], v[192:195], v[124:127]
	v_mfma_f32_16x16x32_bf16 v[120:123], v[168:171], v[192:195], v[120:123]
	v_mfma_f32_16x16x32_bf16 v[108:111], v[160:163], v[200:203], v[108:111]
	v_mfma_f32_16x16x32_bf16 v[104:107], v[168:171], v[200:203], v[104:107]
	v_mfma_f32_16x16x32_bf16 v[92:95], v[160:163], v[208:211], v[92:95]
	v_mfma_f32_16x16x32_bf16 v[88:91], v[168:171], v[208:211], v[88:91]
	v_mfma_f32_16x16x32_bf16 v[76:79], v[160:163], v[216:219], v[76:79]
	v_mfma_f32_16x16x32_bf16 v[72:75], v[168:171], v[216:219], v[72:75]
	s_setprio 0
	s_setprio 1
	v_mfma_f32_16x16x32_bf16 v[116:119], v[172:175], v[188:191], v[116:119]
	v_mfma_f32_16x16x32_bf16 v[112:115], v[180:183], v[188:191], v[112:115]
	v_mfma_f32_16x16x32_bf16 v[100:103], v[172:175], v[196:199], v[100:103]
	v_mfma_f32_16x16x32_bf16 v[96:99], v[180:183], v[196:199], v[96:99]
	v_mfma_f32_16x16x32_bf16 v[84:87], v[172:175], v[204:207], v[84:87]
	v_mfma_f32_16x16x32_bf16 v[80:83], v[180:183], v[204:207], v[80:83]
	v_mfma_f32_16x16x32_bf16 v[68:71], v[172:175], v[212:215], v[68:71]
	v_mfma_f32_16x16x32_bf16 v[64:67], v[180:183], v[212:215], v[64:67]
	v_mfma_f32_16x16x32_bf16 v[116:119], v[176:179], v[192:195], v[116:119]
	v_mfma_f32_16x16x32_bf16 v[112:115], v[184:187], v[192:195], v[112:115]
	v_mfma_f32_16x16x32_bf16 v[100:103], v[176:179], v[200:203], v[100:103]
	v_mfma_f32_16x16x32_bf16 v[96:99], v[184:187], v[200:203], v[96:99]
	v_mfma_f32_16x16x32_bf16 v[84:87], v[176:179], v[208:211], v[84:87]
	v_mfma_f32_16x16x32_bf16 v[80:83], v[184:187], v[208:211], v[80:83]
	v_mfma_f32_16x16x32_bf16 v[68:71], v[176:179], v[216:219], v[68:71]
	v_mfma_f32_16x16x32_bf16 v[64:67], v[184:187], v[216:219], v[64:67]
	s_setprio 0
	s_barrier
	s_cmp_lg_u32 s98, 0
	s_cbranch_scc0 .Llp_29
	s_setprio 2
.Llp_29:
	s_add_i32 s48, s54, s43
	v_lshl_add_u64 v[154:155], s[36:37], 0, v[132:133]
	s_mov_b32 m0, s48
	ds_read_b128 v[188:191], v157 offset:16384
	ds_read_b128 v[192:195], v157 offset:17408
	ds_read_b128 v[196:199], v157 offset:18432
	ds_read_b128 v[200:203], v157 offset:19456
	ds_read_b128 v[204:207], v157 offset:20480
	ds_read_b128 v[208:211], v157 offset:21504
	ds_read_b128 v[212:215], v157 offset:22528
	ds_read_b128 v[216:219], v157 offset:23552
	global_load_lds_dwordx4 v[154:155], off
	s_add_i32 m0, s48, 0x2000
	s_add_u32 s48, s36, 0x40000
	v_lshl_add_u64 v[220:221], s[36:37], 0, v[128:129]
	s_addc_u32 s49, s37, 0
	s_add_i32 s63, s55, s43
	global_load_lds_dwordx4 v[220:221], off
	v_lshl_add_u64 v[222:223], s[48:49], 0, v[132:133]
	s_mov_b32 m0, s63
	v_lshl_add_u64 v[224:225], s[38:39], 0, v[130:131]
	global_load_lds_dwordx4 v[222:223], off
	v_lshl_add_u64 v[222:223], s[48:49], 0, v[128:129]
	s_add_i32 m0, s63, 0x2000
	s_nop 0
	global_load_lds_dwordx4 v[222:223], off
	v_lshl_add_u64 v[222:223], s[38:39], 0, v[134:135]
	s_mov_b32 m0, s29
	s_nop 0
	global_load_lds_dwordx4 v[222:223], off
	s_mov_b32 m0, s44
	s_nop 0
	global_load_lds_dwordx4 v[224:225], off
	s_waitcnt vmcnt(8)
	s_waitcnt lgkmcnt(0)
	s_barrier
; #define PG8_STAGE(bufoff, gbase, voff) do { _Pragma("unroll") for (int _i = 0; _i < 2; ++_i) \
;         __builtin_amdgcn_global_load_lds((const unsigned*)((const char*)(gbase) + (voff)[_i]), (PG8_LAS unsigned*)(lds + (bufoff) + ldsw + _i * 8192), 16, 0, 0); } while (0)
; #define PG8_LDA(dst, b, h) do { _Pragma("unroll") for (int m = 0; m < 4; ++m) _Pragma("unroll") for (int k = 0; k < 2; ++k) dst[m][k] = *(const PG8_LAS bf16x8*)(lds + PG8_SA(b, h) + aoff + m * 2048 + k * 1024); } while (0)
; #define PG8_LDB(dst, b, h) do { _Pragma("unroll") for (int n = 0; n < 2; ++n) _Pragma("unroll") for (int k = 0; k < 2; ++k) dst[n][k] = *(const PG8_LAS bf16x8*)(lds + PG8_SB(b, h) + boff + n * 2048 + k * 1024); } while (0)
; #define PG8_MMA(ai, bj, At, Bt) do { __builtin_amdgcn_s_setprio(1); _Pragma("unroll") for (int m = 0; m < 4; ++m) _Pragma("unroll") for (int n = 0; n < 2; ++n) _Pragma("unroll") for (int k = 0; k < 2; ++k) \
;         acc[ai][bj][m][n] = __builtin_amdgcn_mfma_f32_16x16x32_bf16(Bt[n][k], At[m][k], acc[ai][bj][m][n], 0, 0, 0); __builtin_amdgcn_s_setprio(0); } while (0)
; #define PG8_WAIT_V(n) asm volatile("s_waitcnt vmcnt(" #n ")" ::: "memory")
; #define PG8_WAIT_L(n) asm volatile("s_waitcnt lgkmcnt(" #n ")" ::: "memory")
; #define PG8_BAR __builtin_amdgcn_s_barrier()
; #define PG8_SCHED __builtin_amdgcn_sched_barrier(0)
;     ...
;             PG8_WAIT_V(8); PG8_WAIT_L(0); PG8_BAR; PG8_MMA(1, 0, At, B0); PG8_MMA(1, 1, At, B1); PG8_BAR; PG8_SCHED;
;             PG8_LDB(B0, 1, 0); PG8_LDB(B1, 1, 1); PG8_SCHED; PG8_LDA(At, 1, 0); PG8_STAGE(PG8_SA(0, 1), a2 + hstepA, voffA);
;             PG8_WAIT_V(8); PG8_WAIT_L(0); PG8_BAR; PG8_MMA(0, 0, At, B0); PG8_MMA(0, 1, At, B1); PG8_BAR; PG8_SCHED;
	s_setprio 1
	s_waitcnt lgkmcnt(0)
	v_mfma_f32_16x16x32_bf16 v[60:63], v[144:147], v[188:191], v[60:63]
	v_mfma_f32_16x16x32_bf16 v[56:59], v[164:167], v[188:191], v[56:59]
	v_mfma_f32_16x16x32_bf16 v[44:47], v[144:147], v[196:199], v[44:47]
	v_mfma_f32_16x16x32_bf16 v[40:43], v[164:167], v[196:199], v[40:43]
	v_mfma_f32_16x16x32_bf16 v[28:31], v[144:147], v[204:207], v[28:31]
	v_mfma_f32_16x16x32_bf16 v[24:27], v[164:167], v[204:207], v[24:27]
	v_mfma_f32_16x16x32_bf16 v[12:15], v[144:147], v[212:215], v[12:15]
	v_mfma_f32_16x16x32_bf16 v[8:11], v[164:167], v[212:215], v[8:11]
	v_mfma_f32_16x16x32_bf16 v[60:63], v[160:163], v[192:195], v[60:63]
	v_mfma_f32_16x16x32_bf16 v[56:59], v[168:171], v[192:195], v[56:59]
	v_mfma_f32_16x16x32_bf16 v[44:47], v[160:163], v[200:203], v[44:47]
	v_mfma_f32_16x16x32_bf16 v[40:43], v[168:171], v[200:203], v[40:43]
	v_mfma_f32_16x16x32_bf16 v[28:31], v[160:163], v[208:211], v[28:31]
	v_mfma_f32_16x16x32_bf16 v[24:27], v[168:171], v[208:211], v[24:27]
	v_mfma_f32_16x16x32_bf16 v[12:15], v[160:163], v[216:219], v[12:15]
	v_mfma_f32_16x16x32_bf16 v[8:11], v[168:171], v[216:219], v[8:11]
	s_setprio 0
	s_setprio 1
	v_mfma_f32_16x16x32_bf16 v[52:55], v[172:175], v[188:191], v[52:55]
	v_mfma_f32_16x16x32_bf16 v[48:51], v[180:183], v[188:191], v[48:51]
	v_mfma_f32_16x16x32_bf16 v[36:39], v[172:175], v[196:199], v[36:39]
	v_mfma_f32_16x16x32_bf16 v[32:35], v[180:183], v[196:199], v[32:35]
	v_mfma_f32_16x16x32_bf16 v[20:23], v[172:175], v[204:207], v[20:23]
	v_mfma_f32_16x16x32_bf16 v[16:19], v[180:183], v[204:207], v[16:19]
	v_mfma_f32_16x16x32_bf16 v[4:7], v[172:175], v[212:215], v[4:7]
	v_mfma_f32_16x16x32_bf16 v[0:3], v[180:183], v[212:215], v[0:3]
	v_mfma_f32_16x16x32_bf16 v[52:55], v[176:179], v[192:195], v[52:55]
	v_mfma_f32_16x16x32_bf16 v[48:51], v[184:187], v[192:195], v[48:51]
	v_mfma_f32_16x16x32_bf16 v[36:39], v[176:179], v[200:203], v[36:39]
	v_mfma_f32_16x16x32_bf16 v[32:35], v[184:187], v[200:203], v[32:35]
	v_mfma_f32_16x16x32_bf16 v[20:23], v[176:179], v[208:211], v[20:23]
	v_mfma_f32_16x16x32_bf16 v[16:19], v[184:187], v[208:211], v[16:19]
	v_mfma_f32_16x16x32_bf16 v[4:7], v[176:179], v[216:219], v[4:7]
	v_mfma_f32_16x16x32_bf16 v[0:3], v[184:187], v[216:219], v[0:3]
	s_setprio 0
	s_barrier
	s_cmp_lg_u32 s98, 0
	s_cbranch_scc0 .Llp_30
	s_setprio 2
.Llp_30:
	s_add_i32 s48, 0, 0x18000
	v_add_u32_e32 v148, s48, v149
	s_add_i32 s49, 0, 0x1c000
	ds_read_b128 v[144:147], v148
	ds_read_b128 v[160:163], v148 offset:1024
	ds_read_b128 v[164:167], v148 offset:2048
	ds_read_b128 v[168:171], v148 offset:3072
	v_add_u32_e32 v148, s49, v149
	ds_read_b128 v[172:175], v148
	ds_read_b128 v[176:179], v148 offset:1024
	ds_read_b128 v[180:183], v148 offset:2048
	ds_read_b128 v[184:187], v148 offset:3072
	s_add_u32 s38, s38, 0x40000
	s_addc_u32 s39, s39, 0
	s_mov_b32 m0, s45
	v_lshl_add_u64 v[226:227], s[38:39], 0, v[134:135]
	ds_read_b128 v[188:191], v157 offset:32768
	ds_read_b128 v[192:195], v157 offset:33792
	ds_read_b128 v[196:199], v157 offset:34816
	ds_read_b128 v[200:203], v157 offset:35840
	ds_read_b128 v[204:207], v157 offset:36864
	ds_read_b128 v[208:211], v157 offset:37888
	ds_read_b128 v[212:215], v157 offset:38912
	ds_read_b128 v[216:219], v157 offset:39936
	global_load_lds_dwordx4 v[226:227], off
	v_lshl_add_u64 v[226:227], s[38:39], 0, v[130:131]
	s_mov_b32 m0, s46
	s_nop 0
	global_load_lds_dwordx4 v[226:227], off
	s_waitcnt vmcnt(8)
	s_waitcnt lgkmcnt(0)
	s_barrier
	s_setprio 1
	s_waitcnt lgkmcnt(0)
	v_mfma_f32_16x16x32_bf16 v[124:127], v[144:147], v[188:191], v[124:127]
	v_mfma_f32_16x16x32_bf16 v[120:123], v[164:167], v[188:191], v[120:123]
	v_mfma_f32_16x16x32_bf16 v[108:111], v[144:147], v[196:199], v[108:111]
	v_mfma_f32_16x16x32_bf16 v[104:107], v[164:167], v[196:199], v[104:107]
	v_mfma_f32_16x16x32_bf16 v[92:95], v[144:147], v[204:207], v[92:95]
	v_mfma_f32_16x16x32_bf16 v[88:91], v[164:167], v[204:207], v[88:91]
	v_mfma_f32_16x16x32_bf16 v[76:79], v[144:147], v[212:215], v[76:79]
	v_mfma_f32_16x16x32_bf16 v[72:75], v[164:167], v[212:215], v[72:75]
	v_mfma_f32_16x16x32_bf16 v[124:127], v[160:163], v[192:195], v[124:127]
	v_mfma_f32_16x16x32_bf16 v[120:123], v[168:171], v[192:195], v[120:123]
	v_mfma_f32_16x16x32_bf16 v[108:111], v[160:163], v[200:203], v[108:111]
	v_mfma_f32_16x16x32_bf16 v[104:107], v[168:171], v[200:203], v[104:107]
	v_mfma_f32_16x16x32_bf16 v[92:95], v[160:163], v[208:211], v[92:95]
	v_mfma_f32_16x16x32_bf16 v[88:91], v[168:171], v[208:211], v[88:91]
	v_mfma_f32_16x16x32_bf16 v[76:79], v[160:163], v[216:219], v[76:79]
	v_mfma_f32_16x16x32_bf16 v[72:75], v[168:171], v[216:219], v[72:75]
	s_setprio 0
	s_setprio 1
	v_mfma_f32_16x16x32_bf16 v[116:119], v[172:175], v[188:191], v[116:119]
	v_mfma_f32_16x16x32_bf16 v[112:115], v[180:183], v[188:191], v[112:115]
	v_mfma_f32_16x16x32_bf16 v[100:103], v[172:175], v[196:199], v[100:103]
	v_mfma_f32_16x16x32_bf16 v[96:99], v[180:183], v[196:199], v[96:99]
	v_mfma_f32_16x16x32_bf16 v[84:87], v[172:175], v[204:207], v[84:87]
	v_mfma_f32_16x16x32_bf16 v[80:83], v[180:183], v[204:207], v[80:83]
	v_mfma_f32_16x16x32_bf16 v[68:71], v[172:175], v[212:215], v[68:71]
	v_mfma_f32_16x16x32_bf16 v[64:67], v[180:183], v[212:215], v[64:67]
	v_mfma_f32_16x16x32_bf16 v[116:119], v[176:179], v[192:195], v[116:119]
	v_mfma_f32_16x16x32_bf16 v[112:115], v[184:187], v[192:195], v[112:115]
	v_mfma_f32_16x16x32_bf16 v[100:103], v[176:179], v[200:203], v[100:103]
	v_mfma_f32_16x16x32_bf16 v[96:99], v[184:187], v[200:203], v[96:99]
	v_mfma_f32_16x16x32_bf16 v[84:87], v[176:179], v[208:211], v[84:87]
	v_mfma_f32_16x16x32_bf16 v[80:83], v[184:187], v[208:211], v[80:83]
	v_mfma_f32_16x16x32_bf16 v[68:71], v[176:179], v[216:219], v[68:71]
	v_mfma_f32_16x16x32_bf16 v[64:67], v[184:187], v[216:219], v[64:67]
	s_setprio 0
	s_barrier
	s_cmp_lg_u32 s98, 0
	s_cbranch_scc0 .Llp_31
	s_setprio 2
; #define PG8_STAGE(bufoff, gbase, voff) do { _Pragma("unroll") for (int _i = 0; _i < 2; ++_i) \
;         __builtin_amdgcn_global_load_lds((const unsigned*)((const char*)(gbase) + (voff)[_i]), (PG8_LAS unsigned*)(lds + (bufoff) + ldsw + _i * 8192), 16, 0, 0); } while (0)
; #define PG8_LDA(dst, b, h) do { _Pragma("unroll") for (int m = 0; m < 4; ++m) _Pragma("unroll") for (int k = 0; k < 2; ++k) dst[m][k] = *(const PG8_LAS bf16x8*)(lds + PG8_SA(b, h) + aoff + m * 2048 + k * 1024); } while (0)
; #define PG8_MMA(ai, bj, At, Bt) do { __builtin_amdgcn_s_setprio(1); _Pragma("unroll") for (int m = 0; m < 4; ++m) _Pragma("unroll") for (int n = 0; n < 2; ++n) _Pragma("unroll") for (int k = 0; k < 2; ++k) \
;         acc[ai][bj][m][n] = __builtin_amdgcn_mfma_f32_16x16x32_bf16(Bt[n][k], At[m][k], acc[ai][bj][m][n], 0, 0, 0); __builtin_amdgcn_s_setprio(0); } while (0)
; #define PG8_WAIT_V(n) asm volatile("s_waitcnt vmcnt(" #n ")" ::: "memory")
; #define PG8_WAIT_L(n) asm volatile("s_waitcnt lgkmcnt(" #n ")" ::: "memory")
; #define PG8_BAR __builtin_amdgcn_s_barrier()
; #define PG8_SCHED __builtin_amdgcn_sched_barrier(0)
;     ...
;             PG8_LDA(At, 1, 1); PG8_STAGE(PG8_SB(1, 0), b3, voffB); PG8_STAGE(PG8_SB(1, 1), b3 + hstepB, voffB); PG8_STAGE(PG8_SA(1, 0), a3, voffA);
;             PG8_WAIT_V(8); PG8_WAIT_L(0); PG8_BAR; PG8_MMA(1, 0, At, B0); PG8_MMA(1, 1, At, B1); PG8_BAR; PG8_SCHED;
.Llp_31:
	s_add_i32 s38, s48, s43
	v_lshl_add_u64 v[154:155], v[154:155], 0, s[10:11]
	s_mov_b32 m0, s38
	ds_read_b128 v[188:191], v157 offset:49152
	ds_read_b128 v[192:195], v157 offset:50176
	ds_read_b128 v[196:199], v157 offset:51200
	ds_read_b128 v[200:203], v157 offset:52224
	ds_read_b128 v[204:207], v157 offset:53248
	ds_read_b128 v[208:211], v157 offset:54272
	ds_read_b128 v[212:215], v157 offset:55296
	ds_read_b128 v[216:219], v157 offset:56320
	global_load_lds_dwordx4 v[154:155], off
	s_add_i32 m0, s38, 0x2000
	s_add_u32 s36, s36, 0x40080
	v_lshl_add_u64 v[154:155], v[220:221], 0, s[10:11]
	s_addc_u32 s37, s37, 0
	s_add_i32 s38, s49, s43
	global_load_lds_dwordx4 v[154:155], off
	v_lshl_add_u64 v[154:155], s[36:37], 0, v[132:133]
	s_mov_b32 m0, s38
	s_nop 0
	global_load_lds_dwordx4 v[154:155], off
	v_lshl_add_u64 v[154:155], s[36:37], 0, v[128:129]
	s_add_i32 m0, s38, 0x2000
	s_nop 0
	global_load_lds_dwordx4 v[154:155], off
	v_lshl_add_u64 v[154:155], v[222:223], 0, s[10:11]
	s_mov_b32 m0, s52
	s_nop 0
	global_load_lds_dwordx4 v[154:155], off
	v_lshl_add_u64 v[154:155], v[224:225], 0, s[10:11]
	s_mov_b32 m0, s53
	s_nop 0
	global_load_lds_dwordx4 v[154:155], off
	s_waitcnt vmcnt(8)
	s_waitcnt lgkmcnt(0)
	s_barrier
	s_setprio 1
	s_waitcnt lgkmcnt(0)
	v_mfma_f32_16x16x32_bf16 v[60:63], v[144:147], v[188:191], v[60:63]
	v_mfma_f32_16x16x32_bf16 v[56:59], v[164:167], v[188:191], v[56:59]
	v_mfma_f32_16x16x32_bf16 v[44:47], v[144:147], v[196:199], v[44:47]
	v_mfma_f32_16x16x32_bf16 v[40:43], v[164:167], v[196:199], v[40:43]
	v_mfma_f32_16x16x32_bf16 v[28:31], v[144:147], v[204:207], v[28:31]
	v_mfma_f32_16x16x32_bf16 v[24:27], v[164:167], v[204:207], v[24:27]
	v_mfma_f32_16x16x32_bf16 v[12:15], v[144:147], v[212:215], v[12:15]
	v_mfma_f32_16x16x32_bf16 v[8:11], v[164:167], v[212:215], v[8:11]
	v_mfma_f32_16x16x32_bf16 v[60:63], v[160:163], v[192:195], v[60:63]
	v_mfma_f32_16x16x32_bf16 v[56:59], v[168:171], v[192:195], v[56:59]
	v_mfma_f32_16x16x32_bf16 v[44:47], v[160:163], v[200:203], v[44:47]
	v_mfma_f32_16x16x32_bf16 v[40:43], v[168:171], v[200:203], v[40:43]
	v_mfma_f32_16x16x32_bf16 v[28:31], v[160:163], v[208:211], v[28:31]
	v_mfma_f32_16x16x32_bf16 v[24:27], v[168:171], v[208:211], v[24:27]
	v_mfma_f32_16x16x32_bf16 v[12:15], v[160:163], v[216:219], v[12:15]
	v_mfma_f32_16x16x32_bf16 v[8:11], v[168:171], v[216:219], v[8:11]
	s_setprio 0
	s_setprio 1
	v_mfma_f32_16x16x32_bf16 v[52:55], v[172:175], v[188:191], v[52:55]
	v_mfma_f32_16x16x32_bf16 v[48:51], v[180:183], v[188:191], v[48:51]
	v_mfma_f32_16x16x32_bf16 v[36:39], v[172:175], v[196:199], v[36:39]
	v_mfma_f32_16x16x32_bf16 v[32:35], v[180:183], v[196:199], v[32:35]
	v_mfma_f32_16x16x32_bf16 v[20:23], v[172:175], v[204:207], v[20:23]
	v_mfma_f32_16x16x32_bf16 v[16:19], v[180:183], v[204:207], v[16:19]
	v_mfma_f32_16x16x32_bf16 v[4:7], v[172:175], v[212:215], v[4:7]
	v_mfma_f32_16x16x32_bf16 v[0:3], v[180:183], v[212:215], v[0:3]
	v_mfma_f32_16x16x32_bf16 v[52:55], v[176:179], v[192:195], v[52:55]
	v_mfma_f32_16x16x32_bf16 v[48:51], v[184:187], v[192:195], v[48:51]
	v_mfma_f32_16x16x32_bf16 v[36:39], v[176:179], v[200:203], v[36:39]
	v_mfma_f32_16x16x32_bf16 v[32:35], v[184:187], v[200:203], v[32:35]
	v_mfma_f32_16x16x32_bf16 v[20:23], v[176:179], v[208:211], v[20:23]
	v_mfma_f32_16x16x32_bf16 v[16:19], v[184:187], v[208:211], v[16:19]
	v_mfma_f32_16x16x32_bf16 v[4:7], v[176:179], v[216:219], v[4:7]
	v_mfma_f32_16x16x32_bf16 v[0:3], v[184:187], v[216:219], v[0:3]
	s_setprio 0
	s_barrier
	s_cmp_lg_u32 s98, 0
	s_cbranch_scc0 .Llp_32
	s_setprio 2
.Llp_32:
	s_add_i32 s62, s62, 2
	s_add_u32 s34, s34, 0x100
	s_addc_u32 s35, s35, 0
	s_add_u32 s60, s60, 0x100
	s_addc_u32 s61, s61, 0
	s_cmp_gt_u32 s62, 13
	s_cbranch_scc0 .LBB0_1341
	s_and_b64 vcc, exec, s[16:17]
	s_cbranch_vccz .LBB0_1344
	s_barrier

; #define PG8_STAGE(bufoff, gbase, voff) do { _Pragma("unroll") for (int _i = 0; _i < 2; ++_i) \
;         __builtin_amdgcn_global_load_lds((const unsigned*)((const char*)(gbase) + (voff)[_i]), (PG8_LAS unsigned*)(lds + (bufoff) + ldsw + _i * 8192), 16, 0, 0); } while (0)
; #define PG8_LDA(dst, b, h) do { _Pragma("unroll") for (int m = 0; m < 4; ++m) _Pragma("unroll") for (int k = 0; k < 2; ++k) dst[m][k] = *(const PG8_LAS bf16x8*)(lds + PG8_SA(b, h) + aoff + m * 2048 + k * 1024); } while (0)
; #define PG8_LDB(dst, b, h) do { _Pragma("unroll") for (int n = 0; n < 2; ++n) _Pragma("unroll") for (int k = 0; k < 2; ++k) dst[n][k] = *(const PG8_LAS bf16x8*)(lds + PG8_SB(b, h) + boff + n * 2048 + k * 1024); } while (0)
; #define PG8_MMA(ai, bj, At, Bt) do { __builtin_amdgcn_s_setprio(1); _Pragma("unroll") for (int m = 0; m < 4; ++m) _Pragma("unroll") for (int n = 0; n < 2; ++n) _Pragma("unroll") for (int k = 0; k < 2; ++k) \
;         acc[ai][bj][m][n] = __builtin_amdgcn_mfma_f32_16x16x32_bf16(Bt[n][k], At[m][k], acc[ai][bj][m][n], 0, 0, 0); __builtin_amdgcn_s_setprio(0); } while (0)
; #define PG8_WAIT_V(n) asm volatile("s_waitcnt vmcnt(" #n ")" ::: "memory")
; #define PG8_WAIT_L(n) asm volatile("s_waitcnt lgkmcnt(" #n ")" ::: "memory")
; #define PG8_BAR __builtin_amdgcn_s_barrier()
; #define PG8_SCHED __builtin_amdgcn_sched_barrier(0)
;     ...
;             const bool last = (t == nt - 2);
;             const char* a1 = cA + (size_t)(t + 1) * kstep;
;             const char* a2 = last ? nA : cA + (size_t)(t + 2) * kstep; const char* b2 = last ? nB : cB + (size_t)(t + 2) * kstep;
;             const char* a3 = a2 + kstep; const char* b3 = b2 + kstep;
;             if (last && has_next) S.a_ready(nxt);
;             if constexpr (SP2) {
;             PG8_LDB(B0, 0, 0); PG8_LDB(B1, 0, 1); PG8_SCHED; PG8_LDA(At, 0, 0); PG8_STAGE(PG8_SA(1, 1), a1 + hstepA, voffA);
;             PG8_WAIT_V(8); PG8_WAIT_L(0); PG8_BAR; PG8_MMA(0, 0, At, B0); PG8_MMA(0, 1, At, B1); PG8_BAR; PG8_SCHED;
;             PG8_LDA(At, 0, 1); PG8_STAGE(PG8_SB(0, 0), b2, voffB); PG8_STAGE(PG8_SB(0, 1), b2 + hstepB, voffB); PG8_STAGE(PG8_SA(0, 0), a2, voffA);
;             PG8_WAIT_V(8); PG8_WAIT_L(0); PG8_BAR; PG8_MMA(1, 0, At, B0); PG8_MMA(1, 1, At, B1); PG8_BAR; PG8_SCHED;
.LBB0_1414:
	ds_read_b128 v[128:131], v163
	ds_read_b128 v[132:135], v163 offset:1024
	ds_read_b128 v[152:155], v163 offset:2048
	ds_read_b128 v[156:159], v163 offset:3072
	ds_read_b128 v[166:169], v164
	ds_read_b128 v[170:173], v164 offset:1024
	ds_read_b128 v[174:177], v164 offset:2048
	ds_read_b128 v[178:181], v164 offset:3072
	s_add_u32 s28, s26, 0xfff00080
	s_addc_u32 s29, s27, -1
	s_cmp_eq_u32 s52, 60
	s_cselect_b32 s35, s21, s29
	s_cselect_b32 s34, s48, s28
	s_cselect_b32 s29, s19, s51
	s_cselect_b32 s28, s49, s50
	v_lshl_add_u64 v[160:161], s[26:27], 0, v[144:145]
	s_add_i32 m0, s8, 0xc000
	ds_read_b128 v[182:185], v165
	ds_read_b128 v[186:189], v165 offset:1024
	ds_read_b128 v[190:193], v165 offset:2048
	ds_read_b128 v[194:197], v165 offset:3072
	ds_read_b128 v[198:201], v165 offset:4096
	ds_read_b128 v[202:205], v165 offset:5120
	ds_read_b128 v[206:209], v165 offset:6144
	ds_read_b128 v[210:213], v165 offset:7168
	global_load_lds_dwordx4 v[160:161], off
	v_lshl_add_u64 v[160:161], s[26:27], 0, v[146:147]
	s_add_i32 m0, s8, 0xe000
	s_nop 0
	global_load_lds_dwordx4 v[160:161], off
	s_waitcnt vmcnt(8)
	s_waitcnt lgkmcnt(0)
	s_barrier
	s_setprio 1
	s_waitcnt lgkmcnt(0)
	v_mfma_f32_16x16x32_bf16 v[124:127], v[128:131], v[182:185], v[124:127]
	v_mfma_f32_16x16x32_bf16 v[120:123], v[152:155], v[182:185], v[120:123]
	v_mfma_f32_16x16x32_bf16 v[108:111], v[128:131], v[190:193], v[108:111]
	v_mfma_f32_16x16x32_bf16 v[104:107], v[152:155], v[190:193], v[104:107]
	v_mfma_f32_16x16x32_bf16 v[92:95], v[128:131], v[198:201], v[92:95]
	v_mfma_f32_16x16x32_bf16 v[88:91], v[152:155], v[198:201], v[88:91]
	v_mfma_f32_16x16x32_bf16 v[76:79], v[128:131], v[206:209], v[76:79]
	v_mfma_f32_16x16x32_bf16 v[72:75], v[152:155], v[206:209], v[72:75]
	v_mfma_f32_16x16x32_bf16 v[124:127], v[132:135], v[186:189], v[124:127]
	v_mfma_f32_16x16x32_bf16 v[120:123], v[156:159], v[186:189], v[120:123]
	v_mfma_f32_16x16x32_bf16 v[108:111], v[132:135], v[194:197], v[108:111]
	v_mfma_f32_16x16x32_bf16 v[104:107], v[156:159], v[194:197], v[104:107]
	v_mfma_f32_16x16x32_bf16 v[92:95], v[132:135], v[202:205], v[92:95]
	v_mfma_f32_16x16x32_bf16 v[88:91], v[156:159], v[202:205], v[88:91]
	v_mfma_f32_16x16x32_bf16 v[76:79], v[132:135], v[210:213], v[76:79]
	v_mfma_f32_16x16x32_bf16 v[72:75], v[156:159], v[210:213], v[72:75]
	s_setprio 0
	s_setprio 1
	v_mfma_f32_16x16x32_bf16 v[116:119], v[166:169], v[182:185], v[116:119]
	v_mfma_f32_16x16x32_bf16 v[112:115], v[174:177], v[182:185], v[112:115]
	v_mfma_f32_16x16x32_bf16 v[100:103], v[166:169], v[190:193], v[100:103]
	v_mfma_f32_16x16x32_bf16 v[96:99], v[174:177], v[190:193], v[96:99]
	v_mfma_f32_16x16x32_bf16 v[84:87], v[166:169], v[198:201], v[84:87]
	v_mfma_f32_16x16x32_bf16 v[80:83], v[174:177], v[198:201], v[80:83]
	v_mfma_f32_16x16x32_bf16 v[68:71], v[166:169], v[206:209], v[68:71]
	v_mfma_f32_16x16x32_bf16 v[64:67], v[174:177], v[206:209], v[64:67]
	v_mfma_f32_16x16x32_bf16 v[116:119], v[170:173], v[186:189], v[116:119]
	v_mfma_f32_16x16x32_bf16 v[112:115], v[178:181], v[186:189], v[112:115]
	v_mfma_f32_16x16x32_bf16 v[100:103], v[170:173], v[194:197], v[100:103]
	v_mfma_f32_16x16x32_bf16 v[96:99], v[178:181], v[194:197], v[96:99]
	v_mfma_f32_16x16x32_bf16 v[84:87], v[170:173], v[202:205], v[84:87]
	v_mfma_f32_16x16x32_bf16 v[80:83], v[178:181], v[202:205], v[80:83]
	v_mfma_f32_16x16x32_bf16 v[68:71], v[170:173], v[210:213], v[68:71]
	v_mfma_f32_16x16x32_bf16 v[64:67], v[178:181], v[210:213], v[64:67]
	s_setprio 0
	s_barrier
	s_cmp_lg_u32 s98, 0
	s_cbranch_scc0 .Llp_33
	s_setprio 2
.Llp_33:
	s_add_i32 s53, s46, s39
	v_lshl_add_u64 v[160:161], s[28:29], 0, v[140:141]
	s_mov_b32 m0, s53
	ds_read_b128 v[182:185], v165 offset:16384
	ds_read_b128 v[186:189], v165 offset:17408
	ds_read_b128 v[190:193], v165 offset:18432
	ds_read_b128 v[194:197], v165 offset:19456
	ds_read_b128 v[198:201], v165 offset:20480
	ds_read_b128 v[202:205], v165 offset:21504
	ds_read_b128 v[206:209], v165 offset:22528
	ds_read_b128 v[210:213], v165 offset:23552
	global_load_lds_dwordx4 v[160:161], off
	s_add_i32 m0, s53, 0x2000
	s_add_u32 s54, s28, 0x100000
	v_lshl_add_u64 v[214:215], s[28:29], 0, v[136:137]
	s_addc_u32 s55, s29, 0
	s_add_i32 s53, s47, s39
	global_load_lds_dwordx4 v[214:215], off
	v_lshl_add_u64 v[216:217], s[54:55], 0, v[140:141]
	s_mov_b32 m0, s53
	v_lshl_add_u64 v[218:219], s[34:35], 0, v[138:139]
	global_load_lds_dwordx4 v[216:217], off
	v_lshl_add_u64 v[216:217], s[54:55], 0, v[136:137]
	s_add_i32 m0, s53, 0x2000
	s_nop 0
	global_load_lds_dwordx4 v[216:217], off
	v_lshl_add_u64 v[216:217], s[34:35], 0, v[142:143]
	s_mov_b32 m0, s8
	s_nop 0
	global_load_lds_dwordx4 v[216:217], off
	s_mov_b32 m0, s13
	s_nop 0
	global_load_lds_dwordx4 v[218:219], off
	s_waitcnt vmcnt(8)
	s_waitcnt lgkmcnt(0)
	s_barrier
; #define PG8_STAGE(bufoff, gbase, voff) do { _Pragma("unroll") for (int _i = 0; _i < 2; ++_i) \
;         __builtin_amdgcn_global_load_lds((const unsigned*)((const char*)(gbase) + (voff)[_i]), (PG8_LAS unsigned*)(lds + (bufoff) + ldsw + _i * 8192), 16, 0, 0); } while (0)
; #define PG8_LDA(dst, b, h) do { _Pragma("unroll") for (int m = 0; m < 4; ++m) _Pragma("unroll") for (int k = 0; k < 2; ++k) dst[m][k] = *(const PG8_LAS bf16x8*)(lds + PG8_SA(b, h) + aoff + m * 2048 + k * 1024); } while (0)
; #define PG8_LDB(dst, b, h) do { _Pragma("unroll") for (int n = 0; n < 2; ++n) _Pragma("unroll") for (int k = 0; k < 2; ++k) dst[n][k] = *(const PG8_LAS bf16x8*)(lds + PG8_SB(b, h) + boff + n * 2048 + k * 1024); } while (0)
; #define PG8_MMA(ai, bj, At, Bt) do { __builtin_amdgcn_s_setprio(1); _Pragma("unroll") for (int m = 0; m < 4; ++m) _Pragma("unroll") for (int n = 0; n < 2; ++n) _Pragma("unroll") for (int k = 0; k < 2; ++k) \
;         acc[ai][bj][m][n] = __builtin_amdgcn_mfma_f32_16x16x32_bf16(Bt[n][k], At[m][k], acc[ai][bj][m][n], 0, 0, 0); __builtin_amdgcn_s_setprio(0); } while (0)
; #define PG8_WAIT_V(n) asm volatile("s_waitcnt vmcnt(" #n ")" ::: "memory")
; #define PG8_WAIT_L(n) asm volatile("s_waitcnt lgkmcnt(" #n ")" ::: "memory")
; #define PG8_BAR __builtin_amdgcn_s_barrier()
; #define PG8_SCHED __builtin_amdgcn_sched_barrier(0)
;     ...
;             PG8_WAIT_V(8); PG8_WAIT_L(0); PG8_BAR; PG8_MMA(1, 0, At, B0); PG8_MMA(1, 1, At, B1); PG8_BAR; PG8_SCHED;
;             PG8_LDB(B0, 1, 0); PG8_LDB(B1, 1, 1); PG8_SCHED; PG8_LDA(At, 1, 0); PG8_STAGE(PG8_SA(0, 1), a2 + hstepA, voffA);
;             PG8_WAIT_V(8); PG8_WAIT_L(0); PG8_BAR; PG8_MMA(0, 0, At, B0); PG8_MMA(0, 1, At, B1); PG8_BAR; PG8_SCHED;
	s_setprio 1
	s_waitcnt lgkmcnt(0)
	v_mfma_f32_16x16x32_bf16 v[60:63], v[128:131], v[182:185], v[60:63]
	v_mfma_f32_16x16x32_bf16 v[56:59], v[152:155], v[182:185], v[56:59]
	v_mfma_f32_16x16x32_bf16 v[48:51], v[128:131], v[190:193], v[48:51]
	v_mfma_f32_16x16x32_bf16 v[40:43], v[152:155], v[190:193], v[40:43]
	v_mfma_f32_16x16x32_bf16 v[32:35], v[128:131], v[198:201], v[32:35]
	v_mfma_f32_16x16x32_bf16 v[24:27], v[152:155], v[198:201], v[24:27]
	v_mfma_f32_16x16x32_bf16 v[16:19], v[128:131], v[206:209], v[16:19]
	v_mfma_f32_16x16x32_bf16 v[8:11], v[152:155], v[206:209], v[8:11]
	v_mfma_f32_16x16x32_bf16 v[60:63], v[132:135], v[186:189], v[60:63]
	v_mfma_f32_16x16x32_bf16 v[56:59], v[156:159], v[186:189], v[56:59]
	v_mfma_f32_16x16x32_bf16 v[48:51], v[132:135], v[194:197], v[48:51]
	v_mfma_f32_16x16x32_bf16 v[40:43], v[156:159], v[194:197], v[40:43]
	v_mfma_f32_16x16x32_bf16 v[32:35], v[132:135], v[202:205], v[32:35]
	v_mfma_f32_16x16x32_bf16 v[24:27], v[156:159], v[202:205], v[24:27]
	v_mfma_f32_16x16x32_bf16 v[16:19], v[132:135], v[210:213], v[16:19]
	v_mfma_f32_16x16x32_bf16 v[8:11], v[156:159], v[210:213], v[8:11]
	s_setprio 0
	s_setprio 1
	v_mfma_f32_16x16x32_bf16 v[52:55], v[166:169], v[182:185], v[52:55]
	v_mfma_f32_16x16x32_bf16 v[44:47], v[174:177], v[182:185], v[44:47]
	v_mfma_f32_16x16x32_bf16 v[36:39], v[166:169], v[190:193], v[36:39]
	v_mfma_f32_16x16x32_bf16 v[28:31], v[174:177], v[190:193], v[28:31]
	v_mfma_f32_16x16x32_bf16 v[20:23], v[166:169], v[198:201], v[20:23]
	v_mfma_f32_16x16x32_bf16 v[12:15], v[174:177], v[198:201], v[12:15]
	v_mfma_f32_16x16x32_bf16 v[4:7], v[166:169], v[206:209], v[4:7]
	v_mfma_f32_16x16x32_bf16 v[0:3], v[174:177], v[206:209], v[0:3]
	v_mfma_f32_16x16x32_bf16 v[52:55], v[170:173], v[186:189], v[52:55]
	v_mfma_f32_16x16x32_bf16 v[44:47], v[178:181], v[186:189], v[44:47]
	v_mfma_f32_16x16x32_bf16 v[36:39], v[170:173], v[194:197], v[36:39]
	v_mfma_f32_16x16x32_bf16 v[28:31], v[178:181], v[194:197], v[28:31]
	v_mfma_f32_16x16x32_bf16 v[20:23], v[170:173], v[202:205], v[20:23]
	v_mfma_f32_16x16x32_bf16 v[12:15], v[178:181], v[202:205], v[12:15]
	v_mfma_f32_16x16x32_bf16 v[4:7], v[170:173], v[210:213], v[4:7]
	v_mfma_f32_16x16x32_bf16 v[0:3], v[178:181], v[210:213], v[0:3]
	s_setprio 0
	s_barrier
	s_cmp_lg_u32 s98, 0
	s_cbranch_scc0 .Llp_34
	s_setprio 2
.Llp_34:
	s_add_i32 s53, 0, 0x18000
	s_add_i32 s54, 0, 0x1c000
	v_add_u32_e32 v156, s53, v162
	v_add_u32_e32 v178, s54, v162
	ds_read_b128 v[128:131], v156
	ds_read_b128 v[132:135], v156 offset:1024
	ds_read_b128 v[152:155], v156 offset:2048
	ds_read_b128 v[156:159], v156 offset:3072
	ds_read_b128 v[166:169], v178
	ds_read_b128 v[170:173], v178 offset:1024
	ds_read_b128 v[174:177], v178 offset:2048
	ds_read_b128 v[178:181], v178 offset:3072
	s_add_u32 s34, s34, 0x100000
	s_addc_u32 s35, s35, 0
	s_mov_b32 m0, s40
	v_lshl_add_u64 v[220:221], s[34:35], 0, v[142:143]
	ds_read_b128 v[182:185], v165 offset:32768
	ds_read_b128 v[186:189], v165 offset:33792
	ds_read_b128 v[190:193], v165 offset:34816
	ds_read_b128 v[194:197], v165 offset:35840
	ds_read_b128 v[198:201], v165 offset:36864
	ds_read_b128 v[202:205], v165 offset:37888
	ds_read_b128 v[206:209], v165 offset:38912
	ds_read_b128 v[210:213], v165 offset:39936
	global_load_lds_dwordx4 v[220:221], off
	v_lshl_add_u64 v[220:221], s[34:35], 0, v[138:139]
	s_mov_b32 m0, s41
	s_nop 0
	global_load_lds_dwordx4 v[220:221], off
	s_waitcnt vmcnt(8)
	s_waitcnt lgkmcnt(0)
	s_barrier
	s_setprio 1
	s_waitcnt lgkmcnt(0)
	v_mfma_f32_16x16x32_bf16 v[124:127], v[128:131], v[182:185], v[124:127]
	v_mfma_f32_16x16x32_bf16 v[120:123], v[152:155], v[182:185], v[120:123]
	v_mfma_f32_16x16x32_bf16 v[108:111], v[128:131], v[190:193], v[108:111]
	v_mfma_f32_16x16x32_bf16 v[104:107], v[152:155], v[190:193], v[104:107]
	v_mfma_f32_16x16x32_bf16 v[92:95], v[128:131], v[198:201], v[92:95]
	v_mfma_f32_16x16x32_bf16 v[88:91], v[152:155], v[198:201], v[88:91]
	v_mfma_f32_16x16x32_bf16 v[76:79], v[128:131], v[206:209], v[76:79]
	v_mfma_f32_16x16x32_bf16 v[72:75], v[152:155], v[206:209], v[72:75]
	v_mfma_f32_16x16x32_bf16 v[124:127], v[132:135], v[186:189], v[124:127]
	v_mfma_f32_16x16x32_bf16 v[120:123], v[156:159], v[186:189], v[120:123]
	v_mfma_f32_16x16x32_bf16 v[108:111], v[132:135], v[194:197], v[108:111]
	v_mfma_f32_16x16x32_bf16 v[104:107], v[156:159], v[194:197], v[104:107]
	v_mfma_f32_16x16x32_bf16 v[92:95], v[132:135], v[202:205], v[92:95]
	v_mfma_f32_16x16x32_bf16 v[88:91], v[156:159], v[202:205], v[88:91]
	v_mfma_f32_16x16x32_bf16 v[76:79], v[132:135], v[210:213], v[76:79]
	v_mfma_f32_16x16x32_bf16 v[72:75], v[156:159], v[210:213], v[72:75]
	s_setprio 0
	s_setprio 1
	v_mfma_f32_16x16x32_bf16 v[116:119], v[166:169], v[182:185], v[116:119]
	v_mfma_f32_16x16x32_bf16 v[112:115], v[174:177], v[182:185], v[112:115]
	v_mfma_f32_16x16x32_bf16 v[100:103], v[166:169], v[190:193], v[100:103]
	v_mfma_f32_16x16x32_bf16 v[96:99], v[174:177], v[190:193], v[96:99]
	v_mfma_f32_16x16x32_bf16 v[84:87], v[166:169], v[198:201], v[84:87]
	v_mfma_f32_16x16x32_bf16 v[80:83], v[174:177], v[198:201], v[80:83]
	v_mfma_f32_16x16x32_bf16 v[68:71], v[166:169], v[206:209], v[68:71]
	v_mfma_f32_16x16x32_bf16 v[64:67], v[174:177], v[206:209], v[64:67]
	v_mfma_f32_16x16x32_bf16 v[116:119], v[170:173], v[186:189], v[116:119]
	v_mfma_f32_16x16x32_bf16 v[112:115], v[178:181], v[186:189], v[112:115]
	v_mfma_f32_16x16x32_bf16 v[100:103], v[170:173], v[194:197], v[100:103]
	v_mfma_f32_16x16x32_bf16 v[96:99], v[178:181], v[194:197], v[96:99]
	v_mfma_f32_16x16x32_bf16 v[84:87], v[170:173], v[202:205], v[84:87]
	v_mfma_f32_16x16x32_bf16 v[80:83], v[178:181], v[202:205], v[80:83]
	v_mfma_f32_16x16x32_bf16 v[68:71], v[170:173], v[210:213], v[68:71]
	v_mfma_f32_16x16x32_bf16 v[64:67], v[178:181], v[210:213], v[64:67]
	s_setprio 0
	s_barrier
	s_cmp_lg_u32 s98, 0
	s_cbranch_scc0 .Llp_35
	s_setprio 2
; #define PG8_STAGE(bufoff, gbase, voff) do { _Pragma("unroll") for (int _i = 0; _i < 2; ++_i) \
;         __builtin_amdgcn_global_load_lds((const unsigned*)((const char*)(gbase) + (voff)[_i]), (PG8_LAS unsigned*)(lds + (bufoff) + ldsw + _i * 8192), 16, 0, 0); } while (0)
; #define PG8_LDA(dst, b, h) do { _Pragma("unroll") for (int m = 0; m < 4; ++m) _Pragma("unroll") for (int k = 0; k < 2; ++k) dst[m][k] = *(const PG8_LAS bf16x8*)(lds + PG8_SA(b, h) + aoff + m * 2048 + k * 1024); } while (0)
; #define PG8_MMA(ai, bj, At, Bt) do { __builtin_amdgcn_s_setprio(1); _Pragma("unroll") for (int m = 0; m < 4; ++m) _Pragma("unroll") for (int n = 0; n < 2; ++n) _Pragma("unroll") for (int k = 0; k < 2; ++k) \
;         acc[ai][bj][m][n] = __builtin_amdgcn_mfma_f32_16x16x32_bf16(Bt[n][k], At[m][k], acc[ai][bj][m][n], 0, 0, 0); __builtin_amdgcn_s_setprio(0); } while (0)
; #define PG8_WAIT_V(n) asm volatile("s_waitcnt vmcnt(" #n ")" ::: "memory")
; #define PG8_WAIT_L(n) asm volatile("s_waitcnt lgkmcnt(" #n ")" ::: "memory")
; #define PG8_BAR __builtin_amdgcn_s_barrier()
; #define PG8_SCHED __builtin_amdgcn_sched_barrier(0)
;     ...
;             PG8_LDA(At, 1, 1); PG8_STAGE(PG8_SB(1, 0), b3, voffB); PG8_STAGE(PG8_SB(1, 1), b3 + hstepB, voffB); PG8_STAGE(PG8_SA(1, 0), a3, voffA);
;             PG8_WAIT_V(8); PG8_WAIT_L(0); PG8_BAR; PG8_MMA(1, 0, At, B0); PG8_MMA(1, 1, At, B1); PG8_BAR; PG8_SCHED;
.Llp_35:
	s_add_i32 s34, s53, s39
	v_lshl_add_u64 v[160:161], v[160:161], 0, s[14:15]
	s_mov_b32 m0, s34
	ds_read_b128 v[182:185], v165 offset:49152
	ds_read_b128 v[186:189], v165 offset:50176
	ds_read_b128 v[190:193], v165 offset:51200
	ds_read_b128 v[194:197], v165 offset:52224
	ds_read_b128 v[198:201], v165 offset:53248
	ds_read_b128 v[202:205], v165 offset:54272
	ds_read_b128 v[206:209], v165 offset:55296
	ds_read_b128 v[210:213], v165 offset:56320
	global_load_lds_dwordx4 v[160:161], off
	s_add_i32 m0, s34, 0x2000
	s_add_u32 s28, s28, 0x100080
	v_lshl_add_u64 v[160:161], v[214:215], 0, s[14:15]
	s_addc_u32 s29, s29, 0
	s_add_i32 s34, s54, s39
	global_load_lds_dwordx4 v[160:161], off
	v_lshl_add_u64 v[160:161], s[28:29], 0, v[140:141]
	s_mov_b32 m0, s34
	s_nop 0
	global_load_lds_dwordx4 v[160:161], off
	v_lshl_add_u64 v[160:161], s[28:29], 0, v[136:137]
	s_add_i32 m0, s34, 0x2000
	s_nop 0
	global_load_lds_dwordx4 v[160:161], off
	v_lshl_add_u64 v[160:161], v[216:217], 0, s[14:15]
	s_mov_b32 m0, s44
	s_nop 0
	global_load_lds_dwordx4 v[160:161], off
	v_lshl_add_u64 v[160:161], v[218:219], 0, s[14:15]
	s_mov_b32 m0, s45
	s_nop 0
	global_load_lds_dwordx4 v[160:161], off
	s_waitcnt vmcnt(8)
	s_waitcnt lgkmcnt(0)
	s_barrier
	s_setprio 1
	s_waitcnt lgkmcnt(0)
	v_mfma_f32_16x16x32_bf16 v[60:63], v[128:131], v[182:185], v[60:63]
	v_mfma_f32_16x16x32_bf16 v[56:59], v[152:155], v[182:185], v[56:59]
	v_mfma_f32_16x16x32_bf16 v[48:51], v[128:131], v[190:193], v[48:51]
	v_mfma_f32_16x16x32_bf16 v[40:43], v[152:155], v[190:193], v[40:43]
	v_mfma_f32_16x16x32_bf16 v[32:35], v[128:131], v[198:201], v[32:35]
	v_mfma_f32_16x16x32_bf16 v[24:27], v[152:155], v[198:201], v[24:27]
	v_mfma_f32_16x16x32_bf16 v[16:19], v[128:131], v[206:209], v[16:19]
	v_mfma_f32_16x16x32_bf16 v[8:11], v[152:155], v[206:209], v[8:11]
	v_mfma_f32_16x16x32_bf16 v[60:63], v[132:135], v[186:189], v[60:63]
	v_mfma_f32_16x16x32_bf16 v[56:59], v[156:159], v[186:189], v[56:59]
	v_mfma_f32_16x16x32_bf16 v[48:51], v[132:135], v[194:197], v[48:51]
	v_mfma_f32_16x16x32_bf16 v[40:43], v[156:159], v[194:197], v[40:43]
	v_mfma_f32_16x16x32_bf16 v[32:35], v[132:135], v[202:205], v[32:35]
	v_mfma_f32_16x16x32_bf16 v[24:27], v[156:159], v[202:205], v[24:27]
	v_mfma_f32_16x16x32_bf16 v[16:19], v[132:135], v[210:213], v[16:19]
	v_mfma_f32_16x16x32_bf16 v[8:11], v[156:159], v[210:213], v[8:11]
	s_setprio 0
	s_setprio 1
	v_mfma_f32_16x16x32_bf16 v[52:55], v[166:169], v[182:185], v[52:55]
	v_mfma_f32_16x16x32_bf16 v[44:47], v[174:177], v[182:185], v[44:47]
	v_mfma_f32_16x16x32_bf16 v[36:39], v[166:169], v[190:193], v[36:39]
	v_mfma_f32_16x16x32_bf16 v[28:31], v[174:177], v[190:193], v[28:31]
	v_mfma_f32_16x16x32_bf16 v[20:23], v[166:169], v[198:201], v[20:23]
	v_mfma_f32_16x16x32_bf16 v[12:15], v[174:177], v[198:201], v[12:15]
	v_mfma_f32_16x16x32_bf16 v[4:7], v[166:169], v[206:209], v[4:7]
	v_mfma_f32_16x16x32_bf16 v[0:3], v[174:177], v[206:209], v[0:3]
	v_mfma_f32_16x16x32_bf16 v[52:55], v[170:173], v[186:189], v[52:55]
	v_mfma_f32_16x16x32_bf16 v[44:47], v[178:181], v[186:189], v[44:47]
	v_mfma_f32_16x16x32_bf16 v[36:39], v[170:173], v[194:197], v[36:39]
	v_mfma_f32_16x16x32_bf16 v[28:31], v[178:181], v[194:197], v[28:31]
	v_mfma_f32_16x16x32_bf16 v[20:23], v[170:173], v[202:205], v[20:23]
	v_mfma_f32_16x16x32_bf16 v[12:15], v[178:181], v[202:205], v[12:15]
	v_mfma_f32_16x16x32_bf16 v[4:7], v[170:173], v[210:213], v[4:7]
	v_mfma_f32_16x16x32_bf16 v[0:3], v[178:181], v[210:213], v[0:3]
	s_setprio 0
	s_barrier
	s_cmp_lg_u32 s98, 0
	s_cbranch_scc0 .Llp_36
	s_setprio 2
.Llp_36:
	s_add_i32 s52, s52, 2
	s_add_u32 s26, s26, 0x100
	s_addc_u32 s27, s27, 0
	s_add_u32 s50, s50, 0x100
	s_addc_u32 s51, s51, 0
	s_cmp_gt_u32 s52, 61
	s_cbranch_scc0 .LBB0_1414
	s_and_b64 vcc, exec, s[16:17]
	s_cbranch_vccz .LBB0_1417
	s_barrier
